# GEMM MFMA blocks: first 8 MFMAs of each block issued in front of its opening barrier at low priority (fills matrix-pipe gaps of the other half)
# speedup vs baseline: 1.0053x; 1.0053x over previous
.LBB0_757:
	s_ashr_i32 s17, s16, 31
	s_lshl_b64 s[18:19], s[16:17], 20
	s_add_u32 s18, s35, s18
	s_addc_u32 s19, s40, s19
	s_and_b64 s[20:21], s[4:5], exec
	s_cselect_b32 s17, s19, s29
	s_cselect_b32 s23, s18, s28
	s_ashr_i32 s15, s14, 31
	s_lshl_b64 s[20:21], s[14:15], 19
	s_add_u32 s20, s38, s20
	s_addc_u32 s21, s39, s21
	s_and_b64 s[30:31], s[4:5], exec
	s_cselect_b32 s15, s21, s27
	s_cselect_b32 s25, s20, s26
	s_add_u32 s52, s26, 0x100
	s_addc_u32 s53, s27, 0
	s_add_u32 s26, s28, 0x80080
	s_addc_u32 s27, s29, 0
	s_mov_b32 s54, -2
	s_waitcnt lgkmcnt(0)
	s_add_u32 s28, s26, 0xfff80080
	s_addc_u32 s29, s27, -1
	s_add_i32 s55, 0, 0x10000
	s_cmp_eq_u32 s54, 12
	s_cselect_b32 s31, s17, s29
	s_cselect_b32 s30, s23, s28
	s_cselect_b32 s29, s15, s53
	s_cselect_b32 s28, s25, s52
	s_add_i32 s58, 0, 0x14000
	v_add_u32_e32 v156, s55, v145
	v_add_u32_e32 v172, s58, v145
	ds_read_b128 v[140:143], v156
	ds_read_b128 v[148:151], v156 offset:1024
	ds_read_b128 v[152:155], v156 offset:2048
	ds_read_b128 v[156:159], v156 offset:3072
	ds_read_b128 v[160:163], v172
	ds_read_b128 v[164:167], v172 offset:1024
	ds_read_b128 v[168:171], v172 offset:2048
	ds_read_b128 v[172:175], v172 offset:3072
	s_add_i32 m0, s42, 0xc000
	ds_read_b128 v[176:179], v147
	ds_read_b128 v[180:183], v147 offset:1024
	ds_read_b128 v[184:187], v147 offset:2048
	ds_read_b128 v[208:211], v147 offset:3072
	ds_read_b128 v[230:233], v147 offset:4096
	ds_read_b128 v[234:237], v147 offset:5120
	ds_read_b128 v[238:241], v147 offset:6144
	ds_read_b128 v[242:245], v147 offset:7168
	global_load_lds_dwordx4 v138, s[26:27]
	s_add_i32 m0, s42, 0xe000
	s_nop 0
	global_load_lds_dwordx4 v136, s[26:27]
	s_waitcnt vmcnt(8)
	s_waitcnt lgkmcnt(0)
	v_mfma_f32_16x16x32_bf16 v[126:129], v[140:143], v[176:179], 0
	v_mfma_f32_16x16x32_bf16 v[122:125], v[152:155], v[176:179], 0
	v_mfma_f32_16x16x32_bf16 v[108:111], v[140:143], v[184:187], 0
	v_mfma_f32_16x16x32_bf16 v[104:107], v[152:155], v[184:187], 0
	v_mfma_f32_16x16x32_bf16 v[92:95], v[140:143], v[230:233], 0
	v_mfma_f32_16x16x32_bf16 v[88:91], v[152:155], v[230:233], 0
	v_mfma_f32_16x16x32_bf16 v[76:79], v[140:143], v[238:241], 0
	v_mfma_f32_16x16x32_bf16 v[72:75], v[152:155], v[238:241], 0
	s_barrier
	s_setprio 1
	v_mfma_f32_16x16x32_bf16 v[126:129], v[148:151], v[180:183], v[126:129]
	v_mfma_f32_16x16x32_bf16 v[122:125], v[156:159], v[180:183], v[122:125]
	v_mfma_f32_16x16x32_bf16 v[108:111], v[148:151], v[208:211], v[108:111]
	v_mfma_f32_16x16x32_bf16 v[104:107], v[156:159], v[208:211], v[104:107]
	v_mfma_f32_16x16x32_bf16 v[92:95], v[148:151], v[234:237], v[92:95]
	v_mfma_f32_16x16x32_bf16 v[88:91], v[156:159], v[234:237], v[88:91]
	v_mfma_f32_16x16x32_bf16 v[76:79], v[148:151], v[242:245], v[76:79]
	v_mfma_f32_16x16x32_bf16 v[72:75], v[156:159], v[242:245], v[72:75]
	s_setprio 0
	s_setprio 1
	v_mfma_f32_16x16x32_bf16 v[118:121], v[160:163], v[176:179], 0
	v_mfma_f32_16x16x32_bf16 v[114:117], v[168:171], v[176:179], 0
	v_mfma_f32_16x16x32_bf16 v[100:103], v[160:163], v[184:187], 0
	v_mfma_f32_16x16x32_bf16 v[96:99], v[168:171], v[184:187], 0
	v_mfma_f32_16x16x32_bf16 v[84:87], v[160:163], v[230:233], 0
	v_mfma_f32_16x16x32_bf16 v[80:83], v[168:171], v[230:233], 0
	v_mfma_f32_16x16x32_bf16 v[68:71], v[160:163], v[238:241], 0
	v_mfma_f32_16x16x32_bf16 v[64:67], v[168:171], v[238:241], 0
	v_mfma_f32_16x16x32_bf16 v[118:121], v[164:167], v[180:183], v[118:121]
	v_mfma_f32_16x16x32_bf16 v[114:117], v[172:175], v[180:183], v[114:117]
	v_mfma_f32_16x16x32_bf16 v[100:103], v[164:167], v[208:211], v[100:103]
	v_mfma_f32_16x16x32_bf16 v[96:99], v[172:175], v[208:211], v[96:99]
	v_mfma_f32_16x16x32_bf16 v[84:87], v[164:167], v[234:237], v[84:87]
	v_mfma_f32_16x16x32_bf16 v[80:83], v[172:175], v[234:237], v[80:83]
	v_mfma_f32_16x16x32_bf16 v[68:71], v[164:167], v[242:245], v[68:71]
	v_mfma_f32_16x16x32_bf16 v[64:67], v[172:175], v[242:245], v[64:67]
	s_setprio 0
	s_barrier
	s_add_i32 s55, s55, s41
	s_mov_b32 m0, s55
	ds_read_b128 v[176:179], v147 offset:16384
	ds_read_b128 v[180:183], v147 offset:17408
	ds_read_b128 v[184:187], v147 offset:18432
	ds_read_b128 v[208:211], v147 offset:19456
	ds_read_b128 v[230:233], v147 offset:20480
	ds_read_b128 v[234:237], v147 offset:21504
	ds_read_b128 v[238:241], v147 offset:22528
	ds_read_b128 v[242:245], v147 offset:23552
	global_load_lds_dwordx4 v112, s[28:29]
	s_add_i32 m0, s55, 0x2000
	s_add_u32 s56, s28, 0x40000
	v_lshl_add_u64 v[212:213], s[28:29], 0, v[134:135]
	s_addc_u32 s57, s29, 0
	s_add_i32 s55, s58, s41
	global_load_lds_dwordx4 v134, s[28:29]
	s_mov_b32 m0, s55
	v_lshl_add_u64 v[246:247], s[30:31], 0, v[132:133]
	global_load_lds_dwordx4 v112, s[56:57]
	s_add_i32 m0, s55, 0x2000
	s_nop 0
	global_load_lds_dwordx4 v134, s[56:57]
	v_lshl_add_u64 v[228:229], s[30:31], 0, v[130:131]
	s_mov_b32 m0, s42
	s_nop 0
	global_load_lds_dwordx4 v130, s[30:31]
	s_mov_b32 m0, s43
	s_nop 0
	global_load_lds_dwordx4 v132, s[30:31]
	s_waitcnt vmcnt(8)
	s_waitcnt lgkmcnt(0)
	v_mfma_f32_16x16x32_bf16 v[60:63], v[140:143], v[176:179], 0
	v_mfma_f32_16x16x32_bf16 v[56:59], v[152:155], v[176:179], 0
	v_mfma_f32_16x16x32_bf16 v[44:47], v[140:143], v[184:187], 0
	v_mfma_f32_16x16x32_bf16 v[40:43], v[152:155], v[184:187], 0
	v_mfma_f32_16x16x32_bf16 v[28:31], v[140:143], v[230:233], 0
	v_mfma_f32_16x16x32_bf16 v[24:27], v[152:155], v[230:233], 0
	v_mfma_f32_16x16x32_bf16 v[12:15], v[140:143], v[238:241], 0
	v_mfma_f32_16x16x32_bf16 v[8:11], v[152:155], v[238:241], 0
	s_barrier
	s_setprio 1
	v_mfma_f32_16x16x32_bf16 v[60:63], v[148:151], v[180:183], v[60:63]
	v_mfma_f32_16x16x32_bf16 v[56:59], v[156:159], v[180:183], v[56:59]
	v_mfma_f32_16x16x32_bf16 v[44:47], v[148:151], v[208:211], v[44:47]
	v_mfma_f32_16x16x32_bf16 v[40:43], v[156:159], v[208:211], v[40:43]
	v_mfma_f32_16x16x32_bf16 v[28:31], v[148:151], v[234:237], v[28:31]
	v_mfma_f32_16x16x32_bf16 v[24:27], v[156:159], v[234:237], v[24:27]
	v_mfma_f32_16x16x32_bf16 v[12:15], v[148:151], v[242:245], v[12:15]
	v_mfma_f32_16x16x32_bf16 v[8:11], v[156:159], v[242:245], v[8:11]
	s_setprio 0
	s_setprio 1
	v_mfma_f32_16x16x32_bf16 v[52:55], v[160:163], v[176:179], 0
	v_mfma_f32_16x16x32_bf16 v[48:51], v[168:171], v[176:179], 0
	v_mfma_f32_16x16x32_bf16 v[36:39], v[160:163], v[184:187], 0
	v_mfma_f32_16x16x32_bf16 v[32:35], v[168:171], v[184:187], 0
	v_mfma_f32_16x16x32_bf16 v[20:23], v[160:163], v[230:233], 0
	v_mfma_f32_16x16x32_bf16 v[16:19], v[168:171], v[230:233], 0
	v_mfma_f32_16x16x32_bf16 v[4:7], v[160:163], v[238:241], 0
	v_mfma_f32_16x16x32_bf16 v[0:3], v[168:171], v[238:241], 0
	v_mfma_f32_16x16x32_bf16 v[52:55], v[164:167], v[180:183], v[52:55]
	v_mfma_f32_16x16x32_bf16 v[48:51], v[172:175], v[180:183], v[48:51]
	v_mfma_f32_16x16x32_bf16 v[36:39], v[164:167], v[208:211], v[36:39]
	v_mfma_f32_16x16x32_bf16 v[32:35], v[172:175], v[208:211], v[32:35]
	v_mfma_f32_16x16x32_bf16 v[20:23], v[164:167], v[234:237], v[20:23]
	v_mfma_f32_16x16x32_bf16 v[16:19], v[172:175], v[234:237], v[16:19]
	v_mfma_f32_16x16x32_bf16 v[4:7], v[164:167], v[242:245], v[4:7]
	v_mfma_f32_16x16x32_bf16 v[0:3], v[172:175], v[242:245], v[0:3]
	s_setprio 0
	s_barrier
	s_add_i32 s55, 0, 0x18000
	s_add_i32 s56, 0, 0x1c000
	v_add_u32_e32 v156, s55, v145
	v_add_u32_e32 v172, s56, v145
	ds_read_b128 v[140:143], v156
	ds_read_b128 v[148:151], v156 offset:1024
	ds_read_b128 v[152:155], v156 offset:2048
	ds_read_b128 v[156:159], v156 offset:3072
	ds_read_b128 v[160:163], v172
	ds_read_b128 v[164:167], v172 offset:1024
	ds_read_b128 v[168:171], v172 offset:2048
	ds_read_b128 v[172:175], v172 offset:3072
	s_add_u32 s30, s30, 0x80000
	s_addc_u32 s31, s31, 0
	s_mov_b32 m0, s44
	ds_read_b128 v[176:179], v147 offset:32768
	ds_read_b128 v[180:183], v147 offset:33792
	ds_read_b128 v[184:187], v147 offset:34816
	ds_read_b128 v[208:211], v147 offset:35840
	ds_read_b128 v[230:233], v147 offset:36864
	ds_read_b128 v[234:237], v147 offset:37888
	ds_read_b128 v[238:241], v147 offset:38912
	ds_read_b128 v[242:245], v147 offset:39936
	global_load_lds_dwordx4 v130, s[30:31]
	s_mov_b32 m0, s45
	s_nop 0
	global_load_lds_dwordx4 v132, s[30:31]
	s_waitcnt vmcnt(8)
	s_waitcnt lgkmcnt(0)
	v_mfma_f32_16x16x32_bf16 v[126:129], v[140:143], v[176:179], v[126:129]
	v_mfma_f32_16x16x32_bf16 v[122:125], v[152:155], v[176:179], v[122:125]
	v_mfma_f32_16x16x32_bf16 v[108:111], v[140:143], v[184:187], v[108:111]
	v_mfma_f32_16x16x32_bf16 v[104:107], v[152:155], v[184:187], v[104:107]
	v_mfma_f32_16x16x32_bf16 v[92:95], v[140:143], v[230:233], v[92:95]
	v_mfma_f32_16x16x32_bf16 v[88:91], v[152:155], v[230:233], v[88:91]
	v_mfma_f32_16x16x32_bf16 v[76:79], v[140:143], v[238:241], v[76:79]
	v_mfma_f32_16x16x32_bf16 v[72:75], v[152:155], v[238:241], v[72:75]
	s_barrier
	s_setprio 1
	v_mfma_f32_16x16x32_bf16 v[126:129], v[148:151], v[180:183], v[126:129]
	v_mfma_f32_16x16x32_bf16 v[122:125], v[156:159], v[180:183], v[122:125]
	v_mfma_f32_16x16x32_bf16 v[108:111], v[148:151], v[208:211], v[108:111]
	v_mfma_f32_16x16x32_bf16 v[104:107], v[156:159], v[208:211], v[104:107]
	v_mfma_f32_16x16x32_bf16 v[92:95], v[148:151], v[234:237], v[92:95]
	v_mfma_f32_16x16x32_bf16 v[88:91], v[156:159], v[234:237], v[88:91]
	v_mfma_f32_16x16x32_bf16 v[76:79], v[148:151], v[242:245], v[76:79]
	v_mfma_f32_16x16x32_bf16 v[72:75], v[156:159], v[242:245], v[72:75]
	s_setprio 0
	s_setprio 1
	v_mfma_f32_16x16x32_bf16 v[118:121], v[160:163], v[176:179], v[118:121]
	v_mfma_f32_16x16x32_bf16 v[114:117], v[168:171], v[176:179], v[114:117]
	v_mfma_f32_16x16x32_bf16 v[100:103], v[160:163], v[184:187], v[100:103]
	v_mfma_f32_16x16x32_bf16 v[96:99], v[168:171], v[184:187], v[96:99]
	v_mfma_f32_16x16x32_bf16 v[84:87], v[160:163], v[230:233], v[84:87]
	v_mfma_f32_16x16x32_bf16 v[80:83], v[168:171], v[230:233], v[80:83]
	v_mfma_f32_16x16x32_bf16 v[68:71], v[160:163], v[238:241], v[68:71]
	v_mfma_f32_16x16x32_bf16 v[64:67], v[168:171], v[238:241], v[64:67]
	v_mfma_f32_16x16x32_bf16 v[118:121], v[164:167], v[180:183], v[118:121]
	v_mfma_f32_16x16x32_bf16 v[114:117], v[172:175], v[180:183], v[114:117]
	v_mfma_f32_16x16x32_bf16 v[100:103], v[164:167], v[208:211], v[100:103]
	v_mfma_f32_16x16x32_bf16 v[96:99], v[172:175], v[208:211], v[96:99]
	v_mfma_f32_16x16x32_bf16 v[84:87], v[164:167], v[234:237], v[84:87]
	v_mfma_f32_16x16x32_bf16 v[80:83], v[172:175], v[234:237], v[80:83]
	v_mfma_f32_16x16x32_bf16 v[68:71], v[164:167], v[242:245], v[68:71]
	v_mfma_f32_16x16x32_bf16 v[64:67], v[172:175], v[242:245], v[64:67]
	s_setprio 0
	s_barrier
	s_add_i32 s30, s55, s41
	s_mov_b32 m0, s30
	ds_read_b128 v[176:179], v147 offset:49152
	ds_read_b128 v[180:183], v147 offset:50176
	ds_read_b128 v[184:187], v147 offset:51200
	ds_read_b128 v[208:211], v147 offset:52224
	ds_read_b128 v[230:233], v147 offset:53248
	ds_read_b128 v[234:237], v147 offset:54272
	ds_read_b128 v[238:241], v147 offset:55296
	ds_read_b128 v[242:245], v147 offset:56320
	s_add_u32 s98, s28, 0x80
	s_addc_u32 s99, s29, 0
	global_load_lds_dwordx4 v112, s[98:99]
	s_add_i32 m0, s30, 0x2000
	s_add_u32 s28, s28, 0x40080
	v_lshl_add_u64 v[188:189], v[212:213], 0, s[96:97]
	s_addc_u32 s29, s29, 0
	s_add_i32 s30, s56, s41
	global_load_lds_dwordx4 v[188:189], off
	s_mov_b32 m0, s30
	s_nop 0
	global_load_lds_dwordx4 v112, s[28:29]
	s_add_i32 m0, s30, 0x2000
	s_nop 0
	global_load_lds_dwordx4 v134, s[28:29]
	v_lshl_add_u64 v[188:189], v[228:229], 0, s[96:97]
	s_mov_b32 m0, s47
	s_nop 0
	global_load_lds_dwordx4 v[188:189], off
	v_lshl_add_u64 v[188:189], v[246:247], 0, s[96:97]
	s_mov_b32 m0, s48
	s_nop 0
	global_load_lds_dwordx4 v[188:189], off
	s_waitcnt vmcnt(8)
	s_waitcnt lgkmcnt(0)
	v_mfma_f32_16x16x32_bf16 v[60:63], v[140:143], v[176:179], v[60:63]
	v_mfma_f32_16x16x32_bf16 v[56:59], v[152:155], v[176:179], v[56:59]
	v_mfma_f32_16x16x32_bf16 v[44:47], v[140:143], v[184:187], v[44:47]
	v_mfma_f32_16x16x32_bf16 v[40:43], v[152:155], v[184:187], v[40:43]
	v_mfma_f32_16x16x32_bf16 v[28:31], v[140:143], v[230:233], v[28:31]
	v_mfma_f32_16x16x32_bf16 v[24:27], v[152:155], v[230:233], v[24:27]
	v_mfma_f32_16x16x32_bf16 v[12:15], v[140:143], v[238:241], v[12:15]
	v_mfma_f32_16x16x32_bf16 v[8:11], v[152:155], v[238:241], v[8:11]
	s_barrier
	s_setprio 1
	v_mfma_f32_16x16x32_bf16 v[60:63], v[148:151], v[180:183], v[60:63]
	v_mfma_f32_16x16x32_bf16 v[56:59], v[156:159], v[180:183], v[56:59]
	v_mfma_f32_16x16x32_bf16 v[44:47], v[148:151], v[208:211], v[44:47]
	v_mfma_f32_16x16x32_bf16 v[40:43], v[156:159], v[208:211], v[40:43]
	v_mfma_f32_16x16x32_bf16 v[28:31], v[148:151], v[234:237], v[28:31]
	v_mfma_f32_16x16x32_bf16 v[24:27], v[156:159], v[234:237], v[24:27]
	v_mfma_f32_16x16x32_bf16 v[12:15], v[148:151], v[242:245], v[12:15]
	v_mfma_f32_16x16x32_bf16 v[8:11], v[156:159], v[242:245], v[8:11]
	s_setprio 0
	s_setprio 1
	v_mfma_f32_16x16x32_bf16 v[52:55], v[160:163], v[176:179], v[52:55]
	v_mfma_f32_16x16x32_bf16 v[48:51], v[168:171], v[176:179], v[48:51]
	v_mfma_f32_16x16x32_bf16 v[36:39], v[160:163], v[184:187], v[36:39]
	v_mfma_f32_16x16x32_bf16 v[32:35], v[168:171], v[184:187], v[32:35]
	v_mfma_f32_16x16x32_bf16 v[20:23], v[160:163], v[230:233], v[20:23]
	v_mfma_f32_16x16x32_bf16 v[16:19], v[168:171], v[230:233], v[16:19]
	v_mfma_f32_16x16x32_bf16 v[4:7], v[160:163], v[238:241], v[4:7]
	v_mfma_f32_16x16x32_bf16 v[0:3], v[168:171], v[238:241], v[0:3]
	v_mfma_f32_16x16x32_bf16 v[52:55], v[164:167], v[180:183], v[52:55]
	v_mfma_f32_16x16x32_bf16 v[48:51], v[172:175], v[180:183], v[48:51]
	v_mfma_f32_16x16x32_bf16 v[36:39], v[164:167], v[208:211], v[36:39]
	v_mfma_f32_16x16x32_bf16 v[32:35], v[172:175], v[208:211], v[32:35]
	v_mfma_f32_16x16x32_bf16 v[20:23], v[164:167], v[234:237], v[20:23]
	v_mfma_f32_16x16x32_bf16 v[16:19], v[172:175], v[234:237], v[16:19]
	v_mfma_f32_16x16x32_bf16 v[4:7], v[164:167], v[242:245], v[4:7]
	v_mfma_f32_16x16x32_bf16 v[0:3], v[172:175], v[242:245], v[0:3]
	s_setprio 0
	s_barrier
	s_add_i32 s54, s54, 2
	s_add_u32 s52, s52, 0x100
	s_addc_u32 s53, s53, 0
	s_add_u32 s26, s26, 0x100
	s_addc_u32 s27, s27, 0
	s_cmp_gt_u32 s54, 13
	s_cbranch_scc0 .LBB0_758
	s_branch .Lpeel_exit_758
.LBB0_758:
	s_add_u32 s28, s26, 0xfff80080
	s_addc_u32 s29, s27, -1
	s_add_i32 s55, 0, 0x10000
	s_cmp_eq_u32 s54, 12
	s_cselect_b32 s31, s17, s29
	s_cselect_b32 s30, s23, s28
	s_cselect_b32 s29, s15, s53
	s_cselect_b32 s28, s25, s52
	s_add_i32 s58, 0, 0x14000
	v_add_u32_e32 v156, s55, v145
	v_add_u32_e32 v172, s58, v145
	ds_read_b128 v[140:143], v156
	ds_read_b128 v[148:151], v156 offset:1024
	ds_read_b128 v[152:155], v156 offset:2048
	ds_read_b128 v[156:159], v156 offset:3072
	ds_read_b128 v[160:163], v172
	ds_read_b128 v[164:167], v172 offset:1024
	ds_read_b128 v[168:171], v172 offset:2048
	ds_read_b128 v[172:175], v172 offset:3072
	s_add_i32 m0, s42, 0xc000
	ds_read_b128 v[176:179], v147
	ds_read_b128 v[180:183], v147 offset:1024
	ds_read_b128 v[184:187], v147 offset:2048
	ds_read_b128 v[208:211], v147 offset:3072
	ds_read_b128 v[230:233], v147 offset:4096
	ds_read_b128 v[234:237], v147 offset:5120
	ds_read_b128 v[238:241], v147 offset:6144
	ds_read_b128 v[242:245], v147 offset:7168
	global_load_lds_dwordx4 v138, s[26:27]
	s_add_i32 m0, s42, 0xe000
	s_nop 0
	global_load_lds_dwordx4 v136, s[26:27]
	s_waitcnt vmcnt(8)
	s_waitcnt lgkmcnt(0)
	v_mfma_f32_16x16x32_bf16 v[126:129], v[140:143], v[176:179], v[126:129]
	v_mfma_f32_16x16x32_bf16 v[122:125], v[152:155], v[176:179], v[122:125]
	v_mfma_f32_16x16x32_bf16 v[108:111], v[140:143], v[184:187], v[108:111]
	v_mfma_f32_16x16x32_bf16 v[104:107], v[152:155], v[184:187], v[104:107]
	v_mfma_f32_16x16x32_bf16 v[92:95], v[140:143], v[230:233], v[92:95]
	v_mfma_f32_16x16x32_bf16 v[88:91], v[152:155], v[230:233], v[88:91]
	v_mfma_f32_16x16x32_bf16 v[76:79], v[140:143], v[238:241], v[76:79]
	v_mfma_f32_16x16x32_bf16 v[72:75], v[152:155], v[238:241], v[72:75]
	s_barrier
	s_setprio 1
	v_mfma_f32_16x16x32_bf16 v[126:129], v[148:151], v[180:183], v[126:129]
	v_mfma_f32_16x16x32_bf16 v[122:125], v[156:159], v[180:183], v[122:125]
	v_mfma_f32_16x16x32_bf16 v[108:111], v[148:151], v[208:211], v[108:111]
	v_mfma_f32_16x16x32_bf16 v[104:107], v[156:159], v[208:211], v[104:107]
	v_mfma_f32_16x16x32_bf16 v[92:95], v[148:151], v[234:237], v[92:95]
	v_mfma_f32_16x16x32_bf16 v[88:91], v[156:159], v[234:237], v[88:91]
	v_mfma_f32_16x16x32_bf16 v[76:79], v[148:151], v[242:245], v[76:79]
	v_mfma_f32_16x16x32_bf16 v[72:75], v[156:159], v[242:245], v[72:75]
	s_setprio 0
	s_setprio 1
	v_mfma_f32_16x16x32_bf16 v[118:121], v[160:163], v[176:179], v[118:121]
	v_mfma_f32_16x16x32_bf16 v[114:117], v[168:171], v[176:179], v[114:117]
	v_mfma_f32_16x16x32_bf16 v[100:103], v[160:163], v[184:187], v[100:103]
	v_mfma_f32_16x16x32_bf16 v[96:99], v[168:171], v[184:187], v[96:99]
	v_mfma_f32_16x16x32_bf16 v[84:87], v[160:163], v[230:233], v[84:87]
	v_mfma_f32_16x16x32_bf16 v[80:83], v[168:171], v[230:233], v[80:83]
	v_mfma_f32_16x16x32_bf16 v[68:71], v[160:163], v[238:241], v[68:71]
	v_mfma_f32_16x16x32_bf16 v[64:67], v[168:171], v[238:241], v[64:67]
	v_mfma_f32_16x16x32_bf16 v[118:121], v[164:167], v[180:183], v[118:121]
	v_mfma_f32_16x16x32_bf16 v[114:117], v[172:175], v[180:183], v[114:117]
	v_mfma_f32_16x16x32_bf16 v[100:103], v[164:167], v[208:211], v[100:103]
	v_mfma_f32_16x16x32_bf16 v[96:99], v[172:175], v[208:211], v[96:99]
	v_mfma_f32_16x16x32_bf16 v[84:87], v[164:167], v[234:237], v[84:87]
	v_mfma_f32_16x16x32_bf16 v[80:83], v[172:175], v[234:237], v[80:83]
	v_mfma_f32_16x16x32_bf16 v[68:71], v[164:167], v[242:245], v[68:71]
	v_mfma_f32_16x16x32_bf16 v[64:67], v[172:175], v[242:245], v[64:67]
	s_setprio 0
	s_barrier
	s_add_i32 s55, s55, s41
	s_mov_b32 m0, s55
	ds_read_b128 v[176:179], v147 offset:16384
	ds_read_b128 v[180:183], v147 offset:17408
	ds_read_b128 v[184:187], v147 offset:18432
	ds_read_b128 v[208:211], v147 offset:19456
	ds_read_b128 v[230:233], v147 offset:20480
	ds_read_b128 v[234:237], v147 offset:21504
	ds_read_b128 v[238:241], v147 offset:22528
	ds_read_b128 v[242:245], v147 offset:23552
	global_load_lds_dwordx4 v112, s[28:29]
	s_add_i32 m0, s55, 0x2000
	s_add_u32 s56, s28, 0x40000
	v_lshl_add_u64 v[212:213], s[28:29], 0, v[134:135]
	s_addc_u32 s57, s29, 0
	s_add_i32 s55, s58, s41
	global_load_lds_dwordx4 v134, s[28:29]
	s_mov_b32 m0, s55
	v_lshl_add_u64 v[246:247], s[30:31], 0, v[132:133]
	global_load_lds_dwordx4 v112, s[56:57]
	s_add_i32 m0, s55, 0x2000
	s_nop 0
	global_load_lds_dwordx4 v134, s[56:57]
	v_lshl_add_u64 v[228:229], s[30:31], 0, v[130:131]
	s_mov_b32 m0, s42
	s_nop 0
	global_load_lds_dwordx4 v130, s[30:31]
	s_mov_b32 m0, s43
	s_nop 0
	global_load_lds_dwordx4 v132, s[30:31]
	s_waitcnt vmcnt(8)
	s_waitcnt lgkmcnt(0)
	v_mfma_f32_16x16x32_bf16 v[60:63], v[140:143], v[176:179], v[60:63]
	v_mfma_f32_16x16x32_bf16 v[56:59], v[152:155], v[176:179], v[56:59]
	v_mfma_f32_16x16x32_bf16 v[44:47], v[140:143], v[184:187], v[44:47]
	v_mfma_f32_16x16x32_bf16 v[40:43], v[152:155], v[184:187], v[40:43]
	v_mfma_f32_16x16x32_bf16 v[28:31], v[140:143], v[230:233], v[28:31]
	v_mfma_f32_16x16x32_bf16 v[24:27], v[152:155], v[230:233], v[24:27]
	v_mfma_f32_16x16x32_bf16 v[12:15], v[140:143], v[238:241], v[12:15]
	v_mfma_f32_16x16x32_bf16 v[8:11], v[152:155], v[238:241], v[8:11]
	s_barrier
	s_setprio 1
	v_mfma_f32_16x16x32_bf16 v[60:63], v[148:151], v[180:183], v[60:63]
	v_mfma_f32_16x16x32_bf16 v[56:59], v[156:159], v[180:183], v[56:59]
	v_mfma_f32_16x16x32_bf16 v[44:47], v[148:151], v[208:211], v[44:47]
	v_mfma_f32_16x16x32_bf16 v[40:43], v[156:159], v[208:211], v[40:43]
	v_mfma_f32_16x16x32_bf16 v[28:31], v[148:151], v[234:237], v[28:31]
	v_mfma_f32_16x16x32_bf16 v[24:27], v[156:159], v[234:237], v[24:27]
	v_mfma_f32_16x16x32_bf16 v[12:15], v[148:151], v[242:245], v[12:15]
	v_mfma_f32_16x16x32_bf16 v[8:11], v[156:159], v[242:245], v[8:11]
	s_setprio 0
	s_setprio 1
	v_mfma_f32_16x16x32_bf16 v[52:55], v[160:163], v[176:179], v[52:55]
	v_mfma_f32_16x16x32_bf16 v[48:51], v[168:171], v[176:179], v[48:51]
	v_mfma_f32_16x16x32_bf16 v[36:39], v[160:163], v[184:187], v[36:39]
	v_mfma_f32_16x16x32_bf16 v[32:35], v[168:171], v[184:187], v[32:35]
	v_mfma_f32_16x16x32_bf16 v[20:23], v[160:163], v[230:233], v[20:23]
	v_mfma_f32_16x16x32_bf16 v[16:19], v[168:171], v[230:233], v[16:19]
	v_mfma_f32_16x16x32_bf16 v[4:7], v[160:163], v[238:241], v[4:7]
	v_mfma_f32_16x16x32_bf16 v[0:3], v[168:171], v[238:241], v[0:3]
	v_mfma_f32_16x16x32_bf16 v[52:55], v[164:167], v[180:183], v[52:55]
	v_mfma_f32_16x16x32_bf16 v[48:51], v[172:175], v[180:183], v[48:51]
	v_mfma_f32_16x16x32_bf16 v[36:39], v[164:167], v[208:211], v[36:39]
	v_mfma_f32_16x16x32_bf16 v[32:35], v[172:175], v[208:211], v[32:35]
	v_mfma_f32_16x16x32_bf16 v[20:23], v[164:167], v[234:237], v[20:23]
	v_mfma_f32_16x16x32_bf16 v[16:19], v[172:175], v[234:237], v[16:19]
	v_mfma_f32_16x16x32_bf16 v[4:7], v[164:167], v[242:245], v[4:7]
	v_mfma_f32_16x16x32_bf16 v[0:3], v[172:175], v[242:245], v[0:3]
	s_setprio 0
	s_barrier
	s_add_i32 s55, 0, 0x18000
	s_add_i32 s56, 0, 0x1c000
	v_add_u32_e32 v156, s55, v145
	v_add_u32_e32 v172, s56, v145
	ds_read_b128 v[140:143], v156
	ds_read_b128 v[148:151], v156 offset:1024
	ds_read_b128 v[152:155], v156 offset:2048
	ds_read_b128 v[156:159], v156 offset:3072
	ds_read_b128 v[160:163], v172
	ds_read_b128 v[164:167], v172 offset:1024
	ds_read_b128 v[168:171], v172 offset:2048
	ds_read_b128 v[172:175], v172 offset:3072
	s_add_u32 s30, s30, 0x80000
	s_addc_u32 s31, s31, 0
	s_mov_b32 m0, s44
	ds_read_b128 v[176:179], v147 offset:32768
	ds_read_b128 v[180:183], v147 offset:33792
	ds_read_b128 v[184:187], v147 offset:34816
	ds_read_b128 v[208:211], v147 offset:35840
	ds_read_b128 v[230:233], v147 offset:36864
	ds_read_b128 v[234:237], v147 offset:37888
	ds_read_b128 v[238:241], v147 offset:38912
	ds_read_b128 v[242:245], v147 offset:39936
	global_load_lds_dwordx4 v130, s[30:31]
	s_mov_b32 m0, s45
	s_nop 0
	global_load_lds_dwordx4 v132, s[30:31]
	s_waitcnt vmcnt(8)
	s_waitcnt lgkmcnt(0)
	v_mfma_f32_16x16x32_bf16 v[126:129], v[140:143], v[176:179], v[126:129]
	v_mfma_f32_16x16x32_bf16 v[122:125], v[152:155], v[176:179], v[122:125]
	v_mfma_f32_16x16x32_bf16 v[108:111], v[140:143], v[184:187], v[108:111]
	v_mfma_f32_16x16x32_bf16 v[104:107], v[152:155], v[184:187], v[104:107]
	v_mfma_f32_16x16x32_bf16 v[92:95], v[140:143], v[230:233], v[92:95]
	v_mfma_f32_16x16x32_bf16 v[88:91], v[152:155], v[230:233], v[88:91]
	v_mfma_f32_16x16x32_bf16 v[76:79], v[140:143], v[238:241], v[76:79]
	v_mfma_f32_16x16x32_bf16 v[72:75], v[152:155], v[238:241], v[72:75]
	s_barrier
	s_setprio 1
	v_mfma_f32_16x16x32_bf16 v[126:129], v[148:151], v[180:183], v[126:129]
	v_mfma_f32_16x16x32_bf16 v[122:125], v[156:159], v[180:183], v[122:125]
	v_mfma_f32_16x16x32_bf16 v[108:111], v[148:151], v[208:211], v[108:111]
	v_mfma_f32_16x16x32_bf16 v[104:107], v[156:159], v[208:211], v[104:107]
	v_mfma_f32_16x16x32_bf16 v[92:95], v[148:151], v[234:237], v[92:95]
	v_mfma_f32_16x16x32_bf16 v[88:91], v[156:159], v[234:237], v[88:91]
	v_mfma_f32_16x16x32_bf16 v[76:79], v[148:151], v[242:245], v[76:79]
	v_mfma_f32_16x16x32_bf16 v[72:75], v[156:159], v[242:245], v[72:75]
	s_setprio 0
	s_setprio 1
	v_mfma_f32_16x16x32_bf16 v[118:121], v[160:163], v[176:179], v[118:121]
	v_mfma_f32_16x16x32_bf16 v[114:117], v[168:171], v[176:179], v[114:117]
	v_mfma_f32_16x16x32_bf16 v[100:103], v[160:163], v[184:187], v[100:103]
	v_mfma_f32_16x16x32_bf16 v[96:99], v[168:171], v[184:187], v[96:99]
	v_mfma_f32_16x16x32_bf16 v[84:87], v[160:163], v[230:233], v[84:87]
	v_mfma_f32_16x16x32_bf16 v[80:83], v[168:171], v[230:233], v[80:83]
	v_mfma_f32_16x16x32_bf16 v[68:71], v[160:163], v[238:241], v[68:71]
	v_mfma_f32_16x16x32_bf16 v[64:67], v[168:171], v[238:241], v[64:67]
	v_mfma_f32_16x16x32_bf16 v[118:121], v[164:167], v[180:183], v[118:121]
	v_mfma_f32_16x16x32_bf16 v[114:117], v[172:175], v[180:183], v[114:117]
	v_mfma_f32_16x16x32_bf16 v[100:103], v[164:167], v[208:211], v[100:103]
	v_mfma_f32_16x16x32_bf16 v[96:99], v[172:175], v[208:211], v[96:99]
	v_mfma_f32_16x16x32_bf16 v[84:87], v[164:167], v[234:237], v[84:87]
	v_mfma_f32_16x16x32_bf16 v[80:83], v[172:175], v[234:237], v[80:83]
	v_mfma_f32_16x16x32_bf16 v[68:71], v[164:167], v[242:245], v[68:71]
	v_mfma_f32_16x16x32_bf16 v[64:67], v[172:175], v[242:245], v[64:67]
	s_setprio 0
	s_barrier
	s_add_i32 s30, s55, s41
	s_mov_b32 m0, s30
	ds_read_b128 v[176:179], v147 offset:49152
	ds_read_b128 v[180:183], v147 offset:50176
	ds_read_b128 v[184:187], v147 offset:51200
	ds_read_b128 v[208:211], v147 offset:52224
	ds_read_b128 v[230:233], v147 offset:53248
	ds_read_b128 v[234:237], v147 offset:54272
	ds_read_b128 v[238:241], v147 offset:55296
	ds_read_b128 v[242:245], v147 offset:56320
	s_add_u32 s98, s28, 0x80
	s_addc_u32 s99, s29, 0
	global_load_lds_dwordx4 v112, s[98:99]
	s_add_i32 m0, s30, 0x2000
	s_add_u32 s28, s28, 0x40080
	v_lshl_add_u64 v[188:189], v[212:213], 0, s[96:97]
	s_addc_u32 s29, s29, 0
	s_add_i32 s30, s56, s41
	global_load_lds_dwordx4 v[188:189], off
	s_mov_b32 m0, s30
	s_nop 0
	global_load_lds_dwordx4 v112, s[28:29]
	s_add_i32 m0, s30, 0x2000
	s_nop 0
	global_load_lds_dwordx4 v134, s[28:29]
	v_lshl_add_u64 v[188:189], v[228:229], 0, s[96:97]
	s_mov_b32 m0, s47
	s_nop 0
	global_load_lds_dwordx4 v[188:189], off
	v_lshl_add_u64 v[188:189], v[246:247], 0, s[96:97]
	s_mov_b32 m0, s48
	s_nop 0
	global_load_lds_dwordx4 v[188:189], off
	s_waitcnt vmcnt(8)
	s_waitcnt lgkmcnt(0)
	v_mfma_f32_16x16x32_bf16 v[60:63], v[140:143], v[176:179], v[60:63]
	v_mfma_f32_16x16x32_bf16 v[56:59], v[152:155], v[176:179], v[56:59]
	v_mfma_f32_16x16x32_bf16 v[44:47], v[140:143], v[184:187], v[44:47]
	v_mfma_f32_16x16x32_bf16 v[40:43], v[152:155], v[184:187], v[40:43]
	v_mfma_f32_16x16x32_bf16 v[28:31], v[140:143], v[230:233], v[28:31]
	v_mfma_f32_16x16x32_bf16 v[24:27], v[152:155], v[230:233], v[24:27]
	v_mfma_f32_16x16x32_bf16 v[12:15], v[140:143], v[238:241], v[12:15]
	v_mfma_f32_16x16x32_bf16 v[8:11], v[152:155], v[238:241], v[8:11]
	s_barrier
	s_setprio 1
	v_mfma_f32_16x16x32_bf16 v[60:63], v[148:151], v[180:183], v[60:63]
	v_mfma_f32_16x16x32_bf16 v[56:59], v[156:159], v[180:183], v[56:59]
	v_mfma_f32_16x16x32_bf16 v[44:47], v[148:151], v[208:211], v[44:47]
	v_mfma_f32_16x16x32_bf16 v[40:43], v[156:159], v[208:211], v[40:43]
	v_mfma_f32_16x16x32_bf16 v[28:31], v[148:151], v[234:237], v[28:31]
	v_mfma_f32_16x16x32_bf16 v[24:27], v[156:159], v[234:237], v[24:27]
	v_mfma_f32_16x16x32_bf16 v[12:15], v[148:151], v[242:245], v[12:15]
	v_mfma_f32_16x16x32_bf16 v[8:11], v[156:159], v[242:245], v[8:11]
	s_setprio 0
	s_setprio 1
	v_mfma_f32_16x16x32_bf16 v[52:55], v[160:163], v[176:179], v[52:55]
	v_mfma_f32_16x16x32_bf16 v[48:51], v[168:171], v[176:179], v[48:51]
	v_mfma_f32_16x16x32_bf16 v[36:39], v[160:163], v[184:187], v[36:39]
	v_mfma_f32_16x16x32_bf16 v[32:35], v[168:171], v[184:187], v[32:35]
	v_mfma_f32_16x16x32_bf16 v[20:23], v[160:163], v[230:233], v[20:23]
	v_mfma_f32_16x16x32_bf16 v[16:19], v[168:171], v[230:233], v[16:19]
	v_mfma_f32_16x16x32_bf16 v[4:7], v[160:163], v[238:241], v[4:7]
	v_mfma_f32_16x16x32_bf16 v[0:3], v[168:171], v[238:241], v[0:3]
	v_mfma_f32_16x16x32_bf16 v[52:55], v[164:167], v[180:183], v[52:55]
	v_mfma_f32_16x16x32_bf16 v[48:51], v[172:175], v[180:183], v[48:51]
	v_mfma_f32_16x16x32_bf16 v[36:39], v[164:167], v[208:211], v[36:39]
	v_mfma_f32_16x16x32_bf16 v[32:35], v[172:175], v[208:211], v[32:35]
	v_mfma_f32_16x16x32_bf16 v[20:23], v[164:167], v[234:237], v[20:23]
	v_mfma_f32_16x16x32_bf16 v[16:19], v[172:175], v[234:237], v[16:19]
	v_mfma_f32_16x16x32_bf16 v[4:7], v[164:167], v[242:245], v[4:7]
	v_mfma_f32_16x16x32_bf16 v[0:3], v[172:175], v[242:245], v[0:3]
	s_setprio 0
	s_barrier
	s_add_i32 s54, s54, 2
	s_add_u32 s52, s52, 0x100
	s_addc_u32 s53, s53, 0
	s_add_u32 s26, s26, 0x100
	s_addc_u32 s27, s27, 0
	s_cmp_gt_u32 s54, 13
	s_cbranch_scc0 .LBB0_758

.LBB0_803:
	s_ashr_i32 s15, s14, 31
	s_lshl_b64 s[18:19], s[14:15], 20
	s_add_u32 s18, s38, s18
	s_addc_u32 s19, s39, s19
	s_and_b64 s[0:1], s[0:1], exec
	s_cselect_b32 s15, s19, s25
	s_cselect_b32 s21, s18, s24
	s_add_u32 s50, s24, 0x100
	s_addc_u32 s51, s25, 0
	s_mov_b32 s52, -2
	s_waitcnt lgkmcnt(0)
	s_add_u32 s0, s22, 0x100
	s_addc_u32 s1, s23, 0
	s_add_i32 s53, 0, 0x10000
	s_cmp_eq_u32 s52, 28
	s_cselect_b32 s27, s17, s1
	s_cselect_b32 s26, s16, s0
	s_cselect_b32 s25, s15, s51
	s_cselect_b32 s24, s21, s50
	s_add_i32 s54, 0, 0x14000
	v_add_u32_e32 v156, s53, v145
	v_add_u32_e32 v172, s54, v145
	ds_read_b128 v[140:143], v156
	ds_read_b128 v[148:151], v156 offset:1024
	ds_read_b128 v[152:155], v156 offset:2048
	ds_read_b128 v[156:159], v156 offset:3072
	ds_read_b128 v[160:163], v172
	ds_read_b128 v[164:167], v172 offset:1024
	ds_read_b128 v[168:171], v172 offset:2048
	ds_read_b128 v[172:175], v172 offset:3072
	s_add_i32 m0, s31, 0xc000
	ds_read_b128 v[176:179], v147
	ds_read_b128 v[180:183], v147 offset:1024
	ds_read_b128 v[184:187], v147 offset:2048
	ds_read_b128 v[208:211], v147 offset:3072
	ds_read_b128 v[230:233], v147 offset:4096
	ds_read_b128 v[234:237], v147 offset:5120
	ds_read_b128 v[238:241], v147 offset:6144
	ds_read_b128 v[242:245], v147 offset:7168
	global_load_lds_dwordx4 v138, s[22:23]
	s_add_i32 m0, s31, 0xe000
	s_nop 0
	global_load_lds_dwordx4 v136, s[22:23]
	s_waitcnt vmcnt(8)
	s_waitcnt lgkmcnt(0)
	v_mfma_f32_16x16x32_bf16 v[126:129], v[140:143], v[176:179], 0
	v_mfma_f32_16x16x32_bf16 v[122:125], v[152:155], v[176:179], 0
	v_mfma_f32_16x16x32_bf16 v[108:111], v[140:143], v[184:187], 0
	v_mfma_f32_16x16x32_bf16 v[104:107], v[152:155], v[184:187], 0
	v_mfma_f32_16x16x32_bf16 v[92:95], v[140:143], v[230:233], 0
	v_mfma_f32_16x16x32_bf16 v[88:91], v[152:155], v[230:233], 0
	v_mfma_f32_16x16x32_bf16 v[76:79], v[140:143], v[238:241], 0
	v_mfma_f32_16x16x32_bf16 v[72:75], v[152:155], v[238:241], 0
	s_barrier
	s_setprio 1
	v_mfma_f32_16x16x32_bf16 v[126:129], v[148:151], v[180:183], v[126:129]
	v_mfma_f32_16x16x32_bf16 v[122:125], v[156:159], v[180:183], v[122:125]
	v_mfma_f32_16x16x32_bf16 v[108:111], v[148:151], v[208:211], v[108:111]
	v_mfma_f32_16x16x32_bf16 v[104:107], v[156:159], v[208:211], v[104:107]
	v_mfma_f32_16x16x32_bf16 v[92:95], v[148:151], v[234:237], v[92:95]
	v_mfma_f32_16x16x32_bf16 v[88:91], v[156:159], v[234:237], v[88:91]
	v_mfma_f32_16x16x32_bf16 v[76:79], v[148:151], v[242:245], v[76:79]
	v_mfma_f32_16x16x32_bf16 v[72:75], v[156:159], v[242:245], v[72:75]
	s_setprio 0
	s_setprio 1
	v_mfma_f32_16x16x32_bf16 v[118:121], v[160:163], v[176:179], 0
	v_mfma_f32_16x16x32_bf16 v[114:117], v[168:171], v[176:179], 0
	v_mfma_f32_16x16x32_bf16 v[100:103], v[160:163], v[184:187], 0
	v_mfma_f32_16x16x32_bf16 v[96:99], v[168:171], v[184:187], 0
	v_mfma_f32_16x16x32_bf16 v[84:87], v[160:163], v[230:233], 0
	v_mfma_f32_16x16x32_bf16 v[80:83], v[168:171], v[230:233], 0
	v_mfma_f32_16x16x32_bf16 v[68:71], v[160:163], v[238:241], 0
	v_mfma_f32_16x16x32_bf16 v[64:67], v[168:171], v[238:241], 0
	v_mfma_f32_16x16x32_bf16 v[118:121], v[164:167], v[180:183], v[118:121]
	v_mfma_f32_16x16x32_bf16 v[114:117], v[172:175], v[180:183], v[114:117]
	v_mfma_f32_16x16x32_bf16 v[100:103], v[164:167], v[208:211], v[100:103]
	v_mfma_f32_16x16x32_bf16 v[96:99], v[172:175], v[208:211], v[96:99]
	v_mfma_f32_16x16x32_bf16 v[84:87], v[164:167], v[234:237], v[84:87]
	v_mfma_f32_16x16x32_bf16 v[80:83], v[172:175], v[234:237], v[80:83]
	v_mfma_f32_16x16x32_bf16 v[68:71], v[164:167], v[242:245], v[68:71]
	v_mfma_f32_16x16x32_bf16 v[64:67], v[172:175], v[242:245], v[64:67]
	s_setprio 0
	s_barrier
	s_add_i32 s22, s53, s30
	s_mov_b32 m0, s22
	ds_read_b128 v[176:179], v147 offset:16384
	ds_read_b128 v[180:183], v147 offset:17408
	ds_read_b128 v[184:187], v147 offset:18432
	ds_read_b128 v[208:211], v147 offset:19456
	ds_read_b128 v[230:233], v147 offset:20480
	ds_read_b128 v[234:237], v147 offset:21504
	ds_read_b128 v[238:241], v147 offset:22528
	ds_read_b128 v[242:245], v147 offset:23552
	global_load_lds_dwordx4 v112, s[24:25]
	s_add_i32 m0, s22, 0x2000
	s_add_u32 s22, s24, 0x80000
	v_lshl_add_u64 v[212:213], s[24:25], 0, v[134:135]
	s_addc_u32 s23, s25, 0
	s_add_i32 s53, s54, s30
	global_load_lds_dwordx4 v134, s[24:25]
	s_mov_b32 m0, s53
	s_nop 0
	global_load_lds_dwordx4 v112, s[22:23]
	s_add_i32 m0, s53, 0x2000
	s_nop 0
	global_load_lds_dwordx4 v134, s[22:23]
	s_mov_b32 m0, s31
	s_nop 0
	global_load_lds_dwordx4 v130, s[26:27]
	s_mov_b32 m0, s35
	s_nop 0
	global_load_lds_dwordx4 v132, s[26:27]
	s_waitcnt vmcnt(8)
	s_waitcnt lgkmcnt(0)
	v_mfma_f32_16x16x32_bf16 v[60:63], v[140:143], v[176:179], 0
	v_mfma_f32_16x16x32_bf16 v[56:59], v[152:155], v[176:179], 0
	v_mfma_f32_16x16x32_bf16 v[44:47], v[140:143], v[184:187], 0
	v_mfma_f32_16x16x32_bf16 v[40:43], v[152:155], v[184:187], 0
	v_mfma_f32_16x16x32_bf16 v[28:31], v[140:143], v[230:233], 0
	v_mfma_f32_16x16x32_bf16 v[24:27], v[152:155], v[230:233], 0
	v_mfma_f32_16x16x32_bf16 v[12:15], v[140:143], v[238:241], 0
	v_mfma_f32_16x16x32_bf16 v[8:11], v[152:155], v[238:241], 0
	s_barrier
	s_setprio 1
	v_mfma_f32_16x16x32_bf16 v[60:63], v[148:151], v[180:183], v[60:63]
	v_mfma_f32_16x16x32_bf16 v[56:59], v[156:159], v[180:183], v[56:59]
	v_mfma_f32_16x16x32_bf16 v[44:47], v[148:151], v[208:211], v[44:47]
	v_mfma_f32_16x16x32_bf16 v[40:43], v[156:159], v[208:211], v[40:43]
	v_mfma_f32_16x16x32_bf16 v[28:31], v[148:151], v[234:237], v[28:31]
	v_mfma_f32_16x16x32_bf16 v[24:27], v[156:159], v[234:237], v[24:27]
	v_mfma_f32_16x16x32_bf16 v[12:15], v[148:151], v[242:245], v[12:15]
	v_mfma_f32_16x16x32_bf16 v[8:11], v[156:159], v[242:245], v[8:11]
	s_setprio 0
	s_setprio 1
	v_mfma_f32_16x16x32_bf16 v[52:55], v[160:163], v[176:179], 0
	v_mfma_f32_16x16x32_bf16 v[48:51], v[168:171], v[176:179], 0
	v_mfma_f32_16x16x32_bf16 v[36:39], v[160:163], v[184:187], 0
	v_mfma_f32_16x16x32_bf16 v[32:35], v[168:171], v[184:187], 0
	v_mfma_f32_16x16x32_bf16 v[20:23], v[160:163], v[230:233], 0
	v_mfma_f32_16x16x32_bf16 v[16:19], v[168:171], v[230:233], 0
	v_mfma_f32_16x16x32_bf16 v[4:7], v[160:163], v[238:241], 0
	v_mfma_f32_16x16x32_bf16 v[0:3], v[168:171], v[238:241], 0
	v_mfma_f32_16x16x32_bf16 v[52:55], v[164:167], v[180:183], v[52:55]
	v_mfma_f32_16x16x32_bf16 v[48:51], v[172:175], v[180:183], v[48:51]
	v_mfma_f32_16x16x32_bf16 v[36:39], v[164:167], v[208:211], v[36:39]
	v_mfma_f32_16x16x32_bf16 v[32:35], v[172:175], v[208:211], v[32:35]
	v_mfma_f32_16x16x32_bf16 v[20:23], v[164:167], v[234:237], v[20:23]
	v_mfma_f32_16x16x32_bf16 v[16:19], v[172:175], v[234:237], v[16:19]
	v_mfma_f32_16x16x32_bf16 v[4:7], v[164:167], v[242:245], v[4:7]
	v_mfma_f32_16x16x32_bf16 v[0:3], v[172:175], v[242:245], v[0:3]
	s_setprio 0
	s_barrier
	s_add_i32 s53, 0, 0x18000
	s_add_i32 s54, 0, 0x1c000
	v_add_u32_e32 v156, s53, v145
	v_add_u32_e32 v172, s54, v145
	ds_read_b128 v[140:143], v156
	ds_read_b128 v[148:151], v156 offset:1024
	ds_read_b128 v[152:155], v156 offset:2048
	ds_read_b128 v[156:159], v156 offset:3072
	ds_read_b128 v[160:163], v172
	ds_read_b128 v[164:167], v172 offset:1024
	ds_read_b128 v[168:171], v172 offset:2048
	ds_read_b128 v[172:175], v172 offset:3072
	s_add_u32 s22, s26, 0x120000
	s_addc_u32 s23, s27, 0
	s_mov_b32 m0, s40
	ds_read_b128 v[176:179], v147 offset:32768
	ds_read_b128 v[180:183], v147 offset:33792
	ds_read_b128 v[184:187], v147 offset:34816
	ds_read_b128 v[208:211], v147 offset:35840
	ds_read_b128 v[230:233], v147 offset:36864
	ds_read_b128 v[234:237], v147 offset:37888
	ds_read_b128 v[238:241], v147 offset:38912
	ds_read_b128 v[242:245], v147 offset:39936
	global_load_lds_dwordx4 v130, s[22:23]
	s_mov_b32 m0, s41
	s_nop 0
	global_load_lds_dwordx4 v132, s[22:23]
	s_waitcnt vmcnt(8)
	s_waitcnt lgkmcnt(0)
	v_mfma_f32_16x16x32_bf16 v[126:129], v[140:143], v[176:179], v[126:129]
	v_mfma_f32_16x16x32_bf16 v[122:125], v[152:155], v[176:179], v[122:125]
	v_mfma_f32_16x16x32_bf16 v[108:111], v[140:143], v[184:187], v[108:111]
	v_mfma_f32_16x16x32_bf16 v[104:107], v[152:155], v[184:187], v[104:107]
	v_mfma_f32_16x16x32_bf16 v[92:95], v[140:143], v[230:233], v[92:95]
	v_mfma_f32_16x16x32_bf16 v[88:91], v[152:155], v[230:233], v[88:91]
	v_mfma_f32_16x16x32_bf16 v[76:79], v[140:143], v[238:241], v[76:79]
	v_mfma_f32_16x16x32_bf16 v[72:75], v[152:155], v[238:241], v[72:75]
	s_barrier
	s_setprio 1
	v_mfma_f32_16x16x32_bf16 v[126:129], v[148:151], v[180:183], v[126:129]
	v_mfma_f32_16x16x32_bf16 v[122:125], v[156:159], v[180:183], v[122:125]
	v_mfma_f32_16x16x32_bf16 v[108:111], v[148:151], v[208:211], v[108:111]
	v_mfma_f32_16x16x32_bf16 v[104:107], v[156:159], v[208:211], v[104:107]
	v_mfma_f32_16x16x32_bf16 v[92:95], v[148:151], v[234:237], v[92:95]
	v_mfma_f32_16x16x32_bf16 v[88:91], v[156:159], v[234:237], v[88:91]
	v_mfma_f32_16x16x32_bf16 v[76:79], v[148:151], v[242:245], v[76:79]
	v_mfma_f32_16x16x32_bf16 v[72:75], v[156:159], v[242:245], v[72:75]
	s_setprio 0
	s_setprio 1
	v_mfma_f32_16x16x32_bf16 v[118:121], v[160:163], v[176:179], v[118:121]
	v_mfma_f32_16x16x32_bf16 v[114:117], v[168:171], v[176:179], v[114:117]
	v_mfma_f32_16x16x32_bf16 v[100:103], v[160:163], v[184:187], v[100:103]
	v_mfma_f32_16x16x32_bf16 v[96:99], v[168:171], v[184:187], v[96:99]
	v_mfma_f32_16x16x32_bf16 v[84:87], v[160:163], v[230:233], v[84:87]
	v_mfma_f32_16x16x32_bf16 v[80:83], v[168:171], v[230:233], v[80:83]
	v_mfma_f32_16x16x32_bf16 v[68:71], v[160:163], v[238:241], v[68:71]
	v_mfma_f32_16x16x32_bf16 v[64:67], v[168:171], v[238:241], v[64:67]
	v_mfma_f32_16x16x32_bf16 v[118:121], v[164:167], v[180:183], v[118:121]
	v_mfma_f32_16x16x32_bf16 v[114:117], v[172:175], v[180:183], v[114:117]
	v_mfma_f32_16x16x32_bf16 v[100:103], v[164:167], v[208:211], v[100:103]
	v_mfma_f32_16x16x32_bf16 v[96:99], v[172:175], v[208:211], v[96:99]
	v_mfma_f32_16x16x32_bf16 v[84:87], v[164:167], v[234:237], v[84:87]
	v_mfma_f32_16x16x32_bf16 v[80:83], v[172:175], v[234:237], v[80:83]
	v_mfma_f32_16x16x32_bf16 v[68:71], v[164:167], v[242:245], v[68:71]
	v_mfma_f32_16x16x32_bf16 v[64:67], v[172:175], v[242:245], v[64:67]
	s_setprio 0
	s_barrier
	s_add_i32 s22, s53, s30
	s_mov_b32 m0, s22
	ds_read_b128 v[176:179], v147 offset:49152
	ds_read_b128 v[180:183], v147 offset:50176
	ds_read_b128 v[184:187], v147 offset:51200
	ds_read_b128 v[208:211], v147 offset:52224
	ds_read_b128 v[230:233], v147 offset:53248
	ds_read_b128 v[234:237], v147 offset:54272
	ds_read_b128 v[238:241], v147 offset:55296
	ds_read_b128 v[242:245], v147 offset:56320
	s_add_u32 s98, s24, 0x80
	s_addc_u32 s99, s25, 0
	global_load_lds_dwordx4 v112, s[98:99]
	s_add_i32 m0, s22, 0x2000
	s_add_u32 s22, s24, 0x80080
	v_lshl_add_u64 v[188:189], v[212:213], 0, s[96:97]
	s_addc_u32 s23, s25, 0
	s_add_i32 s24, s54, s30
	global_load_lds_dwordx4 v[188:189], off
	s_mov_b32 m0, s24
	s_nop 0
	global_load_lds_dwordx4 v112, s[22:23]
	s_add_i32 m0, s24, 0x2000
	s_nop 0
	global_load_lds_dwordx4 v134, s[22:23]
	s_mov_b32 m0, s43
	s_nop 0
	s_add_u32 s98, s26, 0x80
	s_addc_u32 s99, s27, 0
	global_load_lds_dwordx4 v130, s[98:99]
	s_mov_b32 m0, s44
	s_nop 0
	s_add_u32 s98, s26, 0x80
	s_addc_u32 s99, s27, 0
	global_load_lds_dwordx4 v132, s[98:99]
	s_waitcnt vmcnt(8)
	s_waitcnt lgkmcnt(0)
	v_mfma_f32_16x16x32_bf16 v[60:63], v[140:143], v[176:179], v[60:63]
	v_mfma_f32_16x16x32_bf16 v[56:59], v[152:155], v[176:179], v[56:59]
	v_mfma_f32_16x16x32_bf16 v[44:47], v[140:143], v[184:187], v[44:47]
	v_mfma_f32_16x16x32_bf16 v[40:43], v[152:155], v[184:187], v[40:43]
	v_mfma_f32_16x16x32_bf16 v[28:31], v[140:143], v[230:233], v[28:31]
	v_mfma_f32_16x16x32_bf16 v[24:27], v[152:155], v[230:233], v[24:27]
	v_mfma_f32_16x16x32_bf16 v[12:15], v[140:143], v[238:241], v[12:15]
	v_mfma_f32_16x16x32_bf16 v[8:11], v[152:155], v[238:241], v[8:11]
	s_barrier
	s_setprio 1
	v_mfma_f32_16x16x32_bf16 v[60:63], v[148:151], v[180:183], v[60:63]
	v_mfma_f32_16x16x32_bf16 v[56:59], v[156:159], v[180:183], v[56:59]
	v_mfma_f32_16x16x32_bf16 v[44:47], v[148:151], v[208:211], v[44:47]
	v_mfma_f32_16x16x32_bf16 v[40:43], v[156:159], v[208:211], v[40:43]
	v_mfma_f32_16x16x32_bf16 v[28:31], v[148:151], v[234:237], v[28:31]
	v_mfma_f32_16x16x32_bf16 v[24:27], v[156:159], v[234:237], v[24:27]
	v_mfma_f32_16x16x32_bf16 v[12:15], v[148:151], v[242:245], v[12:15]
	v_mfma_f32_16x16x32_bf16 v[8:11], v[156:159], v[242:245], v[8:11]
	s_setprio 0
	s_setprio 1
	v_mfma_f32_16x16x32_bf16 v[52:55], v[160:163], v[176:179], v[52:55]
	v_mfma_f32_16x16x32_bf16 v[48:51], v[168:171], v[176:179], v[48:51]
	v_mfma_f32_16x16x32_bf16 v[36:39], v[160:163], v[184:187], v[36:39]
	v_mfma_f32_16x16x32_bf16 v[32:35], v[168:171], v[184:187], v[32:35]
	v_mfma_f32_16x16x32_bf16 v[20:23], v[160:163], v[230:233], v[20:23]
	v_mfma_f32_16x16x32_bf16 v[16:19], v[168:171], v[230:233], v[16:19]
	v_mfma_f32_16x16x32_bf16 v[4:7], v[160:163], v[238:241], v[4:7]
	v_mfma_f32_16x16x32_bf16 v[0:3], v[168:171], v[238:241], v[0:3]
	v_mfma_f32_16x16x32_bf16 v[52:55], v[164:167], v[180:183], v[52:55]
	v_mfma_f32_16x16x32_bf16 v[48:51], v[172:175], v[180:183], v[48:51]
	v_mfma_f32_16x16x32_bf16 v[36:39], v[164:167], v[208:211], v[36:39]
	v_mfma_f32_16x16x32_bf16 v[32:35], v[172:175], v[208:211], v[32:35]
	v_mfma_f32_16x16x32_bf16 v[20:23], v[164:167], v[234:237], v[20:23]
	v_mfma_f32_16x16x32_bf16 v[16:19], v[172:175], v[234:237], v[16:19]
	v_mfma_f32_16x16x32_bf16 v[4:7], v[164:167], v[242:245], v[4:7]
	v_mfma_f32_16x16x32_bf16 v[0:3], v[172:175], v[242:245], v[0:3]
	s_setprio 0
	s_barrier
	s_add_i32 s52, s52, 2
	s_add_u32 s50, s50, 0x100
	s_addc_u32 s51, s51, 0
	s_cmp_gt_u32 s52, 29
	s_mov_b64 s[22:23], s[0:1]
	s_cbranch_scc0 .LBB0_804
	s_branch .Lpeel_exit_804
.LBB0_804:
	s_add_u32 s0, s22, 0x100
	s_addc_u32 s1, s23, 0
	s_add_i32 s53, 0, 0x10000
	s_cmp_eq_u32 s52, 28
	s_cselect_b32 s27, s17, s1
	s_cselect_b32 s26, s16, s0
	s_cselect_b32 s25, s15, s51
	s_cselect_b32 s24, s21, s50
	s_add_i32 s54, 0, 0x14000
	v_add_u32_e32 v156, s53, v145
	v_add_u32_e32 v172, s54, v145
	ds_read_b128 v[140:143], v156
	ds_read_b128 v[148:151], v156 offset:1024
	ds_read_b128 v[152:155], v156 offset:2048
	ds_read_b128 v[156:159], v156 offset:3072
	ds_read_b128 v[160:163], v172
	ds_read_b128 v[164:167], v172 offset:1024
	ds_read_b128 v[168:171], v172 offset:2048
	ds_read_b128 v[172:175], v172 offset:3072
	s_add_i32 m0, s31, 0xc000
	ds_read_b128 v[176:179], v147
	ds_read_b128 v[180:183], v147 offset:1024
	ds_read_b128 v[184:187], v147 offset:2048
	ds_read_b128 v[208:211], v147 offset:3072
	ds_read_b128 v[230:233], v147 offset:4096
	ds_read_b128 v[234:237], v147 offset:5120
	ds_read_b128 v[238:241], v147 offset:6144
	ds_read_b128 v[242:245], v147 offset:7168
	global_load_lds_dwordx4 v138, s[22:23]
	s_add_i32 m0, s31, 0xe000
	s_nop 0
	global_load_lds_dwordx4 v136, s[22:23]
	s_waitcnt vmcnt(8)
	s_waitcnt lgkmcnt(0)
	v_mfma_f32_16x16x32_bf16 v[126:129], v[140:143], v[176:179], v[126:129]
	v_mfma_f32_16x16x32_bf16 v[122:125], v[152:155], v[176:179], v[122:125]
	v_mfma_f32_16x16x32_bf16 v[108:111], v[140:143], v[184:187], v[108:111]
	v_mfma_f32_16x16x32_bf16 v[104:107], v[152:155], v[184:187], v[104:107]
	v_mfma_f32_16x16x32_bf16 v[92:95], v[140:143], v[230:233], v[92:95]
	v_mfma_f32_16x16x32_bf16 v[88:91], v[152:155], v[230:233], v[88:91]
	v_mfma_f32_16x16x32_bf16 v[76:79], v[140:143], v[238:241], v[76:79]
	v_mfma_f32_16x16x32_bf16 v[72:75], v[152:155], v[238:241], v[72:75]
	s_barrier
	s_setprio 1
	v_mfma_f32_16x16x32_bf16 v[126:129], v[148:151], v[180:183], v[126:129]
	v_mfma_f32_16x16x32_bf16 v[122:125], v[156:159], v[180:183], v[122:125]
	v_mfma_f32_16x16x32_bf16 v[108:111], v[148:151], v[208:211], v[108:111]
	v_mfma_f32_16x16x32_bf16 v[104:107], v[156:159], v[208:211], v[104:107]
	v_mfma_f32_16x16x32_bf16 v[92:95], v[148:151], v[234:237], v[92:95]
	v_mfma_f32_16x16x32_bf16 v[88:91], v[156:159], v[234:237], v[88:91]
	v_mfma_f32_16x16x32_bf16 v[76:79], v[148:151], v[242:245], v[76:79]
	v_mfma_f32_16x16x32_bf16 v[72:75], v[156:159], v[242:245], v[72:75]
	s_setprio 0
	s_setprio 1
	v_mfma_f32_16x16x32_bf16 v[118:121], v[160:163], v[176:179], v[118:121]
	v_mfma_f32_16x16x32_bf16 v[114:117], v[168:171], v[176:179], v[114:117]
	v_mfma_f32_16x16x32_bf16 v[100:103], v[160:163], v[184:187], v[100:103]
	v_mfma_f32_16x16x32_bf16 v[96:99], v[168:171], v[184:187], v[96:99]
	v_mfma_f32_16x16x32_bf16 v[84:87], v[160:163], v[230:233], v[84:87]
	v_mfma_f32_16x16x32_bf16 v[80:83], v[168:171], v[230:233], v[80:83]
	v_mfma_f32_16x16x32_bf16 v[68:71], v[160:163], v[238:241], v[68:71]
	v_mfma_f32_16x16x32_bf16 v[64:67], v[168:171], v[238:241], v[64:67]
	v_mfma_f32_16x16x32_bf16 v[118:121], v[164:167], v[180:183], v[118:121]
	v_mfma_f32_16x16x32_bf16 v[114:117], v[172:175], v[180:183], v[114:117]
	v_mfma_f32_16x16x32_bf16 v[100:103], v[164:167], v[208:211], v[100:103]
	v_mfma_f32_16x16x32_bf16 v[96:99], v[172:175], v[208:211], v[96:99]
	v_mfma_f32_16x16x32_bf16 v[84:87], v[164:167], v[234:237], v[84:87]
	v_mfma_f32_16x16x32_bf16 v[80:83], v[172:175], v[234:237], v[80:83]
	v_mfma_f32_16x16x32_bf16 v[68:71], v[164:167], v[242:245], v[68:71]
	v_mfma_f32_16x16x32_bf16 v[64:67], v[172:175], v[242:245], v[64:67]
	s_setprio 0
	s_barrier
	s_add_i32 s22, s53, s30
	s_mov_b32 m0, s22
	ds_read_b128 v[176:179], v147 offset:16384
	ds_read_b128 v[180:183], v147 offset:17408
	ds_read_b128 v[184:187], v147 offset:18432
	ds_read_b128 v[208:211], v147 offset:19456
	ds_read_b128 v[230:233], v147 offset:20480
	ds_read_b128 v[234:237], v147 offset:21504
	ds_read_b128 v[238:241], v147 offset:22528
	ds_read_b128 v[242:245], v147 offset:23552
	global_load_lds_dwordx4 v112, s[24:25]
	s_add_i32 m0, s22, 0x2000
	s_add_u32 s22, s24, 0x80000
	v_lshl_add_u64 v[212:213], s[24:25], 0, v[134:135]
	s_addc_u32 s23, s25, 0
	s_add_i32 s53, s54, s30
	global_load_lds_dwordx4 v134, s[24:25]
	s_mov_b32 m0, s53
	s_nop 0
	global_load_lds_dwordx4 v112, s[22:23]
	s_add_i32 m0, s53, 0x2000
	s_nop 0
	global_load_lds_dwordx4 v134, s[22:23]
	s_mov_b32 m0, s31
	s_nop 0
	global_load_lds_dwordx4 v130, s[26:27]
	s_mov_b32 m0, s35
	s_nop 0
	global_load_lds_dwordx4 v132, s[26:27]
	s_waitcnt vmcnt(8)
	s_waitcnt lgkmcnt(0)
	v_mfma_f32_16x16x32_bf16 v[60:63], v[140:143], v[176:179], v[60:63]
	v_mfma_f32_16x16x32_bf16 v[56:59], v[152:155], v[176:179], v[56:59]
	v_mfma_f32_16x16x32_bf16 v[44:47], v[140:143], v[184:187], v[44:47]
	v_mfma_f32_16x16x32_bf16 v[40:43], v[152:155], v[184:187], v[40:43]
	v_mfma_f32_16x16x32_bf16 v[28:31], v[140:143], v[230:233], v[28:31]
	v_mfma_f32_16x16x32_bf16 v[24:27], v[152:155], v[230:233], v[24:27]
	v_mfma_f32_16x16x32_bf16 v[12:15], v[140:143], v[238:241], v[12:15]
	v_mfma_f32_16x16x32_bf16 v[8:11], v[152:155], v[238:241], v[8:11]
	s_barrier
	s_setprio 1
	v_mfma_f32_16x16x32_bf16 v[60:63], v[148:151], v[180:183], v[60:63]
	v_mfma_f32_16x16x32_bf16 v[56:59], v[156:159], v[180:183], v[56:59]
	v_mfma_f32_16x16x32_bf16 v[44:47], v[148:151], v[208:211], v[44:47]
	v_mfma_f32_16x16x32_bf16 v[40:43], v[156:159], v[208:211], v[40:43]
	v_mfma_f32_16x16x32_bf16 v[28:31], v[148:151], v[234:237], v[28:31]
	v_mfma_f32_16x16x32_bf16 v[24:27], v[156:159], v[234:237], v[24:27]
	v_mfma_f32_16x16x32_bf16 v[12:15], v[148:151], v[242:245], v[12:15]
	v_mfma_f32_16x16x32_bf16 v[8:11], v[156:159], v[242:245], v[8:11]
	s_setprio 0
	s_setprio 1
	v_mfma_f32_16x16x32_bf16 v[52:55], v[160:163], v[176:179], v[52:55]
	v_mfma_f32_16x16x32_bf16 v[48:51], v[168:171], v[176:179], v[48:51]
	v_mfma_f32_16x16x32_bf16 v[36:39], v[160:163], v[184:187], v[36:39]
	v_mfma_f32_16x16x32_bf16 v[32:35], v[168:171], v[184:187], v[32:35]
	v_mfma_f32_16x16x32_bf16 v[20:23], v[160:163], v[230:233], v[20:23]
	v_mfma_f32_16x16x32_bf16 v[16:19], v[168:171], v[230:233], v[16:19]
	v_mfma_f32_16x16x32_bf16 v[4:7], v[160:163], v[238:241], v[4:7]
	v_mfma_f32_16x16x32_bf16 v[0:3], v[168:171], v[238:241], v[0:3]
	v_mfma_f32_16x16x32_bf16 v[52:55], v[164:167], v[180:183], v[52:55]
	v_mfma_f32_16x16x32_bf16 v[48:51], v[172:175], v[180:183], v[48:51]
	v_mfma_f32_16x16x32_bf16 v[36:39], v[164:167], v[208:211], v[36:39]
	v_mfma_f32_16x16x32_bf16 v[32:35], v[172:175], v[208:211], v[32:35]
	v_mfma_f32_16x16x32_bf16 v[20:23], v[164:167], v[234:237], v[20:23]
	v_mfma_f32_16x16x32_bf16 v[16:19], v[172:175], v[234:237], v[16:19]
	v_mfma_f32_16x16x32_bf16 v[4:7], v[164:167], v[242:245], v[4:7]
	v_mfma_f32_16x16x32_bf16 v[0:3], v[172:175], v[242:245], v[0:3]
	s_setprio 0
	s_barrier
	s_add_i32 s53, 0, 0x18000
	s_add_i32 s54, 0, 0x1c000
	v_add_u32_e32 v156, s53, v145
	v_add_u32_e32 v172, s54, v145
	ds_read_b128 v[140:143], v156
	ds_read_b128 v[148:151], v156 offset:1024
	ds_read_b128 v[152:155], v156 offset:2048
	ds_read_b128 v[156:159], v156 offset:3072
	ds_read_b128 v[160:163], v172
	ds_read_b128 v[164:167], v172 offset:1024
	ds_read_b128 v[168:171], v172 offset:2048
	ds_read_b128 v[172:175], v172 offset:3072
	s_add_u32 s22, s26, 0x120000
	s_addc_u32 s23, s27, 0
	s_mov_b32 m0, s40
	ds_read_b128 v[176:179], v147 offset:32768
	ds_read_b128 v[180:183], v147 offset:33792
	ds_read_b128 v[184:187], v147 offset:34816
	ds_read_b128 v[208:211], v147 offset:35840
	ds_read_b128 v[230:233], v147 offset:36864
	ds_read_b128 v[234:237], v147 offset:37888
	ds_read_b128 v[238:241], v147 offset:38912
	ds_read_b128 v[242:245], v147 offset:39936
	global_load_lds_dwordx4 v130, s[22:23]
	s_mov_b32 m0, s41
	s_nop 0
	global_load_lds_dwordx4 v132, s[22:23]
	s_waitcnt vmcnt(8)
	s_waitcnt lgkmcnt(0)
	v_mfma_f32_16x16x32_bf16 v[126:129], v[140:143], v[176:179], v[126:129]
	v_mfma_f32_16x16x32_bf16 v[122:125], v[152:155], v[176:179], v[122:125]
	v_mfma_f32_16x16x32_bf16 v[108:111], v[140:143], v[184:187], v[108:111]
	v_mfma_f32_16x16x32_bf16 v[104:107], v[152:155], v[184:187], v[104:107]
	v_mfma_f32_16x16x32_bf16 v[92:95], v[140:143], v[230:233], v[92:95]
	v_mfma_f32_16x16x32_bf16 v[88:91], v[152:155], v[230:233], v[88:91]
	v_mfma_f32_16x16x32_bf16 v[76:79], v[140:143], v[238:241], v[76:79]
	v_mfma_f32_16x16x32_bf16 v[72:75], v[152:155], v[238:241], v[72:75]
	s_barrier
	s_setprio 1
	v_mfma_f32_16x16x32_bf16 v[126:129], v[148:151], v[180:183], v[126:129]
	v_mfma_f32_16x16x32_bf16 v[122:125], v[156:159], v[180:183], v[122:125]
	v_mfma_f32_16x16x32_bf16 v[108:111], v[148:151], v[208:211], v[108:111]
	v_mfma_f32_16x16x32_bf16 v[104:107], v[156:159], v[208:211], v[104:107]
	v_mfma_f32_16x16x32_bf16 v[92:95], v[148:151], v[234:237], v[92:95]
	v_mfma_f32_16x16x32_bf16 v[88:91], v[156:159], v[234:237], v[88:91]
	v_mfma_f32_16x16x32_bf16 v[76:79], v[148:151], v[242:245], v[76:79]
	v_mfma_f32_16x16x32_bf16 v[72:75], v[156:159], v[242:245], v[72:75]
	s_setprio 0
	s_setprio 1
	v_mfma_f32_16x16x32_bf16 v[118:121], v[160:163], v[176:179], v[118:121]
	v_mfma_f32_16x16x32_bf16 v[114:117], v[168:171], v[176:179], v[114:117]
	v_mfma_f32_16x16x32_bf16 v[100:103], v[160:163], v[184:187], v[100:103]
	v_mfma_f32_16x16x32_bf16 v[96:99], v[168:171], v[184:187], v[96:99]
	v_mfma_f32_16x16x32_bf16 v[84:87], v[160:163], v[230:233], v[84:87]
	v_mfma_f32_16x16x32_bf16 v[80:83], v[168:171], v[230:233], v[80:83]
	v_mfma_f32_16x16x32_bf16 v[68:71], v[160:163], v[238:241], v[68:71]
	v_mfma_f32_16x16x32_bf16 v[64:67], v[168:171], v[238:241], v[64:67]
	v_mfma_f32_16x16x32_bf16 v[118:121], v[164:167], v[180:183], v[118:121]
	v_mfma_f32_16x16x32_bf16 v[114:117], v[172:175], v[180:183], v[114:117]
	v_mfma_f32_16x16x32_bf16 v[100:103], v[164:167], v[208:211], v[100:103]
	v_mfma_f32_16x16x32_bf16 v[96:99], v[172:175], v[208:211], v[96:99]
	v_mfma_f32_16x16x32_bf16 v[84:87], v[164:167], v[234:237], v[84:87]
	v_mfma_f32_16x16x32_bf16 v[80:83], v[172:175], v[234:237], v[80:83]
	v_mfma_f32_16x16x32_bf16 v[68:71], v[164:167], v[242:245], v[68:71]
	v_mfma_f32_16x16x32_bf16 v[64:67], v[172:175], v[242:245], v[64:67]
	s_setprio 0
	s_barrier
	s_add_i32 s22, s53, s30
	s_mov_b32 m0, s22
	ds_read_b128 v[176:179], v147 offset:49152
	ds_read_b128 v[180:183], v147 offset:50176
	ds_read_b128 v[184:187], v147 offset:51200
	ds_read_b128 v[208:211], v147 offset:52224
	ds_read_b128 v[230:233], v147 offset:53248
	ds_read_b128 v[234:237], v147 offset:54272
	ds_read_b128 v[238:241], v147 offset:55296
	ds_read_b128 v[242:245], v147 offset:56320
	s_add_u32 s98, s24, 0x80
	s_addc_u32 s99, s25, 0
	global_load_lds_dwordx4 v112, s[98:99]
	s_add_i32 m0, s22, 0x2000
	s_add_u32 s22, s24, 0x80080
	v_lshl_add_u64 v[188:189], v[212:213], 0, s[96:97]
	s_addc_u32 s23, s25, 0
	s_add_i32 s24, s54, s30
	global_load_lds_dwordx4 v[188:189], off
	s_mov_b32 m0, s24
	s_nop 0
	global_load_lds_dwordx4 v112, s[22:23]
	s_add_i32 m0, s24, 0x2000
	s_nop 0
	global_load_lds_dwordx4 v134, s[22:23]
	s_mov_b32 m0, s43
	s_nop 0
	s_add_u32 s98, s26, 0x80
	s_addc_u32 s99, s27, 0
	global_load_lds_dwordx4 v130, s[98:99]
	s_mov_b32 m0, s44
	s_nop 0
	s_add_u32 s98, s26, 0x80
	s_addc_u32 s99, s27, 0
	global_load_lds_dwordx4 v132, s[98:99]
	s_waitcnt vmcnt(8)
	s_waitcnt lgkmcnt(0)
	v_mfma_f32_16x16x32_bf16 v[60:63], v[140:143], v[176:179], v[60:63]
	v_mfma_f32_16x16x32_bf16 v[56:59], v[152:155], v[176:179], v[56:59]
	v_mfma_f32_16x16x32_bf16 v[44:47], v[140:143], v[184:187], v[44:47]
	v_mfma_f32_16x16x32_bf16 v[40:43], v[152:155], v[184:187], v[40:43]
	v_mfma_f32_16x16x32_bf16 v[28:31], v[140:143], v[230:233], v[28:31]
	v_mfma_f32_16x16x32_bf16 v[24:27], v[152:155], v[230:233], v[24:27]
	v_mfma_f32_16x16x32_bf16 v[12:15], v[140:143], v[238:241], v[12:15]
	v_mfma_f32_16x16x32_bf16 v[8:11], v[152:155], v[238:241], v[8:11]
	s_barrier
	s_setprio 1
	v_mfma_f32_16x16x32_bf16 v[60:63], v[148:151], v[180:183], v[60:63]
	v_mfma_f32_16x16x32_bf16 v[56:59], v[156:159], v[180:183], v[56:59]
	v_mfma_f32_16x16x32_bf16 v[44:47], v[148:151], v[208:211], v[44:47]
	v_mfma_f32_16x16x32_bf16 v[40:43], v[156:159], v[208:211], v[40:43]
	v_mfma_f32_16x16x32_bf16 v[28:31], v[148:151], v[234:237], v[28:31]
	v_mfma_f32_16x16x32_bf16 v[24:27], v[156:159], v[234:237], v[24:27]
	v_mfma_f32_16x16x32_bf16 v[12:15], v[148:151], v[242:245], v[12:15]
	v_mfma_f32_16x16x32_bf16 v[8:11], v[156:159], v[242:245], v[8:11]
	s_setprio 0
	s_setprio 1
	v_mfma_f32_16x16x32_bf16 v[52:55], v[160:163], v[176:179], v[52:55]
	v_mfma_f32_16x16x32_bf16 v[48:51], v[168:171], v[176:179], v[48:51]
	v_mfma_f32_16x16x32_bf16 v[36:39], v[160:163], v[184:187], v[36:39]
	v_mfma_f32_16x16x32_bf16 v[32:35], v[168:171], v[184:187], v[32:35]
	v_mfma_f32_16x16x32_bf16 v[20:23], v[160:163], v[230:233], v[20:23]
	v_mfma_f32_16x16x32_bf16 v[16:19], v[168:171], v[230:233], v[16:19]
	v_mfma_f32_16x16x32_bf16 v[4:7], v[160:163], v[238:241], v[4:7]
	v_mfma_f32_16x16x32_bf16 v[0:3], v[168:171], v[238:241], v[0:3]
	v_mfma_f32_16x16x32_bf16 v[52:55], v[164:167], v[180:183], v[52:55]
	v_mfma_f32_16x16x32_bf16 v[48:51], v[172:175], v[180:183], v[48:51]
	v_mfma_f32_16x16x32_bf16 v[36:39], v[164:167], v[208:211], v[36:39]
	v_mfma_f32_16x16x32_bf16 v[32:35], v[172:175], v[208:211], v[32:35]
	v_mfma_f32_16x16x32_bf16 v[20:23], v[164:167], v[234:237], v[20:23]
	v_mfma_f32_16x16x32_bf16 v[16:19], v[172:175], v[234:237], v[16:19]
	v_mfma_f32_16x16x32_bf16 v[4:7], v[164:167], v[242:245], v[4:7]
	v_mfma_f32_16x16x32_bf16 v[0:3], v[172:175], v[242:245], v[0:3]
	s_setprio 0
	s_barrier
	s_add_i32 s52, s52, 2
	s_add_u32 s50, s50, 0x100
	s_addc_u32 s51, s51, 0
	s_cmp_gt_u32 s52, 29
	s_mov_b64 s[22:23], s[0:1]
	s_cbranch_scc0 .LBB0_804

.LBB0_1136:
	s_add_u32 s48, s18, 0x100
	s_addc_u32 s49, s19, 0
	s_mov_b32 s50, -2
	s_waitcnt lgkmcnt(0)
	s_add_u32 s18, s16, 0x100
	s_addc_u32 s19, s17, 0
	s_add_i32 s51, 0, 0x10000
	s_cmp_eq_u32 s50, 40
	s_cselect_b32 s23, s1, s19
	s_cselect_b32 s22, s0, s18
	s_cselect_b32 s21, s15, s49
	s_cselect_b32 s20, s14, s48
	s_add_i32 s52, 0, 0x14000
	v_add_u32_e32 v156, s51, v145
	v_add_u32_e32 v172, s52, v145
	ds_read_b128 v[140:143], v156
	ds_read_b128 v[148:151], v156 offset:1024
	ds_read_b128 v[152:155], v156 offset:2048
	ds_read_b128 v[156:159], v156 offset:3072
	ds_read_b128 v[160:163], v172
	ds_read_b128 v[164:167], v172 offset:1024
	ds_read_b128 v[168:171], v172 offset:2048
	ds_read_b128 v[172:175], v172 offset:3072
	s_add_i32 m0, s31, 0xc000
	ds_read_b128 v[176:179], v147
	ds_read_b128 v[180:183], v147 offset:1024
	ds_read_b128 v[184:187], v147 offset:2048
	ds_read_b128 v[208:211], v147 offset:3072
	ds_read_b128 v[230:233], v147 offset:4096
	ds_read_b128 v[234:237], v147 offset:5120
	ds_read_b128 v[238:241], v147 offset:6144
	ds_read_b128 v[242:245], v147 offset:7168
	global_load_lds_dwordx4 v138, s[16:17]
	s_add_i32 m0, s31, 0xe000
	s_nop 0
	global_load_lds_dwordx4 v136, s[16:17]
	s_waitcnt vmcnt(8)
	s_waitcnt lgkmcnt(0)
	v_mfma_f32_16x16x32_bf16 v[126:129], v[140:143], v[176:179], 0
	v_mfma_f32_16x16x32_bf16 v[122:125], v[152:155], v[176:179], 0
	v_mfma_f32_16x16x32_bf16 v[108:111], v[140:143], v[184:187], 0
	v_mfma_f32_16x16x32_bf16 v[104:107], v[152:155], v[184:187], 0
	v_mfma_f32_16x16x32_bf16 v[92:95], v[140:143], v[230:233], 0
	v_mfma_f32_16x16x32_bf16 v[88:91], v[152:155], v[230:233], 0
	v_mfma_f32_16x16x32_bf16 v[76:79], v[140:143], v[238:241], 0
	v_mfma_f32_16x16x32_bf16 v[72:75], v[152:155], v[238:241], 0
	s_barrier
	s_setprio 1
	v_mfma_f32_16x16x32_bf16 v[126:129], v[148:151], v[180:183], v[126:129]
	v_mfma_f32_16x16x32_bf16 v[122:125], v[156:159], v[180:183], v[122:125]
	v_mfma_f32_16x16x32_bf16 v[108:111], v[148:151], v[208:211], v[108:111]
	v_mfma_f32_16x16x32_bf16 v[104:107], v[156:159], v[208:211], v[104:107]
	v_mfma_f32_16x16x32_bf16 v[92:95], v[148:151], v[234:237], v[92:95]
	v_mfma_f32_16x16x32_bf16 v[88:91], v[156:159], v[234:237], v[88:91]
	v_mfma_f32_16x16x32_bf16 v[76:79], v[148:151], v[242:245], v[76:79]
	v_mfma_f32_16x16x32_bf16 v[72:75], v[156:159], v[242:245], v[72:75]
	s_setprio 0
	s_setprio 1
	v_mfma_f32_16x16x32_bf16 v[118:121], v[160:163], v[176:179], 0
	v_mfma_f32_16x16x32_bf16 v[114:117], v[168:171], v[176:179], 0
	v_mfma_f32_16x16x32_bf16 v[100:103], v[160:163], v[184:187], 0
	v_mfma_f32_16x16x32_bf16 v[96:99], v[168:171], v[184:187], 0
	v_mfma_f32_16x16x32_bf16 v[84:87], v[160:163], v[230:233], 0
	v_mfma_f32_16x16x32_bf16 v[80:83], v[168:171], v[230:233], 0
	v_mfma_f32_16x16x32_bf16 v[68:71], v[160:163], v[238:241], 0
	v_mfma_f32_16x16x32_bf16 v[64:67], v[168:171], v[238:241], 0
	v_mfma_f32_16x16x32_bf16 v[118:121], v[164:167], v[180:183], v[118:121]
	v_mfma_f32_16x16x32_bf16 v[114:117], v[172:175], v[180:183], v[114:117]
	v_mfma_f32_16x16x32_bf16 v[100:103], v[164:167], v[208:211], v[100:103]
	v_mfma_f32_16x16x32_bf16 v[96:99], v[172:175], v[208:211], v[96:99]
	v_mfma_f32_16x16x32_bf16 v[84:87], v[164:167], v[234:237], v[84:87]
	v_mfma_f32_16x16x32_bf16 v[80:83], v[172:175], v[234:237], v[80:83]
	v_mfma_f32_16x16x32_bf16 v[68:71], v[164:167], v[242:245], v[68:71]
	v_mfma_f32_16x16x32_bf16 v[64:67], v[172:175], v[242:245], v[64:67]
	s_setprio 0
	s_barrier
	s_add_i32 s16, s51, s30
	s_mov_b32 m0, s16
	ds_read_b128 v[176:179], v147 offset:16384
	ds_read_b128 v[180:183], v147 offset:17408
	ds_read_b128 v[184:187], v147 offset:18432
	ds_read_b128 v[208:211], v147 offset:19456
	ds_read_b128 v[230:233], v147 offset:20480
	ds_read_b128 v[234:237], v147 offset:21504
	ds_read_b128 v[238:241], v147 offset:22528
	ds_read_b128 v[242:245], v147 offset:23552
	global_load_lds_dwordx4 v112, s[20:21]
	s_add_i32 m0, s16, 0x2000
	s_add_u32 s16, s20, 0xb0000
	v_lshl_add_u64 v[212:213], s[20:21], 0, v[134:135]
	s_addc_u32 s17, s21, 0
	s_add_i32 s51, s52, s30
	global_load_lds_dwordx4 v134, s[20:21]
	s_mov_b32 m0, s51
	s_nop 0
	global_load_lds_dwordx4 v112, s[16:17]
	s_add_i32 m0, s51, 0x2000
	s_nop 0
	global_load_lds_dwordx4 v134, s[16:17]
	s_mov_b32 m0, s31
	s_nop 0
	global_load_lds_dwordx4 v130, s[22:23]
	s_mov_b32 m0, s35
	s_nop 0
	global_load_lds_dwordx4 v132, s[22:23]
	s_waitcnt vmcnt(8)
	s_waitcnt lgkmcnt(0)
	v_mfma_f32_16x16x32_bf16 v[60:63], v[140:143], v[176:179], 0
	v_mfma_f32_16x16x32_bf16 v[56:59], v[152:155], v[176:179], 0
	v_mfma_f32_16x16x32_bf16 v[44:47], v[140:143], v[184:187], 0
	v_mfma_f32_16x16x32_bf16 v[40:43], v[152:155], v[184:187], 0
	v_mfma_f32_16x16x32_bf16 v[28:31], v[140:143], v[230:233], 0
	v_mfma_f32_16x16x32_bf16 v[24:27], v[152:155], v[230:233], 0
	v_mfma_f32_16x16x32_bf16 v[12:15], v[140:143], v[238:241], 0
	v_mfma_f32_16x16x32_bf16 v[8:11], v[152:155], v[238:241], 0
	s_barrier
	s_setprio 1
	v_mfma_f32_16x16x32_bf16 v[60:63], v[148:151], v[180:183], v[60:63]
	v_mfma_f32_16x16x32_bf16 v[56:59], v[156:159], v[180:183], v[56:59]
	v_mfma_f32_16x16x32_bf16 v[44:47], v[148:151], v[208:211], v[44:47]
	v_mfma_f32_16x16x32_bf16 v[40:43], v[156:159], v[208:211], v[40:43]
	v_mfma_f32_16x16x32_bf16 v[28:31], v[148:151], v[234:237], v[28:31]
	v_mfma_f32_16x16x32_bf16 v[24:27], v[156:159], v[234:237], v[24:27]
	v_mfma_f32_16x16x32_bf16 v[12:15], v[148:151], v[242:245], v[12:15]
	v_mfma_f32_16x16x32_bf16 v[8:11], v[156:159], v[242:245], v[8:11]
	s_setprio 0
	s_setprio 1
	v_mfma_f32_16x16x32_bf16 v[52:55], v[160:163], v[176:179], 0
	v_mfma_f32_16x16x32_bf16 v[48:51], v[168:171], v[176:179], 0
	v_mfma_f32_16x16x32_bf16 v[36:39], v[160:163], v[184:187], 0
	v_mfma_f32_16x16x32_bf16 v[32:35], v[168:171], v[184:187], 0
	v_mfma_f32_16x16x32_bf16 v[20:23], v[160:163], v[230:233], 0
	v_mfma_f32_16x16x32_bf16 v[16:19], v[168:171], v[230:233], 0
	v_mfma_f32_16x16x32_bf16 v[4:7], v[160:163], v[238:241], 0
	v_mfma_f32_16x16x32_bf16 v[0:3], v[168:171], v[238:241], 0
	v_mfma_f32_16x16x32_bf16 v[52:55], v[164:167], v[180:183], v[52:55]
	v_mfma_f32_16x16x32_bf16 v[48:51], v[172:175], v[180:183], v[48:51]
	v_mfma_f32_16x16x32_bf16 v[36:39], v[164:167], v[208:211], v[36:39]
	v_mfma_f32_16x16x32_bf16 v[32:35], v[172:175], v[208:211], v[32:35]
	v_mfma_f32_16x16x32_bf16 v[20:23], v[164:167], v[234:237], v[20:23]
	v_mfma_f32_16x16x32_bf16 v[16:19], v[172:175], v[234:237], v[16:19]
	v_mfma_f32_16x16x32_bf16 v[4:7], v[164:167], v[242:245], v[4:7]
	v_mfma_f32_16x16x32_bf16 v[0:3], v[172:175], v[242:245], v[0:3]
	s_setprio 0
	s_barrier
	s_add_i32 s51, 0, 0x18000
	s_add_i32 s52, 0, 0x1c000
	v_add_u32_e32 v156, s51, v145
	v_add_u32_e32 v172, s52, v145
	ds_read_b128 v[140:143], v156
	ds_read_b128 v[148:151], v156 offset:1024
	ds_read_b128 v[152:155], v156 offset:2048
	ds_read_b128 v[156:159], v156 offset:3072
	ds_read_b128 v[160:163], v172
	ds_read_b128 v[164:167], v172 offset:1024
	ds_read_b128 v[168:171], v172 offset:2048
	ds_read_b128 v[172:175], v172 offset:3072
	s_add_u32 s16, s22, 0xb0000
	s_addc_u32 s17, s23, 0
	s_mov_b32 m0, s36
	ds_read_b128 v[176:179], v147 offset:32768
	ds_read_b128 v[180:183], v147 offset:33792
	ds_read_b128 v[184:187], v147 offset:34816
	ds_read_b128 v[208:211], v147 offset:35840
	ds_read_b128 v[230:233], v147 offset:36864
	ds_read_b128 v[234:237], v147 offset:37888
	ds_read_b128 v[238:241], v147 offset:38912
	ds_read_b128 v[242:245], v147 offset:39936
	global_load_lds_dwordx4 v130, s[16:17]
	s_mov_b32 m0, s37
	s_nop 0
	global_load_lds_dwordx4 v132, s[16:17]
	s_waitcnt vmcnt(8)
	s_waitcnt lgkmcnt(0)
	v_mfma_f32_16x16x32_bf16 v[126:129], v[140:143], v[176:179], v[126:129]
	v_mfma_f32_16x16x32_bf16 v[122:125], v[152:155], v[176:179], v[122:125]
	v_mfma_f32_16x16x32_bf16 v[108:111], v[140:143], v[184:187], v[108:111]
	v_mfma_f32_16x16x32_bf16 v[104:107], v[152:155], v[184:187], v[104:107]
	v_mfma_f32_16x16x32_bf16 v[92:95], v[140:143], v[230:233], v[92:95]
	v_mfma_f32_16x16x32_bf16 v[88:91], v[152:155], v[230:233], v[88:91]
	v_mfma_f32_16x16x32_bf16 v[76:79], v[140:143], v[238:241], v[76:79]
	v_mfma_f32_16x16x32_bf16 v[72:75], v[152:155], v[238:241], v[72:75]
	s_barrier
	s_setprio 1
	v_mfma_f32_16x16x32_bf16 v[126:129], v[148:151], v[180:183], v[126:129]
	v_mfma_f32_16x16x32_bf16 v[122:125], v[156:159], v[180:183], v[122:125]
	v_mfma_f32_16x16x32_bf16 v[108:111], v[148:151], v[208:211], v[108:111]
	v_mfma_f32_16x16x32_bf16 v[104:107], v[156:159], v[208:211], v[104:107]
	v_mfma_f32_16x16x32_bf16 v[92:95], v[148:151], v[234:237], v[92:95]
	v_mfma_f32_16x16x32_bf16 v[88:91], v[156:159], v[234:237], v[88:91]
	v_mfma_f32_16x16x32_bf16 v[76:79], v[148:151], v[242:245], v[76:79]
	v_mfma_f32_16x16x32_bf16 v[72:75], v[156:159], v[242:245], v[72:75]
	s_setprio 0
	s_setprio 1
	v_mfma_f32_16x16x32_bf16 v[118:121], v[160:163], v[176:179], v[118:121]
	v_mfma_f32_16x16x32_bf16 v[114:117], v[168:171], v[176:179], v[114:117]
	v_mfma_f32_16x16x32_bf16 v[100:103], v[160:163], v[184:187], v[100:103]
	v_mfma_f32_16x16x32_bf16 v[96:99], v[168:171], v[184:187], v[96:99]
	v_mfma_f32_16x16x32_bf16 v[84:87], v[160:163], v[230:233], v[84:87]
	v_mfma_f32_16x16x32_bf16 v[80:83], v[168:171], v[230:233], v[80:83]
	v_mfma_f32_16x16x32_bf16 v[68:71], v[160:163], v[238:241], v[68:71]
	v_mfma_f32_16x16x32_bf16 v[64:67], v[168:171], v[238:241], v[64:67]
	v_mfma_f32_16x16x32_bf16 v[118:121], v[164:167], v[180:183], v[118:121]
	v_mfma_f32_16x16x32_bf16 v[114:117], v[172:175], v[180:183], v[114:117]
	v_mfma_f32_16x16x32_bf16 v[100:103], v[164:167], v[208:211], v[100:103]
	v_mfma_f32_16x16x32_bf16 v[96:99], v[172:175], v[208:211], v[96:99]
	v_mfma_f32_16x16x32_bf16 v[84:87], v[164:167], v[234:237], v[84:87]
	v_mfma_f32_16x16x32_bf16 v[80:83], v[172:175], v[234:237], v[80:83]
	v_mfma_f32_16x16x32_bf16 v[68:71], v[164:167], v[242:245], v[68:71]
	v_mfma_f32_16x16x32_bf16 v[64:67], v[172:175], v[242:245], v[64:67]
	s_setprio 0
	s_barrier
	s_add_i32 s16, s51, s30
	s_mov_b32 m0, s16
	ds_read_b128 v[176:179], v147 offset:49152
	ds_read_b128 v[180:183], v147 offset:50176
	ds_read_b128 v[184:187], v147 offset:51200
	ds_read_b128 v[208:211], v147 offset:52224
	ds_read_b128 v[230:233], v147 offset:53248
	ds_read_b128 v[234:237], v147 offset:54272
	ds_read_b128 v[238:241], v147 offset:55296
	ds_read_b128 v[242:245], v147 offset:56320
	s_add_u32 s98, s20, 0x80
	s_addc_u32 s99, s21, 0
	global_load_lds_dwordx4 v112, s[98:99]
	s_add_i32 m0, s16, 0x2000
	s_add_u32 s16, s20, 0xb0080
	v_lshl_add_u64 v[188:189], v[212:213], 0, s[96:97]
	s_addc_u32 s17, s21, 0
	s_add_i32 s20, s52, s30
	global_load_lds_dwordx4 v[188:189], off
	s_mov_b32 m0, s20
	s_nop 0
	global_load_lds_dwordx4 v112, s[16:17]
	s_add_i32 m0, s20, 0x2000
	s_nop 0
	global_load_lds_dwordx4 v134, s[16:17]
	s_mov_b32 m0, s39
	s_nop 0
	s_add_u32 s98, s22, 0x80
	s_addc_u32 s99, s23, 0
	global_load_lds_dwordx4 v130, s[98:99]
	s_mov_b32 m0, s40
	s_nop 0
	s_add_u32 s98, s22, 0x80
	s_addc_u32 s99, s23, 0
	global_load_lds_dwordx4 v132, s[98:99]
	s_waitcnt vmcnt(8)
	s_waitcnt lgkmcnt(0)
	v_mfma_f32_16x16x32_bf16 v[60:63], v[140:143], v[176:179], v[60:63]
	v_mfma_f32_16x16x32_bf16 v[56:59], v[152:155], v[176:179], v[56:59]
	v_mfma_f32_16x16x32_bf16 v[44:47], v[140:143], v[184:187], v[44:47]
	v_mfma_f32_16x16x32_bf16 v[40:43], v[152:155], v[184:187], v[40:43]
	v_mfma_f32_16x16x32_bf16 v[28:31], v[140:143], v[230:233], v[28:31]
	v_mfma_f32_16x16x32_bf16 v[24:27], v[152:155], v[230:233], v[24:27]
	v_mfma_f32_16x16x32_bf16 v[12:15], v[140:143], v[238:241], v[12:15]
	v_mfma_f32_16x16x32_bf16 v[8:11], v[152:155], v[238:241], v[8:11]
	s_barrier
	s_setprio 1
	v_mfma_f32_16x16x32_bf16 v[60:63], v[148:151], v[180:183], v[60:63]
	v_mfma_f32_16x16x32_bf16 v[56:59], v[156:159], v[180:183], v[56:59]
	v_mfma_f32_16x16x32_bf16 v[44:47], v[148:151], v[208:211], v[44:47]
	v_mfma_f32_16x16x32_bf16 v[40:43], v[156:159], v[208:211], v[40:43]
	v_mfma_f32_16x16x32_bf16 v[28:31], v[148:151], v[234:237], v[28:31]
	v_mfma_f32_16x16x32_bf16 v[24:27], v[156:159], v[234:237], v[24:27]
	v_mfma_f32_16x16x32_bf16 v[12:15], v[148:151], v[242:245], v[12:15]
	v_mfma_f32_16x16x32_bf16 v[8:11], v[156:159], v[242:245], v[8:11]
	s_setprio 0
	s_setprio 1
	v_mfma_f32_16x16x32_bf16 v[52:55], v[160:163], v[176:179], v[52:55]
	v_mfma_f32_16x16x32_bf16 v[48:51], v[168:171], v[176:179], v[48:51]
	v_mfma_f32_16x16x32_bf16 v[36:39], v[160:163], v[184:187], v[36:39]
	v_mfma_f32_16x16x32_bf16 v[32:35], v[168:171], v[184:187], v[32:35]
	v_mfma_f32_16x16x32_bf16 v[20:23], v[160:163], v[230:233], v[20:23]
	v_mfma_f32_16x16x32_bf16 v[16:19], v[168:171], v[230:233], v[16:19]
	v_mfma_f32_16x16x32_bf16 v[4:7], v[160:163], v[238:241], v[4:7]
	v_mfma_f32_16x16x32_bf16 v[0:3], v[168:171], v[238:241], v[0:3]
	v_mfma_f32_16x16x32_bf16 v[52:55], v[164:167], v[180:183], v[52:55]
	v_mfma_f32_16x16x32_bf16 v[48:51], v[172:175], v[180:183], v[48:51]
	v_mfma_f32_16x16x32_bf16 v[36:39], v[164:167], v[208:211], v[36:39]
	v_mfma_f32_16x16x32_bf16 v[32:35], v[172:175], v[208:211], v[32:35]
	v_mfma_f32_16x16x32_bf16 v[20:23], v[164:167], v[234:237], v[20:23]
	v_mfma_f32_16x16x32_bf16 v[16:19], v[172:175], v[234:237], v[16:19]
	v_mfma_f32_16x16x32_bf16 v[4:7], v[164:167], v[242:245], v[4:7]
	v_mfma_f32_16x16x32_bf16 v[0:3], v[172:175], v[242:245], v[0:3]
	s_setprio 0
	s_barrier
	s_add_i32 s50, s50, 2
	s_add_u32 s48, s48, 0x100
	s_addc_u32 s49, s49, 0
	s_cmp_gt_u32 s50, 41
	s_mov_b64 s[16:17], s[18:19]
	s_cbranch_scc0 .LBB0_1137
	s_branch .Lpeel_exit_1137
.LBB0_1137:
	s_add_u32 s18, s16, 0x100
	s_addc_u32 s19, s17, 0
	s_add_i32 s51, 0, 0x10000
	s_cmp_eq_u32 s50, 40
	s_cselect_b32 s23, s1, s19
	s_cselect_b32 s22, s0, s18
	s_cselect_b32 s21, s15, s49
	s_cselect_b32 s20, s14, s48
	s_add_i32 s52, 0, 0x14000
	v_add_u32_e32 v156, s51, v145
	v_add_u32_e32 v172, s52, v145
	ds_read_b128 v[140:143], v156
	ds_read_b128 v[148:151], v156 offset:1024
	ds_read_b128 v[152:155], v156 offset:2048
	ds_read_b128 v[156:159], v156 offset:3072
	ds_read_b128 v[160:163], v172
	ds_read_b128 v[164:167], v172 offset:1024
	ds_read_b128 v[168:171], v172 offset:2048
	ds_read_b128 v[172:175], v172 offset:3072
	s_add_i32 m0, s31, 0xc000
	ds_read_b128 v[176:179], v147
	ds_read_b128 v[180:183], v147 offset:1024
	ds_read_b128 v[184:187], v147 offset:2048
	ds_read_b128 v[208:211], v147 offset:3072
	ds_read_b128 v[230:233], v147 offset:4096
	ds_read_b128 v[234:237], v147 offset:5120
	ds_read_b128 v[238:241], v147 offset:6144
	ds_read_b128 v[242:245], v147 offset:7168
	global_load_lds_dwordx4 v138, s[16:17]
	s_add_i32 m0, s31, 0xe000
	s_nop 0
	global_load_lds_dwordx4 v136, s[16:17]
	s_waitcnt vmcnt(8)
	s_waitcnt lgkmcnt(0)
	v_mfma_f32_16x16x32_bf16 v[126:129], v[140:143], v[176:179], v[126:129]
	v_mfma_f32_16x16x32_bf16 v[122:125], v[152:155], v[176:179], v[122:125]
	v_mfma_f32_16x16x32_bf16 v[108:111], v[140:143], v[184:187], v[108:111]
	v_mfma_f32_16x16x32_bf16 v[104:107], v[152:155], v[184:187], v[104:107]
	v_mfma_f32_16x16x32_bf16 v[92:95], v[140:143], v[230:233], v[92:95]
	v_mfma_f32_16x16x32_bf16 v[88:91], v[152:155], v[230:233], v[88:91]
	v_mfma_f32_16x16x32_bf16 v[76:79], v[140:143], v[238:241], v[76:79]
	v_mfma_f32_16x16x32_bf16 v[72:75], v[152:155], v[238:241], v[72:75]
	s_barrier
	s_setprio 1
	v_mfma_f32_16x16x32_bf16 v[126:129], v[148:151], v[180:183], v[126:129]
	v_mfma_f32_16x16x32_bf16 v[122:125], v[156:159], v[180:183], v[122:125]
	v_mfma_f32_16x16x32_bf16 v[108:111], v[148:151], v[208:211], v[108:111]
	v_mfma_f32_16x16x32_bf16 v[104:107], v[156:159], v[208:211], v[104:107]
	v_mfma_f32_16x16x32_bf16 v[92:95], v[148:151], v[234:237], v[92:95]
	v_mfma_f32_16x16x32_bf16 v[88:91], v[156:159], v[234:237], v[88:91]
	v_mfma_f32_16x16x32_bf16 v[76:79], v[148:151], v[242:245], v[76:79]
	v_mfma_f32_16x16x32_bf16 v[72:75], v[156:159], v[242:245], v[72:75]
	s_setprio 0
	s_setprio 1
	v_mfma_f32_16x16x32_bf16 v[118:121], v[160:163], v[176:179], v[118:121]
	v_mfma_f32_16x16x32_bf16 v[114:117], v[168:171], v[176:179], v[114:117]
	v_mfma_f32_16x16x32_bf16 v[100:103], v[160:163], v[184:187], v[100:103]
	v_mfma_f32_16x16x32_bf16 v[96:99], v[168:171], v[184:187], v[96:99]
	v_mfma_f32_16x16x32_bf16 v[84:87], v[160:163], v[230:233], v[84:87]
	v_mfma_f32_16x16x32_bf16 v[80:83], v[168:171], v[230:233], v[80:83]
	v_mfma_f32_16x16x32_bf16 v[68:71], v[160:163], v[238:241], v[68:71]
	v_mfma_f32_16x16x32_bf16 v[64:67], v[168:171], v[238:241], v[64:67]
	v_mfma_f32_16x16x32_bf16 v[118:121], v[164:167], v[180:183], v[118:121]
	v_mfma_f32_16x16x32_bf16 v[114:117], v[172:175], v[180:183], v[114:117]
	v_mfma_f32_16x16x32_bf16 v[100:103], v[164:167], v[208:211], v[100:103]
	v_mfma_f32_16x16x32_bf16 v[96:99], v[172:175], v[208:211], v[96:99]
	v_mfma_f32_16x16x32_bf16 v[84:87], v[164:167], v[234:237], v[84:87]
	v_mfma_f32_16x16x32_bf16 v[80:83], v[172:175], v[234:237], v[80:83]
	v_mfma_f32_16x16x32_bf16 v[68:71], v[164:167], v[242:245], v[68:71]
	v_mfma_f32_16x16x32_bf16 v[64:67], v[172:175], v[242:245], v[64:67]
	s_setprio 0
	s_barrier
	s_add_i32 s16, s51, s30
	s_mov_b32 m0, s16
	ds_read_b128 v[176:179], v147 offset:16384
	ds_read_b128 v[180:183], v147 offset:17408
	ds_read_b128 v[184:187], v147 offset:18432
	ds_read_b128 v[208:211], v147 offset:19456
	ds_read_b128 v[230:233], v147 offset:20480
	ds_read_b128 v[234:237], v147 offset:21504
	ds_read_b128 v[238:241], v147 offset:22528
	ds_read_b128 v[242:245], v147 offset:23552
	global_load_lds_dwordx4 v112, s[20:21]
	s_add_i32 m0, s16, 0x2000
	s_add_u32 s16, s20, 0xb0000
	v_lshl_add_u64 v[212:213], s[20:21], 0, v[134:135]
	s_addc_u32 s17, s21, 0
	s_add_i32 s51, s52, s30
	global_load_lds_dwordx4 v134, s[20:21]
	s_mov_b32 m0, s51
	s_nop 0
	global_load_lds_dwordx4 v112, s[16:17]
	s_add_i32 m0, s51, 0x2000
	s_nop 0
	global_load_lds_dwordx4 v134, s[16:17]
	s_mov_b32 m0, s31
	s_nop 0
	global_load_lds_dwordx4 v130, s[22:23]
	s_mov_b32 m0, s35
	s_nop 0
	global_load_lds_dwordx4 v132, s[22:23]
	s_waitcnt vmcnt(8)
	s_waitcnt lgkmcnt(0)
	v_mfma_f32_16x16x32_bf16 v[60:63], v[140:143], v[176:179], v[60:63]
	v_mfma_f32_16x16x32_bf16 v[56:59], v[152:155], v[176:179], v[56:59]
	v_mfma_f32_16x16x32_bf16 v[44:47], v[140:143], v[184:187], v[44:47]
	v_mfma_f32_16x16x32_bf16 v[40:43], v[152:155], v[184:187], v[40:43]
	v_mfma_f32_16x16x32_bf16 v[28:31], v[140:143], v[230:233], v[28:31]
	v_mfma_f32_16x16x32_bf16 v[24:27], v[152:155], v[230:233], v[24:27]
	v_mfma_f32_16x16x32_bf16 v[12:15], v[140:143], v[238:241], v[12:15]
	v_mfma_f32_16x16x32_bf16 v[8:11], v[152:155], v[238:241], v[8:11]
	s_barrier
	s_setprio 1
	v_mfma_f32_16x16x32_bf16 v[60:63], v[148:151], v[180:183], v[60:63]
	v_mfma_f32_16x16x32_bf16 v[56:59], v[156:159], v[180:183], v[56:59]
	v_mfma_f32_16x16x32_bf16 v[44:47], v[148:151], v[208:211], v[44:47]
	v_mfma_f32_16x16x32_bf16 v[40:43], v[156:159], v[208:211], v[40:43]
	v_mfma_f32_16x16x32_bf16 v[28:31], v[148:151], v[234:237], v[28:31]
	v_mfma_f32_16x16x32_bf16 v[24:27], v[156:159], v[234:237], v[24:27]
	v_mfma_f32_16x16x32_bf16 v[12:15], v[148:151], v[242:245], v[12:15]
	v_mfma_f32_16x16x32_bf16 v[8:11], v[156:159], v[242:245], v[8:11]
	s_setprio 0
	s_setprio 1
	v_mfma_f32_16x16x32_bf16 v[52:55], v[160:163], v[176:179], v[52:55]
	v_mfma_f32_16x16x32_bf16 v[48:51], v[168:171], v[176:179], v[48:51]
	v_mfma_f32_16x16x32_bf16 v[36:39], v[160:163], v[184:187], v[36:39]
	v_mfma_f32_16x16x32_bf16 v[32:35], v[168:171], v[184:187], v[32:35]
	v_mfma_f32_16x16x32_bf16 v[20:23], v[160:163], v[230:233], v[20:23]
	v_mfma_f32_16x16x32_bf16 v[16:19], v[168:171], v[230:233], v[16:19]
	v_mfma_f32_16x16x32_bf16 v[4:7], v[160:163], v[238:241], v[4:7]
	v_mfma_f32_16x16x32_bf16 v[0:3], v[168:171], v[238:241], v[0:3]
	v_mfma_f32_16x16x32_bf16 v[52:55], v[164:167], v[180:183], v[52:55]
	v_mfma_f32_16x16x32_bf16 v[48:51], v[172:175], v[180:183], v[48:51]
	v_mfma_f32_16x16x32_bf16 v[36:39], v[164:167], v[208:211], v[36:39]
	v_mfma_f32_16x16x32_bf16 v[32:35], v[172:175], v[208:211], v[32:35]
	v_mfma_f32_16x16x32_bf16 v[20:23], v[164:167], v[234:237], v[20:23]
	v_mfma_f32_16x16x32_bf16 v[16:19], v[172:175], v[234:237], v[16:19]
	v_mfma_f32_16x16x32_bf16 v[4:7], v[164:167], v[242:245], v[4:7]
	v_mfma_f32_16x16x32_bf16 v[0:3], v[172:175], v[242:245], v[0:3]
	s_setprio 0
	s_barrier
	s_add_i32 s51, 0, 0x18000
	s_add_i32 s52, 0, 0x1c000
	v_add_u32_e32 v156, s51, v145
	v_add_u32_e32 v172, s52, v145
	ds_read_b128 v[140:143], v156
	ds_read_b128 v[148:151], v156 offset:1024
	ds_read_b128 v[152:155], v156 offset:2048
	ds_read_b128 v[156:159], v156 offset:3072
	ds_read_b128 v[160:163], v172
	ds_read_b128 v[164:167], v172 offset:1024
	ds_read_b128 v[168:171], v172 offset:2048
	ds_read_b128 v[172:175], v172 offset:3072
	s_add_u32 s16, s22, 0xb0000
	s_addc_u32 s17, s23, 0
	s_mov_b32 m0, s36
	ds_read_b128 v[176:179], v147 offset:32768
	ds_read_b128 v[180:183], v147 offset:33792
	ds_read_b128 v[184:187], v147 offset:34816
	ds_read_b128 v[208:211], v147 offset:35840
	ds_read_b128 v[230:233], v147 offset:36864
	ds_read_b128 v[234:237], v147 offset:37888
	ds_read_b128 v[238:241], v147 offset:38912
	ds_read_b128 v[242:245], v147 offset:39936
	global_load_lds_dwordx4 v130, s[16:17]
	s_mov_b32 m0, s37
	s_nop 0
	global_load_lds_dwordx4 v132, s[16:17]
	s_waitcnt vmcnt(8)
	s_waitcnt lgkmcnt(0)
	v_mfma_f32_16x16x32_bf16 v[126:129], v[140:143], v[176:179], v[126:129]
	v_mfma_f32_16x16x32_bf16 v[122:125], v[152:155], v[176:179], v[122:125]
	v_mfma_f32_16x16x32_bf16 v[108:111], v[140:143], v[184:187], v[108:111]
	v_mfma_f32_16x16x32_bf16 v[104:107], v[152:155], v[184:187], v[104:107]
	v_mfma_f32_16x16x32_bf16 v[92:95], v[140:143], v[230:233], v[92:95]
	v_mfma_f32_16x16x32_bf16 v[88:91], v[152:155], v[230:233], v[88:91]
	v_mfma_f32_16x16x32_bf16 v[76:79], v[140:143], v[238:241], v[76:79]
	v_mfma_f32_16x16x32_bf16 v[72:75], v[152:155], v[238:241], v[72:75]
	s_barrier
	s_setprio 1
	v_mfma_f32_16x16x32_bf16 v[126:129], v[148:151], v[180:183], v[126:129]
	v_mfma_f32_16x16x32_bf16 v[122:125], v[156:159], v[180:183], v[122:125]
	v_mfma_f32_16x16x32_bf16 v[108:111], v[148:151], v[208:211], v[108:111]
	v_mfma_f32_16x16x32_bf16 v[104:107], v[156:159], v[208:211], v[104:107]
	v_mfma_f32_16x16x32_bf16 v[92:95], v[148:151], v[234:237], v[92:95]
	v_mfma_f32_16x16x32_bf16 v[88:91], v[156:159], v[234:237], v[88:91]
	v_mfma_f32_16x16x32_bf16 v[76:79], v[148:151], v[242:245], v[76:79]
	v_mfma_f32_16x16x32_bf16 v[72:75], v[156:159], v[242:245], v[72:75]
	s_setprio 0
	s_setprio 1
	v_mfma_f32_16x16x32_bf16 v[118:121], v[160:163], v[176:179], v[118:121]
	v_mfma_f32_16x16x32_bf16 v[114:117], v[168:171], v[176:179], v[114:117]
	v_mfma_f32_16x16x32_bf16 v[100:103], v[160:163], v[184:187], v[100:103]
	v_mfma_f32_16x16x32_bf16 v[96:99], v[168:171], v[184:187], v[96:99]
	v_mfma_f32_16x16x32_bf16 v[84:87], v[160:163], v[230:233], v[84:87]
	v_mfma_f32_16x16x32_bf16 v[80:83], v[168:171], v[230:233], v[80:83]
	v_mfma_f32_16x16x32_bf16 v[68:71], v[160:163], v[238:241], v[68:71]
	v_mfma_f32_16x16x32_bf16 v[64:67], v[168:171], v[238:241], v[64:67]
	v_mfma_f32_16x16x32_bf16 v[118:121], v[164:167], v[180:183], v[118:121]
	v_mfma_f32_16x16x32_bf16 v[114:117], v[172:175], v[180:183], v[114:117]
	v_mfma_f32_16x16x32_bf16 v[100:103], v[164:167], v[208:211], v[100:103]
	v_mfma_f32_16x16x32_bf16 v[96:99], v[172:175], v[208:211], v[96:99]
	v_mfma_f32_16x16x32_bf16 v[84:87], v[164:167], v[234:237], v[84:87]
	v_mfma_f32_16x16x32_bf16 v[80:83], v[172:175], v[234:237], v[80:83]
	v_mfma_f32_16x16x32_bf16 v[68:71], v[164:167], v[242:245], v[68:71]
	v_mfma_f32_16x16x32_bf16 v[64:67], v[172:175], v[242:245], v[64:67]
	s_setprio 0
	s_barrier
	s_add_i32 s16, s51, s30
	s_mov_b32 m0, s16
	ds_read_b128 v[176:179], v147 offset:49152
	ds_read_b128 v[180:183], v147 offset:50176
	ds_read_b128 v[184:187], v147 offset:51200
	ds_read_b128 v[208:211], v147 offset:52224
	ds_read_b128 v[230:233], v147 offset:53248
	ds_read_b128 v[234:237], v147 offset:54272
	ds_read_b128 v[238:241], v147 offset:55296
	ds_read_b128 v[242:245], v147 offset:56320
	s_add_u32 s98, s20, 0x80
	s_addc_u32 s99, s21, 0
	global_load_lds_dwordx4 v112, s[98:99]
	s_add_i32 m0, s16, 0x2000
	s_add_u32 s16, s20, 0xb0080
	v_lshl_add_u64 v[188:189], v[212:213], 0, s[96:97]
	s_addc_u32 s17, s21, 0
	s_add_i32 s20, s52, s30
	global_load_lds_dwordx4 v[188:189], off
	s_mov_b32 m0, s20
	s_nop 0
	global_load_lds_dwordx4 v112, s[16:17]
	s_add_i32 m0, s20, 0x2000
	s_nop 0
	global_load_lds_dwordx4 v134, s[16:17]
	s_mov_b32 m0, s39
	s_nop 0
	s_add_u32 s98, s22, 0x80
	s_addc_u32 s99, s23, 0
	global_load_lds_dwordx4 v130, s[98:99]
	s_mov_b32 m0, s40
	s_nop 0
	s_add_u32 s98, s22, 0x80
	s_addc_u32 s99, s23, 0
	global_load_lds_dwordx4 v132, s[98:99]
	s_waitcnt vmcnt(8)
	s_waitcnt lgkmcnt(0)
	v_mfma_f32_16x16x32_bf16 v[60:63], v[140:143], v[176:179], v[60:63]
	v_mfma_f32_16x16x32_bf16 v[56:59], v[152:155], v[176:179], v[56:59]
	v_mfma_f32_16x16x32_bf16 v[44:47], v[140:143], v[184:187], v[44:47]
	v_mfma_f32_16x16x32_bf16 v[40:43], v[152:155], v[184:187], v[40:43]
	v_mfma_f32_16x16x32_bf16 v[28:31], v[140:143], v[230:233], v[28:31]
	v_mfma_f32_16x16x32_bf16 v[24:27], v[152:155], v[230:233], v[24:27]
	v_mfma_f32_16x16x32_bf16 v[12:15], v[140:143], v[238:241], v[12:15]
	v_mfma_f32_16x16x32_bf16 v[8:11], v[152:155], v[238:241], v[8:11]
	s_barrier
	s_setprio 1
	v_mfma_f32_16x16x32_bf16 v[60:63], v[148:151], v[180:183], v[60:63]
	v_mfma_f32_16x16x32_bf16 v[56:59], v[156:159], v[180:183], v[56:59]
	v_mfma_f32_16x16x32_bf16 v[44:47], v[148:151], v[208:211], v[44:47]
	v_mfma_f32_16x16x32_bf16 v[40:43], v[156:159], v[208:211], v[40:43]
	v_mfma_f32_16x16x32_bf16 v[28:31], v[148:151], v[234:237], v[28:31]
	v_mfma_f32_16x16x32_bf16 v[24:27], v[156:159], v[234:237], v[24:27]
	v_mfma_f32_16x16x32_bf16 v[12:15], v[148:151], v[242:245], v[12:15]
	v_mfma_f32_16x16x32_bf16 v[8:11], v[156:159], v[242:245], v[8:11]
	s_setprio 0
	s_setprio 1
	v_mfma_f32_16x16x32_bf16 v[52:55], v[160:163], v[176:179], v[52:55]
	v_mfma_f32_16x16x32_bf16 v[48:51], v[168:171], v[176:179], v[48:51]
	v_mfma_f32_16x16x32_bf16 v[36:39], v[160:163], v[184:187], v[36:39]
	v_mfma_f32_16x16x32_bf16 v[32:35], v[168:171], v[184:187], v[32:35]
	v_mfma_f32_16x16x32_bf16 v[20:23], v[160:163], v[230:233], v[20:23]
	v_mfma_f32_16x16x32_bf16 v[16:19], v[168:171], v[230:233], v[16:19]
	v_mfma_f32_16x16x32_bf16 v[4:7], v[160:163], v[238:241], v[4:7]
	v_mfma_f32_16x16x32_bf16 v[0:3], v[168:171], v[238:241], v[0:3]
	v_mfma_f32_16x16x32_bf16 v[52:55], v[164:167], v[180:183], v[52:55]
	v_mfma_f32_16x16x32_bf16 v[48:51], v[172:175], v[180:183], v[48:51]
	v_mfma_f32_16x16x32_bf16 v[36:39], v[164:167], v[208:211], v[36:39]
	v_mfma_f32_16x16x32_bf16 v[32:35], v[172:175], v[208:211], v[32:35]
	v_mfma_f32_16x16x32_bf16 v[20:23], v[164:167], v[234:237], v[20:23]
	v_mfma_f32_16x16x32_bf16 v[16:19], v[172:175], v[234:237], v[16:19]
	v_mfma_f32_16x16x32_bf16 v[4:7], v[164:167], v[242:245], v[4:7]
	v_mfma_f32_16x16x32_bf16 v[0:3], v[172:175], v[242:245], v[0:3]
	s_setprio 0
	s_barrier
	s_add_i32 s50, s50, 2
	s_add_u32 s48, s48, 0x100
	s_addc_u32 s49, s49, 0
	s_cmp_gt_u32 s50, 41
	s_mov_b64 s[16:17], s[18:19]
	s_cbranch_scc0 .LBB0_1137

.LBB0_1951:
	s_ashr_i32 s17, s16, 31
	s_lshl_b64 s[18:19], s[16:17], 19
	s_add_u32 s18, s42, s18
	s_addc_u32 s19, s43, s19
	s_and_b64 s[20:21], s[2:3], exec
	s_cselect_b32 s5, s19, s27
	s_cselect_b32 s17, s18, s26
	s_ashr_i32 s15, s14, 31
	s_lshl_b64 s[20:21], s[14:15], 19
	s_add_u32 s20, s40, s20
	s_addc_u32 s21, s41, s21
	s_and_b64 s[28:29], s[2:3], exec
	s_cselect_b32 s15, s21, s25
	s_cselect_b32 s51, s20, s24
	s_add_u32 s52, s24, 0x100
	s_addc_u32 s53, s25, 0
	s_add_u32 s24, s26, 0x40080
	s_addc_u32 s25, s27, 0
	s_mov_b32 s54, -2
	s_add_u32 s26, s24, 0xfffc0080
	s_addc_u32 s27, s25, -1
	s_add_i32 s55, 0, 0x10000
	s_cmp_eq_u32 s54, 12
	s_cselect_b32 s29, s5, s27
	s_cselect_b32 s28, s17, s26
	v_add_u32_e32 v144, s55, v146
	s_cselect_b32 s27, s15, s53
	s_cselect_b32 s26, s51, s52
	s_add_i32 s58, 0, 0x14000
	ds_read_b128 v[140:143], v144
	ds_read_b128 v[150:153], v144 offset:1024
	ds_read_b128 v[154:157], v144 offset:2048
	ds_read_b128 v[158:161], v144 offset:3072
	v_add_u32_e32 v144, s58, v146
	ds_read_b128 v[162:165], v144
	ds_read_b128 v[166:169], v144 offset:1024
	ds_read_b128 v[170:173], v144 offset:2048
	ds_read_b128 v[174:177], v144 offset:3072
	s_add_i32 m0, s23, 0xc000
	ds_read_b128 v[178:181], v149
	ds_read_b128 v[182:185], v149 offset:1024
	ds_read_b128 v[186:189], v149 offset:2048
	ds_read_b128 v[208:211], v149 offset:3072
	ds_read_b128 v[230:233], v149 offset:4096
	ds_read_b128 v[234:237], v149 offset:5120
	ds_read_b128 v[238:241], v149 offset:6144
	ds_read_b128 v[242:245], v149 offset:7168
	global_load_lds_dwordx4 v138, s[24:25]
	s_add_i32 m0, s23, 0xe000
	s_nop 0
	global_load_lds_dwordx4 v136, s[24:25]
	s_waitcnt vmcnt(8)
	s_waitcnt lgkmcnt(0)
	v_mfma_f32_16x16x32_bf16 v[126:129], v[140:143], v[178:181], 0
	v_mfma_f32_16x16x32_bf16 v[118:121], v[154:157], v[178:181], 0
	v_mfma_f32_16x16x32_bf16 v[108:111], v[140:143], v[186:189], 0
	v_mfma_f32_16x16x32_bf16 v[100:103], v[154:157], v[186:189], 0
	v_mfma_f32_16x16x32_bf16 v[92:95], v[140:143], v[230:233], 0
	v_mfma_f32_16x16x32_bf16 v[84:87], v[154:157], v[230:233], 0
	v_mfma_f32_16x16x32_bf16 v[76:79], v[140:143], v[238:241], 0
	v_mfma_f32_16x16x32_bf16 v[68:71], v[154:157], v[238:241], 0
	s_barrier
	s_setprio 1
	v_mfma_f32_16x16x32_bf16 v[126:129], v[150:153], v[182:185], v[126:129]
	v_mfma_f32_16x16x32_bf16 v[118:121], v[158:161], v[182:185], v[118:121]
	v_mfma_f32_16x16x32_bf16 v[108:111], v[150:153], v[208:211], v[108:111]
	v_mfma_f32_16x16x32_bf16 v[100:103], v[158:161], v[208:211], v[100:103]
	v_mfma_f32_16x16x32_bf16 v[92:95], v[150:153], v[234:237], v[92:95]
	v_mfma_f32_16x16x32_bf16 v[84:87], v[158:161], v[234:237], v[84:87]
	v_mfma_f32_16x16x32_bf16 v[76:79], v[150:153], v[242:245], v[76:79]
	v_mfma_f32_16x16x32_bf16 v[68:71], v[158:161], v[242:245], v[68:71]
	s_setprio 0
	s_setprio 1
	v_mfma_f32_16x16x32_bf16 v[122:125], v[162:165], v[178:181], 0
	v_mfma_f32_16x16x32_bf16 v[114:117], v[170:173], v[178:181], 0
	v_mfma_f32_16x16x32_bf16 v[104:107], v[162:165], v[186:189], 0
	v_mfma_f32_16x16x32_bf16 v[96:99], v[170:173], v[186:189], 0
	v_mfma_f32_16x16x32_bf16 v[88:91], v[162:165], v[230:233], 0
	v_mfma_f32_16x16x32_bf16 v[80:83], v[170:173], v[230:233], 0
	v_mfma_f32_16x16x32_bf16 v[72:75], v[162:165], v[238:241], 0
	v_mfma_f32_16x16x32_bf16 v[64:67], v[170:173], v[238:241], 0
	v_mfma_f32_16x16x32_bf16 v[122:125], v[166:169], v[182:185], v[122:125]
	v_mfma_f32_16x16x32_bf16 v[114:117], v[174:177], v[182:185], v[114:117]
	v_mfma_f32_16x16x32_bf16 v[104:107], v[166:169], v[208:211], v[104:107]
	v_mfma_f32_16x16x32_bf16 v[96:99], v[174:177], v[208:211], v[96:99]
	v_mfma_f32_16x16x32_bf16 v[88:91], v[166:169], v[234:237], v[88:91]
	v_mfma_f32_16x16x32_bf16 v[80:83], v[174:177], v[234:237], v[80:83]
	v_mfma_f32_16x16x32_bf16 v[72:75], v[166:169], v[242:245], v[72:75]
	v_mfma_f32_16x16x32_bf16 v[64:67], v[174:177], v[242:245], v[64:67]
	s_setprio 0
	s_barrier
	s_add_i32 s55, s55, s35
	s_mov_b32 m0, s55
	ds_read_b128 v[178:181], v149 offset:16384
	ds_read_b128 v[182:185], v149 offset:17408
	ds_read_b128 v[186:189], v149 offset:18432
	ds_read_b128 v[208:211], v149 offset:19456
	ds_read_b128 v[230:233], v149 offset:20480
	ds_read_b128 v[234:237], v149 offset:21504
	ds_read_b128 v[238:241], v149 offset:22528
	ds_read_b128 v[242:245], v149 offset:23552
	global_load_lds_dwordx4 v112, s[26:27]
	s_add_i32 m0, s55, 0x2000
	s_add_u32 s56, s26, 0x40000
	v_lshl_add_u64 v[246:247], s[26:27], 0, v[134:135]
	s_addc_u32 s57, s27, 0
	s_add_i32 s55, s58, s35
	global_load_lds_dwordx4 v134, s[26:27]
	s_mov_b32 m0, s55
	v_lshl_add_u64 v[250:251], s[28:29], 0, v[132:133]
	global_load_lds_dwordx4 v112, s[56:57]
	s_add_i32 m0, s55, 0x2000
	s_nop 0
	global_load_lds_dwordx4 v134, s[56:57]
	v_lshl_add_u64 v[248:249], s[28:29], 0, v[130:131]
	s_mov_b32 m0, s23
	s_nop 0
	global_load_lds_dwordx4 v130, s[28:29]
	s_mov_b32 m0, s44
	s_nop 0
	global_load_lds_dwordx4 v132, s[28:29]
	s_waitcnt vmcnt(8)
	s_waitcnt lgkmcnt(0)
	v_mfma_f32_16x16x32_bf16 v[60:63], v[140:143], v[178:181], 0
	v_mfma_f32_16x16x32_bf16 v[52:55], v[154:157], v[178:181], 0
	v_mfma_f32_16x16x32_bf16 v[44:47], v[140:143], v[186:189], 0
	v_mfma_f32_16x16x32_bf16 v[36:39], v[154:157], v[186:189], 0
	v_mfma_f32_16x16x32_bf16 v[28:31], v[140:143], v[230:233], 0
	v_mfma_f32_16x16x32_bf16 v[20:23], v[154:157], v[230:233], 0
	v_mfma_f32_16x16x32_bf16 v[12:15], v[140:143], v[238:241], 0
	v_mfma_f32_16x16x32_bf16 v[4:7], v[154:157], v[238:241], 0
	s_barrier
	s_setprio 1
	v_mfma_f32_16x16x32_bf16 v[60:63], v[150:153], v[182:185], v[60:63]
	v_mfma_f32_16x16x32_bf16 v[52:55], v[158:161], v[182:185], v[52:55]
	v_mfma_f32_16x16x32_bf16 v[44:47], v[150:153], v[208:211], v[44:47]
	v_mfma_f32_16x16x32_bf16 v[36:39], v[158:161], v[208:211], v[36:39]
	v_mfma_f32_16x16x32_bf16 v[28:31], v[150:153], v[234:237], v[28:31]
	v_mfma_f32_16x16x32_bf16 v[20:23], v[158:161], v[234:237], v[20:23]
	v_mfma_f32_16x16x32_bf16 v[12:15], v[150:153], v[242:245], v[12:15]
	v_mfma_f32_16x16x32_bf16 v[4:7], v[158:161], v[242:245], v[4:7]
	s_setprio 0
	s_setprio 1
	v_mfma_f32_16x16x32_bf16 v[56:59], v[162:165], v[178:181], 0
	v_mfma_f32_16x16x32_bf16 v[48:51], v[170:173], v[178:181], 0
	v_mfma_f32_16x16x32_bf16 v[40:43], v[162:165], v[186:189], 0
	v_mfma_f32_16x16x32_bf16 v[32:35], v[170:173], v[186:189], 0
	v_mfma_f32_16x16x32_bf16 v[24:27], v[162:165], v[230:233], 0
	v_mfma_f32_16x16x32_bf16 v[16:19], v[170:173], v[230:233], 0
	v_mfma_f32_16x16x32_bf16 v[8:11], v[162:165], v[238:241], 0
	v_mfma_f32_16x16x32_bf16 v[0:3], v[170:173], v[238:241], 0
	v_mfma_f32_16x16x32_bf16 v[56:59], v[166:169], v[182:185], v[56:59]
	v_mfma_f32_16x16x32_bf16 v[48:51], v[174:177], v[182:185], v[48:51]
	v_mfma_f32_16x16x32_bf16 v[40:43], v[166:169], v[208:211], v[40:43]
	v_mfma_f32_16x16x32_bf16 v[32:35], v[174:177], v[208:211], v[32:35]
	v_mfma_f32_16x16x32_bf16 v[24:27], v[166:169], v[234:237], v[24:27]
	v_mfma_f32_16x16x32_bf16 v[16:19], v[174:177], v[234:237], v[16:19]
	v_mfma_f32_16x16x32_bf16 v[8:11], v[166:169], v[242:245], v[8:11]
	v_mfma_f32_16x16x32_bf16 v[0:3], v[174:177], v[242:245], v[0:3]
	s_setprio 0
	s_barrier
	s_add_i32 s55, 0, 0x18000
	v_add_u32_e32 v144, s55, v146
	s_add_i32 s56, 0, 0x1c000
	ds_read_b128 v[140:143], v144
	ds_read_b128 v[150:153], v144 offset:1024
	ds_read_b128 v[154:157], v144 offset:2048
	ds_read_b128 v[158:161], v144 offset:3072
	v_add_u32_e32 v144, s56, v146
	ds_read_b128 v[162:165], v144
	ds_read_b128 v[166:169], v144 offset:1024
	ds_read_b128 v[170:173], v144 offset:2048
	ds_read_b128 v[174:177], v144 offset:3072
	s_add_u32 s28, s28, 0x40000
	s_addc_u32 s29, s29, 0
	s_mov_b32 m0, s45
	ds_read_b128 v[178:181], v149 offset:32768
	ds_read_b128 v[182:185], v149 offset:33792
	ds_read_b128 v[186:189], v149 offset:34816
	ds_read_b128 v[208:211], v149 offset:35840
	ds_read_b128 v[230:233], v149 offset:36864
	ds_read_b128 v[234:237], v149 offset:37888
	ds_read_b128 v[238:241], v149 offset:38912
	ds_read_b128 v[242:245], v149 offset:39936
	global_load_lds_dwordx4 v130, s[28:29]
	s_mov_b32 m0, s46
	s_nop 0
	global_load_lds_dwordx4 v132, s[28:29]
	s_waitcnt vmcnt(8)
	s_waitcnt lgkmcnt(0)
	v_mfma_f32_16x16x32_bf16 v[126:129], v[140:143], v[178:181], v[126:129]
	v_mfma_f32_16x16x32_bf16 v[118:121], v[154:157], v[178:181], v[118:121]
	v_mfma_f32_16x16x32_bf16 v[108:111], v[140:143], v[186:189], v[108:111]
	v_mfma_f32_16x16x32_bf16 v[100:103], v[154:157], v[186:189], v[100:103]
	v_mfma_f32_16x16x32_bf16 v[92:95], v[140:143], v[230:233], v[92:95]
	v_mfma_f32_16x16x32_bf16 v[84:87], v[154:157], v[230:233], v[84:87]
	v_mfma_f32_16x16x32_bf16 v[76:79], v[140:143], v[238:241], v[76:79]
	v_mfma_f32_16x16x32_bf16 v[68:71], v[154:157], v[238:241], v[68:71]
	s_barrier
	s_setprio 1
	v_mfma_f32_16x16x32_bf16 v[126:129], v[150:153], v[182:185], v[126:129]
	v_mfma_f32_16x16x32_bf16 v[118:121], v[158:161], v[182:185], v[118:121]
	v_mfma_f32_16x16x32_bf16 v[108:111], v[150:153], v[208:211], v[108:111]
	v_mfma_f32_16x16x32_bf16 v[100:103], v[158:161], v[208:211], v[100:103]
	v_mfma_f32_16x16x32_bf16 v[92:95], v[150:153], v[234:237], v[92:95]
	v_mfma_f32_16x16x32_bf16 v[84:87], v[158:161], v[234:237], v[84:87]
	v_mfma_f32_16x16x32_bf16 v[76:79], v[150:153], v[242:245], v[76:79]
	v_mfma_f32_16x16x32_bf16 v[68:71], v[158:161], v[242:245], v[68:71]
	s_setprio 0
	s_setprio 1
	v_mfma_f32_16x16x32_bf16 v[122:125], v[162:165], v[178:181], v[122:125]
	v_mfma_f32_16x16x32_bf16 v[114:117], v[170:173], v[178:181], v[114:117]
	v_mfma_f32_16x16x32_bf16 v[104:107], v[162:165], v[186:189], v[104:107]
	v_mfma_f32_16x16x32_bf16 v[96:99], v[170:173], v[186:189], v[96:99]
	v_mfma_f32_16x16x32_bf16 v[88:91], v[162:165], v[230:233], v[88:91]
	v_mfma_f32_16x16x32_bf16 v[80:83], v[170:173], v[230:233], v[80:83]
	v_mfma_f32_16x16x32_bf16 v[72:75], v[162:165], v[238:241], v[72:75]
	v_mfma_f32_16x16x32_bf16 v[64:67], v[170:173], v[238:241], v[64:67]
	v_mfma_f32_16x16x32_bf16 v[122:125], v[166:169], v[182:185], v[122:125]
	v_mfma_f32_16x16x32_bf16 v[114:117], v[174:177], v[182:185], v[114:117]
	v_mfma_f32_16x16x32_bf16 v[104:107], v[166:169], v[208:211], v[104:107]
	v_mfma_f32_16x16x32_bf16 v[96:99], v[174:177], v[208:211], v[96:99]
	v_mfma_f32_16x16x32_bf16 v[88:91], v[166:169], v[234:237], v[88:91]
	v_mfma_f32_16x16x32_bf16 v[80:83], v[174:177], v[234:237], v[80:83]
	v_mfma_f32_16x16x32_bf16 v[72:75], v[166:169], v[242:245], v[72:75]
	v_mfma_f32_16x16x32_bf16 v[64:67], v[174:177], v[242:245], v[64:67]
	s_setprio 0
	s_barrier
	s_add_i32 s28, s55, s35
	s_mov_b32 m0, s28
	ds_read_b128 v[178:181], v149 offset:49152
	ds_read_b128 v[182:185], v149 offset:50176
	ds_read_b128 v[186:189], v149 offset:51200
	ds_read_b128 v[208:211], v149 offset:52224
	ds_read_b128 v[230:233], v149 offset:53248
	ds_read_b128 v[234:237], v149 offset:54272
	ds_read_b128 v[238:241], v149 offset:55296
	ds_read_b128 v[242:245], v149 offset:56320
	s_add_u32 s98, s26, 0x80
	s_addc_u32 s99, s27, 0
	global_load_lds_dwordx4 v112, s[98:99]
	s_add_i32 m0, s28, 0x2000
	s_add_u32 s26, s26, 0x40080
	v_lshl_add_u64 v[212:213], v[246:247], 0, s[96:97]
	s_addc_u32 s27, s27, 0
	s_add_i32 s28, s56, s35
	global_load_lds_dwordx4 v[212:213], off
	s_mov_b32 m0, s28
	s_nop 0
	global_load_lds_dwordx4 v112, s[26:27]
	s_add_i32 m0, s28, 0x2000
	s_nop 0
	global_load_lds_dwordx4 v134, s[26:27]
	v_lshl_add_u64 v[212:213], v[248:249], 0, s[96:97]
	s_mov_b32 m0, s47
	s_nop 0
	global_load_lds_dwordx4 v[212:213], off
	v_lshl_add_u64 v[212:213], v[250:251], 0, s[96:97]
	s_mov_b32 m0, s48
	s_nop 0
	global_load_lds_dwordx4 v[212:213], off
	s_waitcnt vmcnt(8)
	s_waitcnt lgkmcnt(0)
	v_mfma_f32_16x16x32_bf16 v[60:63], v[140:143], v[178:181], v[60:63]
	v_mfma_f32_16x16x32_bf16 v[52:55], v[154:157], v[178:181], v[52:55]
	v_mfma_f32_16x16x32_bf16 v[44:47], v[140:143], v[186:189], v[44:47]
	v_mfma_f32_16x16x32_bf16 v[36:39], v[154:157], v[186:189], v[36:39]
	v_mfma_f32_16x16x32_bf16 v[28:31], v[140:143], v[230:233], v[28:31]
	v_mfma_f32_16x16x32_bf16 v[20:23], v[154:157], v[230:233], v[20:23]
	v_mfma_f32_16x16x32_bf16 v[12:15], v[140:143], v[238:241], v[12:15]
	v_mfma_f32_16x16x32_bf16 v[4:7], v[154:157], v[238:241], v[4:7]
	s_barrier
	s_setprio 1
	v_mfma_f32_16x16x32_bf16 v[60:63], v[150:153], v[182:185], v[60:63]
	v_mfma_f32_16x16x32_bf16 v[52:55], v[158:161], v[182:185], v[52:55]
	v_mfma_f32_16x16x32_bf16 v[44:47], v[150:153], v[208:211], v[44:47]
	v_mfma_f32_16x16x32_bf16 v[36:39], v[158:161], v[208:211], v[36:39]
	v_mfma_f32_16x16x32_bf16 v[28:31], v[150:153], v[234:237], v[28:31]
	v_mfma_f32_16x16x32_bf16 v[20:23], v[158:161], v[234:237], v[20:23]
	v_mfma_f32_16x16x32_bf16 v[12:15], v[150:153], v[242:245], v[12:15]
	v_mfma_f32_16x16x32_bf16 v[4:7], v[158:161], v[242:245], v[4:7]
	s_setprio 0
	s_setprio 1
	v_mfma_f32_16x16x32_bf16 v[56:59], v[162:165], v[178:181], v[56:59]
	v_mfma_f32_16x16x32_bf16 v[48:51], v[170:173], v[178:181], v[48:51]
	v_mfma_f32_16x16x32_bf16 v[40:43], v[162:165], v[186:189], v[40:43]
	v_mfma_f32_16x16x32_bf16 v[32:35], v[170:173], v[186:189], v[32:35]
	v_mfma_f32_16x16x32_bf16 v[24:27], v[162:165], v[230:233], v[24:27]
	v_mfma_f32_16x16x32_bf16 v[16:19], v[170:173], v[230:233], v[16:19]
	v_mfma_f32_16x16x32_bf16 v[8:11], v[162:165], v[238:241], v[8:11]
	v_mfma_f32_16x16x32_bf16 v[0:3], v[170:173], v[238:241], v[0:3]
	v_mfma_f32_16x16x32_bf16 v[56:59], v[166:169], v[182:185], v[56:59]
	v_mfma_f32_16x16x32_bf16 v[48:51], v[174:177], v[182:185], v[48:51]
	v_mfma_f32_16x16x32_bf16 v[40:43], v[166:169], v[208:211], v[40:43]
	v_mfma_f32_16x16x32_bf16 v[32:35], v[174:177], v[208:211], v[32:35]
	v_mfma_f32_16x16x32_bf16 v[24:27], v[166:169], v[234:237], v[24:27]
	v_mfma_f32_16x16x32_bf16 v[16:19], v[174:177], v[234:237], v[16:19]
	v_mfma_f32_16x16x32_bf16 v[8:11], v[166:169], v[242:245], v[8:11]
	v_mfma_f32_16x16x32_bf16 v[0:3], v[174:177], v[242:245], v[0:3]
	s_setprio 0
	s_barrier
	s_add_i32 s54, s54, 2
	s_add_u32 s52, s52, 0x100
	s_addc_u32 s53, s53, 0
	s_add_u32 s24, s24, 0x100
	s_addc_u32 s25, s25, 0
	s_cmp_gt_u32 s54, 13
	s_cbranch_scc0 .LBB0_1952
	s_branch .Lpeel_exit_1952
.LBB0_1952:
	s_add_u32 s26, s24, 0xfffc0080
	s_addc_u32 s27, s25, -1
	s_add_i32 s55, 0, 0x10000
	s_cmp_eq_u32 s54, 12
	s_cselect_b32 s29, s5, s27
	s_cselect_b32 s28, s17, s26
	v_add_u32_e32 v144, s55, v146
	s_cselect_b32 s27, s15, s53
	s_cselect_b32 s26, s51, s52
	s_add_i32 s58, 0, 0x14000
	ds_read_b128 v[140:143], v144
	ds_read_b128 v[150:153], v144 offset:1024
	ds_read_b128 v[154:157], v144 offset:2048
	ds_read_b128 v[158:161], v144 offset:3072
	v_add_u32_e32 v144, s58, v146
	ds_read_b128 v[162:165], v144
	ds_read_b128 v[166:169], v144 offset:1024
	ds_read_b128 v[170:173], v144 offset:2048
	ds_read_b128 v[174:177], v144 offset:3072
	s_add_i32 m0, s23, 0xc000
	ds_read_b128 v[178:181], v149
	ds_read_b128 v[182:185], v149 offset:1024
	ds_read_b128 v[186:189], v149 offset:2048
	ds_read_b128 v[208:211], v149 offset:3072
	ds_read_b128 v[230:233], v149 offset:4096
	ds_read_b128 v[234:237], v149 offset:5120
	ds_read_b128 v[238:241], v149 offset:6144
	ds_read_b128 v[242:245], v149 offset:7168
	global_load_lds_dwordx4 v138, s[24:25]
	s_add_i32 m0, s23, 0xe000
	s_nop 0
	global_load_lds_dwordx4 v136, s[24:25]
	s_waitcnt vmcnt(8)
	s_waitcnt lgkmcnt(0)
	v_mfma_f32_16x16x32_bf16 v[126:129], v[140:143], v[178:181], v[126:129]
	v_mfma_f32_16x16x32_bf16 v[118:121], v[154:157], v[178:181], v[118:121]
	v_mfma_f32_16x16x32_bf16 v[108:111], v[140:143], v[186:189], v[108:111]
	v_mfma_f32_16x16x32_bf16 v[100:103], v[154:157], v[186:189], v[100:103]
	v_mfma_f32_16x16x32_bf16 v[92:95], v[140:143], v[230:233], v[92:95]
	v_mfma_f32_16x16x32_bf16 v[84:87], v[154:157], v[230:233], v[84:87]
	v_mfma_f32_16x16x32_bf16 v[76:79], v[140:143], v[238:241], v[76:79]
	v_mfma_f32_16x16x32_bf16 v[68:71], v[154:157], v[238:241], v[68:71]
	s_barrier
	s_setprio 1
	v_mfma_f32_16x16x32_bf16 v[126:129], v[150:153], v[182:185], v[126:129]
	v_mfma_f32_16x16x32_bf16 v[118:121], v[158:161], v[182:185], v[118:121]
	v_mfma_f32_16x16x32_bf16 v[108:111], v[150:153], v[208:211], v[108:111]
	v_mfma_f32_16x16x32_bf16 v[100:103], v[158:161], v[208:211], v[100:103]
	v_mfma_f32_16x16x32_bf16 v[92:95], v[150:153], v[234:237], v[92:95]
	v_mfma_f32_16x16x32_bf16 v[84:87], v[158:161], v[234:237], v[84:87]
	v_mfma_f32_16x16x32_bf16 v[76:79], v[150:153], v[242:245], v[76:79]
	v_mfma_f32_16x16x32_bf16 v[68:71], v[158:161], v[242:245], v[68:71]
	s_setprio 0
	s_setprio 1
	v_mfma_f32_16x16x32_bf16 v[122:125], v[162:165], v[178:181], v[122:125]
	v_mfma_f32_16x16x32_bf16 v[114:117], v[170:173], v[178:181], v[114:117]
	v_mfma_f32_16x16x32_bf16 v[104:107], v[162:165], v[186:189], v[104:107]
	v_mfma_f32_16x16x32_bf16 v[96:99], v[170:173], v[186:189], v[96:99]
	v_mfma_f32_16x16x32_bf16 v[88:91], v[162:165], v[230:233], v[88:91]
	v_mfma_f32_16x16x32_bf16 v[80:83], v[170:173], v[230:233], v[80:83]
	v_mfma_f32_16x16x32_bf16 v[72:75], v[162:165], v[238:241], v[72:75]
	v_mfma_f32_16x16x32_bf16 v[64:67], v[170:173], v[238:241], v[64:67]
	v_mfma_f32_16x16x32_bf16 v[122:125], v[166:169], v[182:185], v[122:125]
	v_mfma_f32_16x16x32_bf16 v[114:117], v[174:177], v[182:185], v[114:117]
	v_mfma_f32_16x16x32_bf16 v[104:107], v[166:169], v[208:211], v[104:107]
	v_mfma_f32_16x16x32_bf16 v[96:99], v[174:177], v[208:211], v[96:99]
	v_mfma_f32_16x16x32_bf16 v[88:91], v[166:169], v[234:237], v[88:91]
	v_mfma_f32_16x16x32_bf16 v[80:83], v[174:177], v[234:237], v[80:83]
	v_mfma_f32_16x16x32_bf16 v[72:75], v[166:169], v[242:245], v[72:75]
	v_mfma_f32_16x16x32_bf16 v[64:67], v[174:177], v[242:245], v[64:67]
	s_setprio 0
	s_barrier
	s_add_i32 s55, s55, s35
	s_mov_b32 m0, s55
	ds_read_b128 v[178:181], v149 offset:16384
	ds_read_b128 v[182:185], v149 offset:17408
	ds_read_b128 v[186:189], v149 offset:18432
	ds_read_b128 v[208:211], v149 offset:19456
	ds_read_b128 v[230:233], v149 offset:20480
	ds_read_b128 v[234:237], v149 offset:21504
	ds_read_b128 v[238:241], v149 offset:22528
	ds_read_b128 v[242:245], v149 offset:23552
	global_load_lds_dwordx4 v112, s[26:27]
	s_add_i32 m0, s55, 0x2000
	s_add_u32 s56, s26, 0x40000
	v_lshl_add_u64 v[246:247], s[26:27], 0, v[134:135]
	s_addc_u32 s57, s27, 0
	s_add_i32 s55, s58, s35
	global_load_lds_dwordx4 v134, s[26:27]
	s_mov_b32 m0, s55
	v_lshl_add_u64 v[250:251], s[28:29], 0, v[132:133]
	global_load_lds_dwordx4 v112, s[56:57]
	s_add_i32 m0, s55, 0x2000
	s_nop 0
	global_load_lds_dwordx4 v134, s[56:57]
	v_lshl_add_u64 v[248:249], s[28:29], 0, v[130:131]
	s_mov_b32 m0, s23
	s_nop 0
	global_load_lds_dwordx4 v130, s[28:29]
	s_mov_b32 m0, s44
	s_nop 0
	global_load_lds_dwordx4 v132, s[28:29]
	s_waitcnt vmcnt(8)
	s_waitcnt lgkmcnt(0)
	v_mfma_f32_16x16x32_bf16 v[60:63], v[140:143], v[178:181], v[60:63]
	v_mfma_f32_16x16x32_bf16 v[52:55], v[154:157], v[178:181], v[52:55]
	v_mfma_f32_16x16x32_bf16 v[44:47], v[140:143], v[186:189], v[44:47]
	v_mfma_f32_16x16x32_bf16 v[36:39], v[154:157], v[186:189], v[36:39]
	v_mfma_f32_16x16x32_bf16 v[28:31], v[140:143], v[230:233], v[28:31]
	v_mfma_f32_16x16x32_bf16 v[20:23], v[154:157], v[230:233], v[20:23]
	v_mfma_f32_16x16x32_bf16 v[12:15], v[140:143], v[238:241], v[12:15]
	v_mfma_f32_16x16x32_bf16 v[4:7], v[154:157], v[238:241], v[4:7]
	s_barrier
	s_setprio 1
	v_mfma_f32_16x16x32_bf16 v[60:63], v[150:153], v[182:185], v[60:63]
	v_mfma_f32_16x16x32_bf16 v[52:55], v[158:161], v[182:185], v[52:55]
	v_mfma_f32_16x16x32_bf16 v[44:47], v[150:153], v[208:211], v[44:47]
	v_mfma_f32_16x16x32_bf16 v[36:39], v[158:161], v[208:211], v[36:39]
	v_mfma_f32_16x16x32_bf16 v[28:31], v[150:153], v[234:237], v[28:31]
	v_mfma_f32_16x16x32_bf16 v[20:23], v[158:161], v[234:237], v[20:23]
	v_mfma_f32_16x16x32_bf16 v[12:15], v[150:153], v[242:245], v[12:15]
	v_mfma_f32_16x16x32_bf16 v[4:7], v[158:161], v[242:245], v[4:7]
	s_setprio 0
	s_setprio 1
	v_mfma_f32_16x16x32_bf16 v[56:59], v[162:165], v[178:181], v[56:59]
	v_mfma_f32_16x16x32_bf16 v[48:51], v[170:173], v[178:181], v[48:51]
	v_mfma_f32_16x16x32_bf16 v[40:43], v[162:165], v[186:189], v[40:43]
	v_mfma_f32_16x16x32_bf16 v[32:35], v[170:173], v[186:189], v[32:35]
	v_mfma_f32_16x16x32_bf16 v[24:27], v[162:165], v[230:233], v[24:27]
	v_mfma_f32_16x16x32_bf16 v[16:19], v[170:173], v[230:233], v[16:19]
	v_mfma_f32_16x16x32_bf16 v[8:11], v[162:165], v[238:241], v[8:11]
	v_mfma_f32_16x16x32_bf16 v[0:3], v[170:173], v[238:241], v[0:3]
	v_mfma_f32_16x16x32_bf16 v[56:59], v[166:169], v[182:185], v[56:59]
	v_mfma_f32_16x16x32_bf16 v[48:51], v[174:177], v[182:185], v[48:51]
	v_mfma_f32_16x16x32_bf16 v[40:43], v[166:169], v[208:211], v[40:43]
	v_mfma_f32_16x16x32_bf16 v[32:35], v[174:177], v[208:211], v[32:35]
	v_mfma_f32_16x16x32_bf16 v[24:27], v[166:169], v[234:237], v[24:27]
	v_mfma_f32_16x16x32_bf16 v[16:19], v[174:177], v[234:237], v[16:19]
	v_mfma_f32_16x16x32_bf16 v[8:11], v[166:169], v[242:245], v[8:11]
	v_mfma_f32_16x16x32_bf16 v[0:3], v[174:177], v[242:245], v[0:3]
	s_setprio 0
	s_barrier
	s_add_i32 s55, 0, 0x18000
	v_add_u32_e32 v144, s55, v146
	s_add_i32 s56, 0, 0x1c000
	ds_read_b128 v[140:143], v144
	ds_read_b128 v[150:153], v144 offset:1024
	ds_read_b128 v[154:157], v144 offset:2048
	ds_read_b128 v[158:161], v144 offset:3072
	v_add_u32_e32 v144, s56, v146
	ds_read_b128 v[162:165], v144
	ds_read_b128 v[166:169], v144 offset:1024
	ds_read_b128 v[170:173], v144 offset:2048
	ds_read_b128 v[174:177], v144 offset:3072
	s_add_u32 s28, s28, 0x40000
	s_addc_u32 s29, s29, 0
	s_mov_b32 m0, s45
	ds_read_b128 v[178:181], v149 offset:32768
	ds_read_b128 v[182:185], v149 offset:33792
	ds_read_b128 v[186:189], v149 offset:34816
	ds_read_b128 v[208:211], v149 offset:35840
	ds_read_b128 v[230:233], v149 offset:36864
	ds_read_b128 v[234:237], v149 offset:37888
	ds_read_b128 v[238:241], v149 offset:38912
	ds_read_b128 v[242:245], v149 offset:39936
	global_load_lds_dwordx4 v130, s[28:29]
	s_mov_b32 m0, s46
	s_nop 0
	global_load_lds_dwordx4 v132, s[28:29]
	s_waitcnt vmcnt(8)
	s_waitcnt lgkmcnt(0)
	v_mfma_f32_16x16x32_bf16 v[126:129], v[140:143], v[178:181], v[126:129]
	v_mfma_f32_16x16x32_bf16 v[118:121], v[154:157], v[178:181], v[118:121]
	v_mfma_f32_16x16x32_bf16 v[108:111], v[140:143], v[186:189], v[108:111]
	v_mfma_f32_16x16x32_bf16 v[100:103], v[154:157], v[186:189], v[100:103]
	v_mfma_f32_16x16x32_bf16 v[92:95], v[140:143], v[230:233], v[92:95]
	v_mfma_f32_16x16x32_bf16 v[84:87], v[154:157], v[230:233], v[84:87]
	v_mfma_f32_16x16x32_bf16 v[76:79], v[140:143], v[238:241], v[76:79]
	v_mfma_f32_16x16x32_bf16 v[68:71], v[154:157], v[238:241], v[68:71]
	s_barrier
	s_setprio 1
	v_mfma_f32_16x16x32_bf16 v[126:129], v[150:153], v[182:185], v[126:129]
	v_mfma_f32_16x16x32_bf16 v[118:121], v[158:161], v[182:185], v[118:121]
	v_mfma_f32_16x16x32_bf16 v[108:111], v[150:153], v[208:211], v[108:111]
	v_mfma_f32_16x16x32_bf16 v[100:103], v[158:161], v[208:211], v[100:103]
	v_mfma_f32_16x16x32_bf16 v[92:95], v[150:153], v[234:237], v[92:95]
	v_mfma_f32_16x16x32_bf16 v[84:87], v[158:161], v[234:237], v[84:87]
	v_mfma_f32_16x16x32_bf16 v[76:79], v[150:153], v[242:245], v[76:79]
	v_mfma_f32_16x16x32_bf16 v[68:71], v[158:161], v[242:245], v[68:71]
	s_setprio 0
	s_setprio 1
	v_mfma_f32_16x16x32_bf16 v[122:125], v[162:165], v[178:181], v[122:125]
	v_mfma_f32_16x16x32_bf16 v[114:117], v[170:173], v[178:181], v[114:117]
	v_mfma_f32_16x16x32_bf16 v[104:107], v[162:165], v[186:189], v[104:107]
	v_mfma_f32_16x16x32_bf16 v[96:99], v[170:173], v[186:189], v[96:99]
	v_mfma_f32_16x16x32_bf16 v[88:91], v[162:165], v[230:233], v[88:91]
	v_mfma_f32_16x16x32_bf16 v[80:83], v[170:173], v[230:233], v[80:83]
	v_mfma_f32_16x16x32_bf16 v[72:75], v[162:165], v[238:241], v[72:75]
	v_mfma_f32_16x16x32_bf16 v[64:67], v[170:173], v[238:241], v[64:67]
	v_mfma_f32_16x16x32_bf16 v[122:125], v[166:169], v[182:185], v[122:125]
	v_mfma_f32_16x16x32_bf16 v[114:117], v[174:177], v[182:185], v[114:117]
	v_mfma_f32_16x16x32_bf16 v[104:107], v[166:169], v[208:211], v[104:107]
	v_mfma_f32_16x16x32_bf16 v[96:99], v[174:177], v[208:211], v[96:99]
	v_mfma_f32_16x16x32_bf16 v[88:91], v[166:169], v[234:237], v[88:91]
	v_mfma_f32_16x16x32_bf16 v[80:83], v[174:177], v[234:237], v[80:83]
	v_mfma_f32_16x16x32_bf16 v[72:75], v[166:169], v[242:245], v[72:75]
	v_mfma_f32_16x16x32_bf16 v[64:67], v[174:177], v[242:245], v[64:67]
	s_setprio 0
	s_barrier
	s_add_i32 s28, s55, s35
	s_mov_b32 m0, s28
	ds_read_b128 v[178:181], v149 offset:49152
	ds_read_b128 v[182:185], v149 offset:50176
	ds_read_b128 v[186:189], v149 offset:51200
	ds_read_b128 v[208:211], v149 offset:52224
	ds_read_b128 v[230:233], v149 offset:53248
	ds_read_b128 v[234:237], v149 offset:54272
	ds_read_b128 v[238:241], v149 offset:55296
	ds_read_b128 v[242:245], v149 offset:56320
	s_add_u32 s98, s26, 0x80
	s_addc_u32 s99, s27, 0
	global_load_lds_dwordx4 v112, s[98:99]
	s_add_i32 m0, s28, 0x2000
	s_add_u32 s26, s26, 0x40080
	v_lshl_add_u64 v[212:213], v[246:247], 0, s[96:97]
	s_addc_u32 s27, s27, 0
	s_add_i32 s28, s56, s35
	global_load_lds_dwordx4 v[212:213], off
	s_mov_b32 m0, s28
	s_nop 0
	global_load_lds_dwordx4 v112, s[26:27]
	s_add_i32 m0, s28, 0x2000
	s_nop 0
	global_load_lds_dwordx4 v134, s[26:27]
	v_lshl_add_u64 v[212:213], v[248:249], 0, s[96:97]
	s_mov_b32 m0, s47
	s_nop 0
	global_load_lds_dwordx4 v[212:213], off
	v_lshl_add_u64 v[212:213], v[250:251], 0, s[96:97]
	s_mov_b32 m0, s48
	s_nop 0
	global_load_lds_dwordx4 v[212:213], off
	s_waitcnt vmcnt(8)
	s_waitcnt lgkmcnt(0)
	v_mfma_f32_16x16x32_bf16 v[60:63], v[140:143], v[178:181], v[60:63]
	v_mfma_f32_16x16x32_bf16 v[52:55], v[154:157], v[178:181], v[52:55]
	v_mfma_f32_16x16x32_bf16 v[44:47], v[140:143], v[186:189], v[44:47]
	v_mfma_f32_16x16x32_bf16 v[36:39], v[154:157], v[186:189], v[36:39]
	v_mfma_f32_16x16x32_bf16 v[28:31], v[140:143], v[230:233], v[28:31]
	v_mfma_f32_16x16x32_bf16 v[20:23], v[154:157], v[230:233], v[20:23]
	v_mfma_f32_16x16x32_bf16 v[12:15], v[140:143], v[238:241], v[12:15]
	v_mfma_f32_16x16x32_bf16 v[4:7], v[154:157], v[238:241], v[4:7]
	s_barrier
	s_setprio 1
	v_mfma_f32_16x16x32_bf16 v[60:63], v[150:153], v[182:185], v[60:63]
	v_mfma_f32_16x16x32_bf16 v[52:55], v[158:161], v[182:185], v[52:55]
	v_mfma_f32_16x16x32_bf16 v[44:47], v[150:153], v[208:211], v[44:47]
	v_mfma_f32_16x16x32_bf16 v[36:39], v[158:161], v[208:211], v[36:39]
	v_mfma_f32_16x16x32_bf16 v[28:31], v[150:153], v[234:237], v[28:31]
	v_mfma_f32_16x16x32_bf16 v[20:23], v[158:161], v[234:237], v[20:23]
	v_mfma_f32_16x16x32_bf16 v[12:15], v[150:153], v[242:245], v[12:15]
	v_mfma_f32_16x16x32_bf16 v[4:7], v[158:161], v[242:245], v[4:7]
	s_setprio 0
	s_setprio 1
	v_mfma_f32_16x16x32_bf16 v[56:59], v[162:165], v[178:181], v[56:59]
	v_mfma_f32_16x16x32_bf16 v[48:51], v[170:173], v[178:181], v[48:51]
	v_mfma_f32_16x16x32_bf16 v[40:43], v[162:165], v[186:189], v[40:43]
	v_mfma_f32_16x16x32_bf16 v[32:35], v[170:173], v[186:189], v[32:35]
	v_mfma_f32_16x16x32_bf16 v[24:27], v[162:165], v[230:233], v[24:27]
	v_mfma_f32_16x16x32_bf16 v[16:19], v[170:173], v[230:233], v[16:19]
	v_mfma_f32_16x16x32_bf16 v[8:11], v[162:165], v[238:241], v[8:11]
	v_mfma_f32_16x16x32_bf16 v[0:3], v[170:173], v[238:241], v[0:3]
	v_mfma_f32_16x16x32_bf16 v[56:59], v[166:169], v[182:185], v[56:59]
	v_mfma_f32_16x16x32_bf16 v[48:51], v[174:177], v[182:185], v[48:51]
	v_mfma_f32_16x16x32_bf16 v[40:43], v[166:169], v[208:211], v[40:43]
	v_mfma_f32_16x16x32_bf16 v[32:35], v[174:177], v[208:211], v[32:35]
	v_mfma_f32_16x16x32_bf16 v[24:27], v[166:169], v[234:237], v[24:27]
	v_mfma_f32_16x16x32_bf16 v[16:19], v[174:177], v[234:237], v[16:19]
	v_mfma_f32_16x16x32_bf16 v[8:11], v[166:169], v[242:245], v[8:11]
	v_mfma_f32_16x16x32_bf16 v[0:3], v[174:177], v[242:245], v[0:3]
	s_setprio 0
	s_barrier
	s_add_i32 s54, s54, 2
	s_add_u32 s52, s52, 0x100
	s_addc_u32 s53, s53, 0
	s_add_u32 s24, s24, 0x100
	s_addc_u32 s25, s25, 0
	s_cmp_gt_u32 s54, 13
	s_cbranch_scc0 .LBB0_1952

.LBB0_2150:
	s_ashr_i32 s29, s28, 31
	s_lshl_b64 s[30:31], s[28:29], 19
	s_add_u32 s30, s49, s30
	s_addc_u32 s31, s50, s31
	s_and_b64 s[40:41], s[6:7], exec
	s_cselect_b32 s11, s31, s39
	s_cselect_b32 s29, s30, s38
	s_ashr_i32 s27, s26, 31
	s_lshl_b64 s[40:41], s[26:27], 19
	s_add_u32 s46, s51, s40
	s_addc_u32 s47, s52, s41
	s_and_b64 s[40:41], s[6:7], exec
	s_cselect_b32 s27, s47, s9
	s_cselect_b32 s35, s46, s8
	s_add_u32 s42, s8, 0x100
	s_addc_u32 s43, s9, 0
	s_add_u32 s8, s38, 0x40080
	s_addc_u32 s9, s39, 0
	s_mov_b32 s44, -2
	s_add_u32 s38, s8, 0xfffc0080
	s_addc_u32 s39, s9, -1
	s_add_i32 s45, 0, 0x10000
	s_cmp_eq_u32 s44, 12
	s_cselect_b32 s41, s11, s39
	s_cselect_b32 s40, s29, s38
	v_add_u32_e32 v112, s45, v169
	s_cselect_b32 s39, s27, s43
	s_cselect_b32 s38, s35, s42
	s_add_i32 s68, 0, 0x14000
	ds_read_b128 v[130:133], v112
	ds_read_b128 v[134:137], v112 offset:1024
	ds_read_b128 v[150:153], v112 offset:2048
	ds_read_b128 v[154:157], v112 offset:3072
	v_add_u32_e32 v112, s68, v169
	ds_read_b128 v[158:161], v112
	ds_read_b128 v[162:165], v112 offset:1024
	ds_read_b128 v[174:177], v112 offset:2048
	ds_read_b128 v[178:181], v112 offset:3072
	s_add_i32 m0, s37, 0xc000
	ds_read_b128 v[182:185], v172
	ds_read_b128 v[186:189], v172 offset:1024
	ds_read_b128 v[208:211], v172 offset:2048
	ds_read_b128 v[230:233], v172 offset:3072
	ds_read_b128 v[234:237], v172 offset:4096
	ds_read_b128 v[238:241], v172 offset:5120
	ds_read_b128 v[242:245], v172 offset:6144
	ds_read_b128 v[246:249], v172 offset:7168
	global_load_lds_dwordx4 v148, s[8:9]
	s_add_i32 m0, s37, 0xe000
	s_nop 0
	global_load_lds_dwordx4 v146, s[8:9]
	s_waitcnt vmcnt(8)
	s_waitcnt lgkmcnt(0)
	v_mfma_f32_16x16x32_bf16 v[126:129], v[130:133], v[182:185], 0
	v_mfma_f32_16x16x32_bf16 v[122:125], v[150:153], v[182:185], 0
	v_mfma_f32_16x16x32_bf16 v[108:111], v[130:133], v[208:211], 0
	v_mfma_f32_16x16x32_bf16 v[104:107], v[150:153], v[208:211], 0
	v_mfma_f32_16x16x32_bf16 v[92:95], v[130:133], v[234:237], 0
	v_mfma_f32_16x16x32_bf16 v[88:91], v[150:153], v[234:237], 0
	v_mfma_f32_16x16x32_bf16 v[76:79], v[130:133], v[242:245], 0
	v_mfma_f32_16x16x32_bf16 v[72:75], v[150:153], v[242:245], 0
	s_barrier
	s_setprio 1
	v_mfma_f32_16x16x32_bf16 v[126:129], v[134:137], v[186:189], v[126:129]
	v_mfma_f32_16x16x32_bf16 v[122:125], v[154:157], v[186:189], v[122:125]
	v_mfma_f32_16x16x32_bf16 v[108:111], v[134:137], v[230:233], v[108:111]
	v_mfma_f32_16x16x32_bf16 v[104:107], v[154:157], v[230:233], v[104:107]
	v_mfma_f32_16x16x32_bf16 v[92:95], v[134:137], v[238:241], v[92:95]
	v_mfma_f32_16x16x32_bf16 v[88:91], v[154:157], v[238:241], v[88:91]
	v_mfma_f32_16x16x32_bf16 v[76:79], v[134:137], v[246:249], v[76:79]
	v_mfma_f32_16x16x32_bf16 v[72:75], v[154:157], v[246:249], v[72:75]
	s_setprio 0
	s_setprio 1
	v_mfma_f32_16x16x32_bf16 v[118:121], v[158:161], v[182:185], 0
	v_mfma_f32_16x16x32_bf16 v[114:117], v[174:177], v[182:185], 0
	v_mfma_f32_16x16x32_bf16 v[100:103], v[158:161], v[208:211], 0
	v_mfma_f32_16x16x32_bf16 v[96:99], v[174:177], v[208:211], 0
	v_mfma_f32_16x16x32_bf16 v[84:87], v[158:161], v[234:237], 0
	v_mfma_f32_16x16x32_bf16 v[80:83], v[174:177], v[234:237], 0
	v_mfma_f32_16x16x32_bf16 v[68:71], v[158:161], v[242:245], 0
	v_mfma_f32_16x16x32_bf16 v[64:67], v[174:177], v[242:245], 0
	v_mfma_f32_16x16x32_bf16 v[118:121], v[162:165], v[186:189], v[118:121]
	v_mfma_f32_16x16x32_bf16 v[114:117], v[178:181], v[186:189], v[114:117]
	v_mfma_f32_16x16x32_bf16 v[100:103], v[162:165], v[230:233], v[100:103]
	v_mfma_f32_16x16x32_bf16 v[96:99], v[178:181], v[230:233], v[96:99]
	v_mfma_f32_16x16x32_bf16 v[84:87], v[162:165], v[238:241], v[84:87]
	v_mfma_f32_16x16x32_bf16 v[80:83], v[178:181], v[238:241], v[80:83]
	v_mfma_f32_16x16x32_bf16 v[68:71], v[162:165], v[246:249], v[68:71]
	v_mfma_f32_16x16x32_bf16 v[64:67], v[178:181], v[246:249], v[64:67]
	s_setprio 0
	s_barrier
	s_add_i32 s45, s45, s58
	s_mov_b32 m0, s45
	ds_read_b128 v[182:185], v172 offset:16384
	ds_read_b128 v[186:189], v172 offset:17408
	ds_read_b128 v[208:211], v172 offset:18432
	ds_read_b128 v[230:233], v172 offset:19456
	ds_read_b128 v[234:237], v172 offset:20480
	ds_read_b128 v[238:241], v172 offset:21504
	ds_read_b128 v[242:245], v172 offset:22528
	ds_read_b128 v[246:249], v172 offset:23552
	global_load_lds_dwordx4 v140, s[38:39]
	s_add_i32 m0, s45, 0x2000
	s_add_u32 s66, s38, 0x40000
	v_lshl_add_u64 v[212:213], s[38:39], 0, v[144:145]
	s_addc_u32 s67, s39, 0
	s_add_i32 s45, s68, s58
	global_load_lds_dwordx4 v144, s[38:39]
	s_mov_b32 m0, s45
	v_lshl_add_u64 v[250:251], s[40:41], 0, v[142:143]
	global_load_lds_dwordx4 v140, s[66:67]
	s_add_i32 m0, s45, 0x2000
	s_nop 0
	global_load_lds_dwordx4 v144, s[66:67]
	v_lshl_add_u64 v[228:229], s[40:41], 0, v[138:139]
	s_mov_b32 m0, s37
	s_nop 0
	global_load_lds_dwordx4 v138, s[40:41]
	s_mov_b32 m0, s59
	s_nop 0
	global_load_lds_dwordx4 v142, s[40:41]
	s_waitcnt vmcnt(8)
	s_waitcnt lgkmcnt(0)
	v_mfma_f32_16x16x32_bf16 v[60:63], v[130:133], v[182:185], 0
	v_mfma_f32_16x16x32_bf16 v[56:59], v[150:153], v[182:185], 0
	v_mfma_f32_16x16x32_bf16 v[44:47], v[130:133], v[208:211], 0
	v_mfma_f32_16x16x32_bf16 v[40:43], v[150:153], v[208:211], 0
	v_mfma_f32_16x16x32_bf16 v[28:31], v[130:133], v[234:237], 0
	v_mfma_f32_16x16x32_bf16 v[24:27], v[150:153], v[234:237], 0
	v_mfma_f32_16x16x32_bf16 v[12:15], v[130:133], v[242:245], 0
	v_mfma_f32_16x16x32_bf16 v[8:11], v[150:153], v[242:245], 0
	s_barrier
	s_setprio 1
	v_mfma_f32_16x16x32_bf16 v[60:63], v[134:137], v[186:189], v[60:63]
	v_mfma_f32_16x16x32_bf16 v[56:59], v[154:157], v[186:189], v[56:59]
	v_mfma_f32_16x16x32_bf16 v[44:47], v[134:137], v[230:233], v[44:47]
	v_mfma_f32_16x16x32_bf16 v[40:43], v[154:157], v[230:233], v[40:43]
	v_mfma_f32_16x16x32_bf16 v[28:31], v[134:137], v[238:241], v[28:31]
	v_mfma_f32_16x16x32_bf16 v[24:27], v[154:157], v[238:241], v[24:27]
	v_mfma_f32_16x16x32_bf16 v[12:15], v[134:137], v[246:249], v[12:15]
	v_mfma_f32_16x16x32_bf16 v[8:11], v[154:157], v[246:249], v[8:11]
	s_setprio 0
	s_setprio 1
	v_mfma_f32_16x16x32_bf16 v[52:55], v[158:161], v[182:185], 0
	v_mfma_f32_16x16x32_bf16 v[48:51], v[174:177], v[182:185], 0
	v_mfma_f32_16x16x32_bf16 v[36:39], v[158:161], v[208:211], 0
	v_mfma_f32_16x16x32_bf16 v[32:35], v[174:177], v[208:211], 0
	v_mfma_f32_16x16x32_bf16 v[20:23], v[158:161], v[234:237], 0
	v_mfma_f32_16x16x32_bf16 v[16:19], v[174:177], v[234:237], 0
	v_mfma_f32_16x16x32_bf16 v[4:7], v[158:161], v[242:245], 0
	v_mfma_f32_16x16x32_bf16 v[0:3], v[174:177], v[242:245], 0
	v_mfma_f32_16x16x32_bf16 v[52:55], v[162:165], v[186:189], v[52:55]
	v_mfma_f32_16x16x32_bf16 v[48:51], v[178:181], v[186:189], v[48:51]
	v_mfma_f32_16x16x32_bf16 v[36:39], v[162:165], v[230:233], v[36:39]
	v_mfma_f32_16x16x32_bf16 v[32:35], v[178:181], v[230:233], v[32:35]
	v_mfma_f32_16x16x32_bf16 v[20:23], v[162:165], v[238:241], v[20:23]
	v_mfma_f32_16x16x32_bf16 v[16:19], v[178:181], v[238:241], v[16:19]
	v_mfma_f32_16x16x32_bf16 v[4:7], v[162:165], v[246:249], v[4:7]
	v_mfma_f32_16x16x32_bf16 v[0:3], v[178:181], v[246:249], v[0:3]
	s_setprio 0
	s_barrier
	s_add_i32 s45, 0, 0x18000
	v_add_u32_e32 v112, s45, v169
	s_add_i32 s66, 0, 0x1c000
	ds_read_b128 v[130:133], v112
	ds_read_b128 v[134:137], v112 offset:1024
	ds_read_b128 v[150:153], v112 offset:2048
	ds_read_b128 v[154:157], v112 offset:3072
	v_add_u32_e32 v112, s66, v169
	ds_read_b128 v[158:161], v112
	ds_read_b128 v[162:165], v112 offset:1024
	ds_read_b128 v[174:177], v112 offset:2048
	ds_read_b128 v[178:181], v112 offset:3072
	s_add_u32 s40, s40, 0x40000
	s_addc_u32 s41, s41, 0
	s_mov_b32 m0, s60
	ds_read_b128 v[182:185], v172 offset:32768
	ds_read_b128 v[186:189], v172 offset:33792
	ds_read_b128 v[208:211], v172 offset:34816
	ds_read_b128 v[230:233], v172 offset:35840
	ds_read_b128 v[234:237], v172 offset:36864
	ds_read_b128 v[238:241], v172 offset:37888
	ds_read_b128 v[242:245], v172 offset:38912
	ds_read_b128 v[246:249], v172 offset:39936
	global_load_lds_dwordx4 v138, s[40:41]
	s_mov_b32 m0, s61
	s_nop 0
	global_load_lds_dwordx4 v142, s[40:41]
	s_waitcnt vmcnt(8)
	s_waitcnt lgkmcnt(0)
	v_mfma_f32_16x16x32_bf16 v[126:129], v[130:133], v[182:185], v[126:129]
	v_mfma_f32_16x16x32_bf16 v[122:125], v[150:153], v[182:185], v[122:125]
	v_mfma_f32_16x16x32_bf16 v[108:111], v[130:133], v[208:211], v[108:111]
	v_mfma_f32_16x16x32_bf16 v[104:107], v[150:153], v[208:211], v[104:107]
	v_mfma_f32_16x16x32_bf16 v[92:95], v[130:133], v[234:237], v[92:95]
	v_mfma_f32_16x16x32_bf16 v[88:91], v[150:153], v[234:237], v[88:91]
	v_mfma_f32_16x16x32_bf16 v[76:79], v[130:133], v[242:245], v[76:79]
	v_mfma_f32_16x16x32_bf16 v[72:75], v[150:153], v[242:245], v[72:75]
	s_barrier
	s_setprio 1
	v_mfma_f32_16x16x32_bf16 v[126:129], v[134:137], v[186:189], v[126:129]
	v_mfma_f32_16x16x32_bf16 v[122:125], v[154:157], v[186:189], v[122:125]
	v_mfma_f32_16x16x32_bf16 v[108:111], v[134:137], v[230:233], v[108:111]
	v_mfma_f32_16x16x32_bf16 v[104:107], v[154:157], v[230:233], v[104:107]
	v_mfma_f32_16x16x32_bf16 v[92:95], v[134:137], v[238:241], v[92:95]
	v_mfma_f32_16x16x32_bf16 v[88:91], v[154:157], v[238:241], v[88:91]
	v_mfma_f32_16x16x32_bf16 v[76:79], v[134:137], v[246:249], v[76:79]
	v_mfma_f32_16x16x32_bf16 v[72:75], v[154:157], v[246:249], v[72:75]
	s_setprio 0
	s_setprio 1
	v_mfma_f32_16x16x32_bf16 v[118:121], v[158:161], v[182:185], v[118:121]
	v_mfma_f32_16x16x32_bf16 v[114:117], v[174:177], v[182:185], v[114:117]
	v_mfma_f32_16x16x32_bf16 v[100:103], v[158:161], v[208:211], v[100:103]
	v_mfma_f32_16x16x32_bf16 v[96:99], v[174:177], v[208:211], v[96:99]
	v_mfma_f32_16x16x32_bf16 v[84:87], v[158:161], v[234:237], v[84:87]
	v_mfma_f32_16x16x32_bf16 v[80:83], v[174:177], v[234:237], v[80:83]
	v_mfma_f32_16x16x32_bf16 v[68:71], v[158:161], v[242:245], v[68:71]
	v_mfma_f32_16x16x32_bf16 v[64:67], v[174:177], v[242:245], v[64:67]
	v_mfma_f32_16x16x32_bf16 v[118:121], v[162:165], v[186:189], v[118:121]
	v_mfma_f32_16x16x32_bf16 v[114:117], v[178:181], v[186:189], v[114:117]
	v_mfma_f32_16x16x32_bf16 v[100:103], v[162:165], v[230:233], v[100:103]
	v_mfma_f32_16x16x32_bf16 v[96:99], v[178:181], v[230:233], v[96:99]
	v_mfma_f32_16x16x32_bf16 v[84:87], v[162:165], v[238:241], v[84:87]
	v_mfma_f32_16x16x32_bf16 v[80:83], v[178:181], v[238:241], v[80:83]
	v_mfma_f32_16x16x32_bf16 v[68:71], v[162:165], v[246:249], v[68:71]
	v_mfma_f32_16x16x32_bf16 v[64:67], v[178:181], v[246:249], v[64:67]
	s_setprio 0
	s_barrier
	s_add_i32 s40, s45, s58
	s_mov_b32 m0, s40
	ds_read_b128 v[182:185], v172 offset:49152
	ds_read_b128 v[186:189], v172 offset:50176
	ds_read_b128 v[208:211], v172 offset:51200
	ds_read_b128 v[230:233], v172 offset:52224
	ds_read_b128 v[234:237], v172 offset:53248
	ds_read_b128 v[238:241], v172 offset:54272
	ds_read_b128 v[242:245], v172 offset:55296
	ds_read_b128 v[246:249], v172 offset:56320
	s_add_u32 s98, s38, 0x80
	s_addc_u32 s99, s39, 0
	global_load_lds_dwordx4 v140, s[98:99]
	s_add_i32 m0, s40, 0x2000
	s_add_u32 s38, s38, 0x40080
	v_lshl_add_u64 v[166:167], v[212:213], 0, s[96:97]
	s_addc_u32 s39, s39, 0
	s_add_i32 s40, s66, s58
	global_load_lds_dwordx4 v[166:167], off
	s_mov_b32 m0, s40
	s_nop 0
	global_load_lds_dwordx4 v140, s[38:39]
	s_add_i32 m0, s40, 0x2000
	s_nop 0
	global_load_lds_dwordx4 v144, s[38:39]
	v_lshl_add_u64 v[166:167], v[228:229], 0, s[96:97]
	s_mov_b32 m0, s62
	s_nop 0
	global_load_lds_dwordx4 v[166:167], off
	v_lshl_add_u64 v[166:167], v[250:251], 0, s[96:97]
	s_mov_b32 m0, s63
	s_nop 0
	global_load_lds_dwordx4 v[166:167], off
	s_waitcnt vmcnt(8)
	s_waitcnt lgkmcnt(0)
	v_mfma_f32_16x16x32_bf16 v[60:63], v[130:133], v[182:185], v[60:63]
	v_mfma_f32_16x16x32_bf16 v[56:59], v[150:153], v[182:185], v[56:59]
	v_mfma_f32_16x16x32_bf16 v[44:47], v[130:133], v[208:211], v[44:47]
	v_mfma_f32_16x16x32_bf16 v[40:43], v[150:153], v[208:211], v[40:43]
	v_mfma_f32_16x16x32_bf16 v[28:31], v[130:133], v[234:237], v[28:31]
	v_mfma_f32_16x16x32_bf16 v[24:27], v[150:153], v[234:237], v[24:27]
	v_mfma_f32_16x16x32_bf16 v[12:15], v[130:133], v[242:245], v[12:15]
	v_mfma_f32_16x16x32_bf16 v[8:11], v[150:153], v[242:245], v[8:11]
	s_barrier
	s_setprio 1
	v_mfma_f32_16x16x32_bf16 v[60:63], v[134:137], v[186:189], v[60:63]
	v_mfma_f32_16x16x32_bf16 v[56:59], v[154:157], v[186:189], v[56:59]
	v_mfma_f32_16x16x32_bf16 v[44:47], v[134:137], v[230:233], v[44:47]
	v_mfma_f32_16x16x32_bf16 v[40:43], v[154:157], v[230:233], v[40:43]
	v_mfma_f32_16x16x32_bf16 v[28:31], v[134:137], v[238:241], v[28:31]
	v_mfma_f32_16x16x32_bf16 v[24:27], v[154:157], v[238:241], v[24:27]
	v_mfma_f32_16x16x32_bf16 v[12:15], v[134:137], v[246:249], v[12:15]
	v_mfma_f32_16x16x32_bf16 v[8:11], v[154:157], v[246:249], v[8:11]
	s_setprio 0
	s_setprio 1
	v_mfma_f32_16x16x32_bf16 v[52:55], v[158:161], v[182:185], v[52:55]
	v_mfma_f32_16x16x32_bf16 v[48:51], v[174:177], v[182:185], v[48:51]
	v_mfma_f32_16x16x32_bf16 v[36:39], v[158:161], v[208:211], v[36:39]
	v_mfma_f32_16x16x32_bf16 v[32:35], v[174:177], v[208:211], v[32:35]
	v_mfma_f32_16x16x32_bf16 v[20:23], v[158:161], v[234:237], v[20:23]
	v_mfma_f32_16x16x32_bf16 v[16:19], v[174:177], v[234:237], v[16:19]
	v_mfma_f32_16x16x32_bf16 v[4:7], v[158:161], v[242:245], v[4:7]
	v_mfma_f32_16x16x32_bf16 v[0:3], v[174:177], v[242:245], v[0:3]
	v_mfma_f32_16x16x32_bf16 v[52:55], v[162:165], v[186:189], v[52:55]
	v_mfma_f32_16x16x32_bf16 v[48:51], v[178:181], v[186:189], v[48:51]
	v_mfma_f32_16x16x32_bf16 v[36:39], v[162:165], v[230:233], v[36:39]
	v_mfma_f32_16x16x32_bf16 v[32:35], v[178:181], v[230:233], v[32:35]
	v_mfma_f32_16x16x32_bf16 v[20:23], v[162:165], v[238:241], v[20:23]
	v_mfma_f32_16x16x32_bf16 v[16:19], v[178:181], v[238:241], v[16:19]
	v_mfma_f32_16x16x32_bf16 v[4:7], v[162:165], v[246:249], v[4:7]
	v_mfma_f32_16x16x32_bf16 v[0:3], v[178:181], v[246:249], v[0:3]
	s_setprio 0
	s_barrier
	s_add_i32 s44, s44, 2
	s_add_u32 s42, s42, 0x100
	s_addc_u32 s43, s43, 0
	s_add_u32 s8, s8, 0x100
	s_addc_u32 s9, s9, 0
	s_cmp_gt_u32 s44, 13
	s_cbranch_scc0 .LBB0_2151
	s_branch .Lpeel_exit_2151
.LBB0_2151:
	s_add_u32 s38, s8, 0xfffc0080
	s_addc_u32 s39, s9, -1
	s_add_i32 s45, 0, 0x10000
	s_cmp_eq_u32 s44, 12
	s_cselect_b32 s41, s11, s39
	s_cselect_b32 s40, s29, s38
	v_add_u32_e32 v112, s45, v169
	s_cselect_b32 s39, s27, s43
	s_cselect_b32 s38, s35, s42
	s_add_i32 s68, 0, 0x14000
	ds_read_b128 v[130:133], v112
	ds_read_b128 v[134:137], v112 offset:1024
	ds_read_b128 v[150:153], v112 offset:2048
	ds_read_b128 v[154:157], v112 offset:3072
	v_add_u32_e32 v112, s68, v169
	ds_read_b128 v[158:161], v112
	ds_read_b128 v[162:165], v112 offset:1024
	ds_read_b128 v[174:177], v112 offset:2048
	ds_read_b128 v[178:181], v112 offset:3072
	s_add_i32 m0, s37, 0xc000
	ds_read_b128 v[182:185], v172
	ds_read_b128 v[186:189], v172 offset:1024
	ds_read_b128 v[208:211], v172 offset:2048
	ds_read_b128 v[230:233], v172 offset:3072
	ds_read_b128 v[234:237], v172 offset:4096
	ds_read_b128 v[238:241], v172 offset:5120
	ds_read_b128 v[242:245], v172 offset:6144
	ds_read_b128 v[246:249], v172 offset:7168
	global_load_lds_dwordx4 v148, s[8:9]
	s_add_i32 m0, s37, 0xe000
	s_nop 0
	global_load_lds_dwordx4 v146, s[8:9]
	s_waitcnt vmcnt(8)
	s_waitcnt lgkmcnt(0)
	v_mfma_f32_16x16x32_bf16 v[126:129], v[130:133], v[182:185], v[126:129]
	v_mfma_f32_16x16x32_bf16 v[122:125], v[150:153], v[182:185], v[122:125]
	v_mfma_f32_16x16x32_bf16 v[108:111], v[130:133], v[208:211], v[108:111]
	v_mfma_f32_16x16x32_bf16 v[104:107], v[150:153], v[208:211], v[104:107]
	v_mfma_f32_16x16x32_bf16 v[92:95], v[130:133], v[234:237], v[92:95]
	v_mfma_f32_16x16x32_bf16 v[88:91], v[150:153], v[234:237], v[88:91]
	v_mfma_f32_16x16x32_bf16 v[76:79], v[130:133], v[242:245], v[76:79]
	v_mfma_f32_16x16x32_bf16 v[72:75], v[150:153], v[242:245], v[72:75]
	s_barrier
	s_setprio 1
	v_mfma_f32_16x16x32_bf16 v[126:129], v[134:137], v[186:189], v[126:129]
	v_mfma_f32_16x16x32_bf16 v[122:125], v[154:157], v[186:189], v[122:125]
	v_mfma_f32_16x16x32_bf16 v[108:111], v[134:137], v[230:233], v[108:111]
	v_mfma_f32_16x16x32_bf16 v[104:107], v[154:157], v[230:233], v[104:107]
	v_mfma_f32_16x16x32_bf16 v[92:95], v[134:137], v[238:241], v[92:95]
	v_mfma_f32_16x16x32_bf16 v[88:91], v[154:157], v[238:241], v[88:91]
	v_mfma_f32_16x16x32_bf16 v[76:79], v[134:137], v[246:249], v[76:79]
	v_mfma_f32_16x16x32_bf16 v[72:75], v[154:157], v[246:249], v[72:75]
	s_setprio 0
	s_setprio 1
	v_mfma_f32_16x16x32_bf16 v[118:121], v[158:161], v[182:185], v[118:121]
	v_mfma_f32_16x16x32_bf16 v[114:117], v[174:177], v[182:185], v[114:117]
	v_mfma_f32_16x16x32_bf16 v[100:103], v[158:161], v[208:211], v[100:103]
	v_mfma_f32_16x16x32_bf16 v[96:99], v[174:177], v[208:211], v[96:99]
	v_mfma_f32_16x16x32_bf16 v[84:87], v[158:161], v[234:237], v[84:87]
	v_mfma_f32_16x16x32_bf16 v[80:83], v[174:177], v[234:237], v[80:83]
	v_mfma_f32_16x16x32_bf16 v[68:71], v[158:161], v[242:245], v[68:71]
	v_mfma_f32_16x16x32_bf16 v[64:67], v[174:177], v[242:245], v[64:67]
	v_mfma_f32_16x16x32_bf16 v[118:121], v[162:165], v[186:189], v[118:121]
	v_mfma_f32_16x16x32_bf16 v[114:117], v[178:181], v[186:189], v[114:117]
	v_mfma_f32_16x16x32_bf16 v[100:103], v[162:165], v[230:233], v[100:103]
	v_mfma_f32_16x16x32_bf16 v[96:99], v[178:181], v[230:233], v[96:99]
	v_mfma_f32_16x16x32_bf16 v[84:87], v[162:165], v[238:241], v[84:87]
	v_mfma_f32_16x16x32_bf16 v[80:83], v[178:181], v[238:241], v[80:83]
	v_mfma_f32_16x16x32_bf16 v[68:71], v[162:165], v[246:249], v[68:71]
	v_mfma_f32_16x16x32_bf16 v[64:67], v[178:181], v[246:249], v[64:67]
	s_setprio 0
	s_barrier
	s_add_i32 s45, s45, s58
	s_mov_b32 m0, s45
	ds_read_b128 v[182:185], v172 offset:16384
	ds_read_b128 v[186:189], v172 offset:17408
	ds_read_b128 v[208:211], v172 offset:18432
	ds_read_b128 v[230:233], v172 offset:19456
	ds_read_b128 v[234:237], v172 offset:20480
	ds_read_b128 v[238:241], v172 offset:21504
	ds_read_b128 v[242:245], v172 offset:22528
	ds_read_b128 v[246:249], v172 offset:23552
	global_load_lds_dwordx4 v140, s[38:39]
	s_add_i32 m0, s45, 0x2000
	s_add_u32 s66, s38, 0x40000
	v_lshl_add_u64 v[212:213], s[38:39], 0, v[144:145]
	s_addc_u32 s67, s39, 0
	s_add_i32 s45, s68, s58
	global_load_lds_dwordx4 v144, s[38:39]
	s_mov_b32 m0, s45
	v_lshl_add_u64 v[250:251], s[40:41], 0, v[142:143]
	global_load_lds_dwordx4 v140, s[66:67]
	s_add_i32 m0, s45, 0x2000
	s_nop 0
	global_load_lds_dwordx4 v144, s[66:67]
	v_lshl_add_u64 v[228:229], s[40:41], 0, v[138:139]
	s_mov_b32 m0, s37
	s_nop 0
	global_load_lds_dwordx4 v138, s[40:41]
	s_mov_b32 m0, s59
	s_nop 0
	global_load_lds_dwordx4 v142, s[40:41]
	s_waitcnt vmcnt(8)
	s_waitcnt lgkmcnt(0)
	v_mfma_f32_16x16x32_bf16 v[60:63], v[130:133], v[182:185], v[60:63]
	v_mfma_f32_16x16x32_bf16 v[56:59], v[150:153], v[182:185], v[56:59]
	v_mfma_f32_16x16x32_bf16 v[44:47], v[130:133], v[208:211], v[44:47]
	v_mfma_f32_16x16x32_bf16 v[40:43], v[150:153], v[208:211], v[40:43]
	v_mfma_f32_16x16x32_bf16 v[28:31], v[130:133], v[234:237], v[28:31]
	v_mfma_f32_16x16x32_bf16 v[24:27], v[150:153], v[234:237], v[24:27]
	v_mfma_f32_16x16x32_bf16 v[12:15], v[130:133], v[242:245], v[12:15]
	v_mfma_f32_16x16x32_bf16 v[8:11], v[150:153], v[242:245], v[8:11]
	s_barrier
	s_setprio 1
	v_mfma_f32_16x16x32_bf16 v[60:63], v[134:137], v[186:189], v[60:63]
	v_mfma_f32_16x16x32_bf16 v[56:59], v[154:157], v[186:189], v[56:59]
	v_mfma_f32_16x16x32_bf16 v[44:47], v[134:137], v[230:233], v[44:47]
	v_mfma_f32_16x16x32_bf16 v[40:43], v[154:157], v[230:233], v[40:43]
	v_mfma_f32_16x16x32_bf16 v[28:31], v[134:137], v[238:241], v[28:31]
	v_mfma_f32_16x16x32_bf16 v[24:27], v[154:157], v[238:241], v[24:27]
	v_mfma_f32_16x16x32_bf16 v[12:15], v[134:137], v[246:249], v[12:15]
	v_mfma_f32_16x16x32_bf16 v[8:11], v[154:157], v[246:249], v[8:11]
	s_setprio 0
	s_setprio 1
	v_mfma_f32_16x16x32_bf16 v[52:55], v[158:161], v[182:185], v[52:55]
	v_mfma_f32_16x16x32_bf16 v[48:51], v[174:177], v[182:185], v[48:51]
	v_mfma_f32_16x16x32_bf16 v[36:39], v[158:161], v[208:211], v[36:39]
	v_mfma_f32_16x16x32_bf16 v[32:35], v[174:177], v[208:211], v[32:35]
	v_mfma_f32_16x16x32_bf16 v[20:23], v[158:161], v[234:237], v[20:23]
	v_mfma_f32_16x16x32_bf16 v[16:19], v[174:177], v[234:237], v[16:19]
	v_mfma_f32_16x16x32_bf16 v[4:7], v[158:161], v[242:245], v[4:7]
	v_mfma_f32_16x16x32_bf16 v[0:3], v[174:177], v[242:245], v[0:3]
	v_mfma_f32_16x16x32_bf16 v[52:55], v[162:165], v[186:189], v[52:55]
	v_mfma_f32_16x16x32_bf16 v[48:51], v[178:181], v[186:189], v[48:51]
	v_mfma_f32_16x16x32_bf16 v[36:39], v[162:165], v[230:233], v[36:39]
	v_mfma_f32_16x16x32_bf16 v[32:35], v[178:181], v[230:233], v[32:35]
	v_mfma_f32_16x16x32_bf16 v[20:23], v[162:165], v[238:241], v[20:23]
	v_mfma_f32_16x16x32_bf16 v[16:19], v[178:181], v[238:241], v[16:19]
	v_mfma_f32_16x16x32_bf16 v[4:7], v[162:165], v[246:249], v[4:7]
	v_mfma_f32_16x16x32_bf16 v[0:3], v[178:181], v[246:249], v[0:3]
	s_setprio 0
	s_barrier
	s_add_i32 s45, 0, 0x18000
	v_add_u32_e32 v112, s45, v169
	s_add_i32 s66, 0, 0x1c000
	ds_read_b128 v[130:133], v112
	ds_read_b128 v[134:137], v112 offset:1024
	ds_read_b128 v[150:153], v112 offset:2048
	ds_read_b128 v[154:157], v112 offset:3072
	v_add_u32_e32 v112, s66, v169
	ds_read_b128 v[158:161], v112
	ds_read_b128 v[162:165], v112 offset:1024
	ds_read_b128 v[174:177], v112 offset:2048
	ds_read_b128 v[178:181], v112 offset:3072
	s_add_u32 s40, s40, 0x40000
	s_addc_u32 s41, s41, 0
	s_mov_b32 m0, s60
	ds_read_b128 v[182:185], v172 offset:32768
	ds_read_b128 v[186:189], v172 offset:33792
	ds_read_b128 v[208:211], v172 offset:34816
	ds_read_b128 v[230:233], v172 offset:35840
	ds_read_b128 v[234:237], v172 offset:36864
	ds_read_b128 v[238:241], v172 offset:37888
	ds_read_b128 v[242:245], v172 offset:38912
	ds_read_b128 v[246:249], v172 offset:39936
	global_load_lds_dwordx4 v138, s[40:41]
	s_mov_b32 m0, s61
	s_nop 0
	global_load_lds_dwordx4 v142, s[40:41]
	s_waitcnt vmcnt(8)
	s_waitcnt lgkmcnt(0)
	v_mfma_f32_16x16x32_bf16 v[126:129], v[130:133], v[182:185], v[126:129]
	v_mfma_f32_16x16x32_bf16 v[122:125], v[150:153], v[182:185], v[122:125]
	v_mfma_f32_16x16x32_bf16 v[108:111], v[130:133], v[208:211], v[108:111]
	v_mfma_f32_16x16x32_bf16 v[104:107], v[150:153], v[208:211], v[104:107]
	v_mfma_f32_16x16x32_bf16 v[92:95], v[130:133], v[234:237], v[92:95]
	v_mfma_f32_16x16x32_bf16 v[88:91], v[150:153], v[234:237], v[88:91]
	v_mfma_f32_16x16x32_bf16 v[76:79], v[130:133], v[242:245], v[76:79]
	v_mfma_f32_16x16x32_bf16 v[72:75], v[150:153], v[242:245], v[72:75]
	s_barrier
	s_setprio 1
	v_mfma_f32_16x16x32_bf16 v[126:129], v[134:137], v[186:189], v[126:129]
	v_mfma_f32_16x16x32_bf16 v[122:125], v[154:157], v[186:189], v[122:125]
	v_mfma_f32_16x16x32_bf16 v[108:111], v[134:137], v[230:233], v[108:111]
	v_mfma_f32_16x16x32_bf16 v[104:107], v[154:157], v[230:233], v[104:107]
	v_mfma_f32_16x16x32_bf16 v[92:95], v[134:137], v[238:241], v[92:95]
	v_mfma_f32_16x16x32_bf16 v[88:91], v[154:157], v[238:241], v[88:91]
	v_mfma_f32_16x16x32_bf16 v[76:79], v[134:137], v[246:249], v[76:79]
	v_mfma_f32_16x16x32_bf16 v[72:75], v[154:157], v[246:249], v[72:75]
	s_setprio 0
	s_setprio 1
	v_mfma_f32_16x16x32_bf16 v[118:121], v[158:161], v[182:185], v[118:121]
	v_mfma_f32_16x16x32_bf16 v[114:117], v[174:177], v[182:185], v[114:117]
	v_mfma_f32_16x16x32_bf16 v[100:103], v[158:161], v[208:211], v[100:103]
	v_mfma_f32_16x16x32_bf16 v[96:99], v[174:177], v[208:211], v[96:99]
	v_mfma_f32_16x16x32_bf16 v[84:87], v[158:161], v[234:237], v[84:87]
	v_mfma_f32_16x16x32_bf16 v[80:83], v[174:177], v[234:237], v[80:83]
	v_mfma_f32_16x16x32_bf16 v[68:71], v[158:161], v[242:245], v[68:71]
	v_mfma_f32_16x16x32_bf16 v[64:67], v[174:177], v[242:245], v[64:67]
	v_mfma_f32_16x16x32_bf16 v[118:121], v[162:165], v[186:189], v[118:121]
	v_mfma_f32_16x16x32_bf16 v[114:117], v[178:181], v[186:189], v[114:117]
	v_mfma_f32_16x16x32_bf16 v[100:103], v[162:165], v[230:233], v[100:103]
	v_mfma_f32_16x16x32_bf16 v[96:99], v[178:181], v[230:233], v[96:99]
	v_mfma_f32_16x16x32_bf16 v[84:87], v[162:165], v[238:241], v[84:87]
	v_mfma_f32_16x16x32_bf16 v[80:83], v[178:181], v[238:241], v[80:83]
	v_mfma_f32_16x16x32_bf16 v[68:71], v[162:165], v[246:249], v[68:71]
	v_mfma_f32_16x16x32_bf16 v[64:67], v[178:181], v[246:249], v[64:67]
	s_setprio 0
	s_barrier
	s_add_i32 s40, s45, s58
	s_mov_b32 m0, s40
	ds_read_b128 v[182:185], v172 offset:49152
	ds_read_b128 v[186:189], v172 offset:50176
	ds_read_b128 v[208:211], v172 offset:51200
	ds_read_b128 v[230:233], v172 offset:52224
	ds_read_b128 v[234:237], v172 offset:53248
	ds_read_b128 v[238:241], v172 offset:54272
	ds_read_b128 v[242:245], v172 offset:55296
	ds_read_b128 v[246:249], v172 offset:56320
	s_add_u32 s98, s38, 0x80
	s_addc_u32 s99, s39, 0
	global_load_lds_dwordx4 v140, s[98:99]
	s_add_i32 m0, s40, 0x2000
	s_add_u32 s38, s38, 0x40080
	v_lshl_add_u64 v[166:167], v[212:213], 0, s[96:97]
	s_addc_u32 s39, s39, 0
	s_add_i32 s40, s66, s58
	global_load_lds_dwordx4 v[166:167], off
	s_mov_b32 m0, s40
	s_nop 0
	global_load_lds_dwordx4 v140, s[38:39]
	s_add_i32 m0, s40, 0x2000
	s_nop 0
	global_load_lds_dwordx4 v144, s[38:39]
	v_lshl_add_u64 v[166:167], v[228:229], 0, s[96:97]
	s_mov_b32 m0, s62
	s_nop 0
	global_load_lds_dwordx4 v[166:167], off
	v_lshl_add_u64 v[166:167], v[250:251], 0, s[96:97]
	s_mov_b32 m0, s63
	s_nop 0
	global_load_lds_dwordx4 v[166:167], off
	s_waitcnt vmcnt(8)
	s_waitcnt lgkmcnt(0)
	v_mfma_f32_16x16x32_bf16 v[60:63], v[130:133], v[182:185], v[60:63]
	v_mfma_f32_16x16x32_bf16 v[56:59], v[150:153], v[182:185], v[56:59]
	v_mfma_f32_16x16x32_bf16 v[44:47], v[130:133], v[208:211], v[44:47]
	v_mfma_f32_16x16x32_bf16 v[40:43], v[150:153], v[208:211], v[40:43]
	v_mfma_f32_16x16x32_bf16 v[28:31], v[130:133], v[234:237], v[28:31]
	v_mfma_f32_16x16x32_bf16 v[24:27], v[150:153], v[234:237], v[24:27]
	v_mfma_f32_16x16x32_bf16 v[12:15], v[130:133], v[242:245], v[12:15]
	v_mfma_f32_16x16x32_bf16 v[8:11], v[150:153], v[242:245], v[8:11]
	s_barrier
	s_setprio 1
	v_mfma_f32_16x16x32_bf16 v[60:63], v[134:137], v[186:189], v[60:63]
	v_mfma_f32_16x16x32_bf16 v[56:59], v[154:157], v[186:189], v[56:59]
	v_mfma_f32_16x16x32_bf16 v[44:47], v[134:137], v[230:233], v[44:47]
	v_mfma_f32_16x16x32_bf16 v[40:43], v[154:157], v[230:233], v[40:43]
	v_mfma_f32_16x16x32_bf16 v[28:31], v[134:137], v[238:241], v[28:31]
	v_mfma_f32_16x16x32_bf16 v[24:27], v[154:157], v[238:241], v[24:27]
	v_mfma_f32_16x16x32_bf16 v[12:15], v[134:137], v[246:249], v[12:15]
	v_mfma_f32_16x16x32_bf16 v[8:11], v[154:157], v[246:249], v[8:11]
	s_setprio 0
	s_setprio 1
	v_mfma_f32_16x16x32_bf16 v[52:55], v[158:161], v[182:185], v[52:55]
	v_mfma_f32_16x16x32_bf16 v[48:51], v[174:177], v[182:185], v[48:51]
	v_mfma_f32_16x16x32_bf16 v[36:39], v[158:161], v[208:211], v[36:39]
	v_mfma_f32_16x16x32_bf16 v[32:35], v[174:177], v[208:211], v[32:35]
	v_mfma_f32_16x16x32_bf16 v[20:23], v[158:161], v[234:237], v[20:23]
	v_mfma_f32_16x16x32_bf16 v[16:19], v[174:177], v[234:237], v[16:19]
	v_mfma_f32_16x16x32_bf16 v[4:7], v[158:161], v[242:245], v[4:7]
	v_mfma_f32_16x16x32_bf16 v[0:3], v[174:177], v[242:245], v[0:3]
	v_mfma_f32_16x16x32_bf16 v[52:55], v[162:165], v[186:189], v[52:55]
	v_mfma_f32_16x16x32_bf16 v[48:51], v[178:181], v[186:189], v[48:51]
	v_mfma_f32_16x16x32_bf16 v[36:39], v[162:165], v[230:233], v[36:39]
	v_mfma_f32_16x16x32_bf16 v[32:35], v[178:181], v[230:233], v[32:35]
	v_mfma_f32_16x16x32_bf16 v[20:23], v[162:165], v[238:241], v[20:23]
	v_mfma_f32_16x16x32_bf16 v[16:19], v[178:181], v[238:241], v[16:19]
	v_mfma_f32_16x16x32_bf16 v[4:7], v[162:165], v[246:249], v[4:7]
	v_mfma_f32_16x16x32_bf16 v[0:3], v[178:181], v[246:249], v[0:3]
	s_setprio 0
	s_barrier
	s_add_i32 s44, s44, 2
	s_add_u32 s42, s42, 0x100
	s_addc_u32 s43, s43, 0
	s_add_u32 s8, s8, 0x100
	s_addc_u32 s9, s9, 0
	s_cmp_gt_u32 s44, 13
	s_cbranch_scc0 .LBB0_2151

.LBB0_2368:
	s_ashr_i32 s23, s22, 31
	s_lshl_b64 s[24:25], s[22:23], 19
	s_add_u32 s24, s49, s24
	s_addc_u32 s25, s50, s25
	s_and_b64 s[26:27], s[2:3], exec
	s_cselect_b32 s5, s25, s29
	s_cselect_b32 s23, s24, s28
	s_ashr_i32 s15, s14, 31
	s_lshl_b64 s[26:27], s[14:15], 19
	s_add_u32 s26, s51, s26
	s_addc_u32 s27, s52, s27
	s_and_b64 s[30:31], s[2:3], exec
	s_cselect_b32 s15, s27, s7
	s_cselect_b32 s47, s26, s6
	s_add_u32 s54, s6, 0x100
	s_addc_u32 s55, s7, 0
	s_add_u32 s6, s28, 0x40080
	s_addc_u32 s7, s29, 0
	s_mov_b32 s56, -2
	s_waitcnt lgkmcnt(0)
	s_add_u32 s28, s6, 0xfffc0080
	s_addc_u32 s29, s7, -1
	s_add_i32 s57, 0, 0x10000
	s_cmp_eq_u32 s56, 12
	s_cselect_b32 s31, s5, s29
	s_cselect_b32 s30, s23, s28
	v_add_u32_e32 v146, s57, v148
	s_cselect_b32 s29, s15, s55
	s_cselect_b32 s28, s47, s54
	s_add_i32 s60, 0, 0x14000
	ds_read_b128 v[142:145], v146
	ds_read_b128 v[152:155], v146 offset:1024
	ds_read_b128 v[156:159], v146 offset:2048
	ds_read_b128 v[160:163], v146 offset:3072
	v_add_u32_e32 v146, s60, v148
	ds_read_b128 v[164:167], v146
	ds_read_b128 v[168:171], v146 offset:1024
	ds_read_b128 v[172:175], v146 offset:2048
	ds_read_b128 v[176:179], v146 offset:3072
	s_add_i32 m0, s21, 0xc000
	ds_read_b128 v[180:183], v151
	ds_read_b128 v[184:187], v151 offset:1024
	ds_read_b128 v[208:211], v151 offset:2048
	ds_read_b128 v[230:233], v151 offset:3072
	ds_read_b128 v[234:237], v151 offset:4096
	ds_read_b128 v[238:241], v151 offset:5120
	ds_read_b128 v[242:245], v151 offset:6144
	ds_read_b128 v[246:249], v151 offset:7168
	global_load_lds_dwordx4 v140, s[6:7]
	s_add_i32 m0, s21, 0xe000
	s_nop 0
	global_load_lds_dwordx4 v138, s[6:7]
	s_waitcnt vmcnt(8)
	s_waitcnt lgkmcnt(0)
	v_mfma_f32_16x16x32_bf16 v[126:129], v[142:145], v[180:183], 0
	v_mfma_f32_16x16x32_bf16 v[122:125], v[156:159], v[180:183], 0
	v_mfma_f32_16x16x32_bf16 v[108:111], v[142:145], v[208:211], 0
	v_mfma_f32_16x16x32_bf16 v[104:107], v[156:159], v[208:211], 0
	v_mfma_f32_16x16x32_bf16 v[92:95], v[142:145], v[234:237], 0
	v_mfma_f32_16x16x32_bf16 v[88:91], v[156:159], v[234:237], 0
	v_mfma_f32_16x16x32_bf16 v[76:79], v[142:145], v[242:245], 0
	v_mfma_f32_16x16x32_bf16 v[72:75], v[156:159], v[242:245], 0
	s_barrier
	s_setprio 1
	v_mfma_f32_16x16x32_bf16 v[126:129], v[152:155], v[184:187], v[126:129]
	v_mfma_f32_16x16x32_bf16 v[122:125], v[160:163], v[184:187], v[122:125]
	v_mfma_f32_16x16x32_bf16 v[108:111], v[152:155], v[230:233], v[108:111]
	v_mfma_f32_16x16x32_bf16 v[104:107], v[160:163], v[230:233], v[104:107]
	v_mfma_f32_16x16x32_bf16 v[92:95], v[152:155], v[238:241], v[92:95]
	v_mfma_f32_16x16x32_bf16 v[88:91], v[160:163], v[238:241], v[88:91]
	v_mfma_f32_16x16x32_bf16 v[76:79], v[152:155], v[246:249], v[76:79]
	v_mfma_f32_16x16x32_bf16 v[72:75], v[160:163], v[246:249], v[72:75]
	s_setprio 0
	s_setprio 1
	v_mfma_f32_16x16x32_bf16 v[118:121], v[164:167], v[180:183], 0
	v_mfma_f32_16x16x32_bf16 v[114:117], v[172:175], v[180:183], 0
	v_mfma_f32_16x16x32_bf16 v[100:103], v[164:167], v[208:211], 0
	v_mfma_f32_16x16x32_bf16 v[96:99], v[172:175], v[208:211], 0
	v_mfma_f32_16x16x32_bf16 v[84:87], v[164:167], v[234:237], 0
	v_mfma_f32_16x16x32_bf16 v[80:83], v[172:175], v[234:237], 0
	v_mfma_f32_16x16x32_bf16 v[68:71], v[164:167], v[242:245], 0
	v_mfma_f32_16x16x32_bf16 v[64:67], v[172:175], v[242:245], 0
	v_mfma_f32_16x16x32_bf16 v[118:121], v[168:171], v[184:187], v[118:121]
	v_mfma_f32_16x16x32_bf16 v[114:117], v[176:179], v[184:187], v[114:117]
	v_mfma_f32_16x16x32_bf16 v[100:103], v[168:171], v[230:233], v[100:103]
	v_mfma_f32_16x16x32_bf16 v[96:99], v[176:179], v[230:233], v[96:99]
	v_mfma_f32_16x16x32_bf16 v[84:87], v[168:171], v[238:241], v[84:87]
	v_mfma_f32_16x16x32_bf16 v[80:83], v[176:179], v[238:241], v[80:83]
	v_mfma_f32_16x16x32_bf16 v[68:71], v[168:171], v[246:249], v[68:71]
	v_mfma_f32_16x16x32_bf16 v[64:67], v[176:179], v[246:249], v[64:67]
	s_setprio 0
	s_barrier
	s_add_i32 s57, s57, s39
	s_mov_b32 m0, s57
	ds_read_b128 v[180:183], v151 offset:16384
	ds_read_b128 v[184:187], v151 offset:17408
	ds_read_b128 v[208:211], v151 offset:18432
	ds_read_b128 v[230:233], v151 offset:19456
	ds_read_b128 v[234:237], v151 offset:20480
	ds_read_b128 v[238:241], v151 offset:21504
	ds_read_b128 v[242:245], v151 offset:22528
	ds_read_b128 v[246:249], v151 offset:23552
	global_load_lds_dwordx4 v112, s[28:29]
	s_add_i32 m0, s57, 0x2000
	s_add_u32 s58, s28, 0x40000
	v_lshl_add_u64 v[212:213], s[28:29], 0, v[134:135]
	s_addc_u32 s59, s29, 0
	s_add_i32 s57, s60, s39
	global_load_lds_dwordx4 v134, s[28:29]
	s_mov_b32 m0, s57
	v_lshl_add_u64 v[252:253], s[30:31], 0, v[132:133]
	global_load_lds_dwordx4 v112, s[58:59]
	s_add_i32 m0, s57, 0x2000
	s_nop 0
	global_load_lds_dwordx4 v134, s[58:59]
	v_lshl_add_u64 v[250:251], s[30:31], 0, v[130:131]
	s_mov_b32 m0, s21
	s_nop 0
	global_load_lds_dwordx4 v130, s[30:31]
	s_mov_b32 m0, s40
	s_nop 0
	global_load_lds_dwordx4 v132, s[30:31]
	s_waitcnt vmcnt(8)
	s_waitcnt lgkmcnt(0)
	v_mfma_f32_16x16x32_bf16 v[60:63], v[142:145], v[180:183], 0
	v_mfma_f32_16x16x32_bf16 v[56:59], v[156:159], v[180:183], 0
	v_mfma_f32_16x16x32_bf16 v[44:47], v[142:145], v[208:211], 0
	v_mfma_f32_16x16x32_bf16 v[40:43], v[156:159], v[208:211], 0
	v_mfma_f32_16x16x32_bf16 v[28:31], v[142:145], v[234:237], 0
	v_mfma_f32_16x16x32_bf16 v[24:27], v[156:159], v[234:237], 0
	v_mfma_f32_16x16x32_bf16 v[12:15], v[142:145], v[242:245], 0
	v_mfma_f32_16x16x32_bf16 v[8:11], v[156:159], v[242:245], 0
	s_barrier
	s_setprio 1
	v_mfma_f32_16x16x32_bf16 v[60:63], v[152:155], v[184:187], v[60:63]
	v_mfma_f32_16x16x32_bf16 v[56:59], v[160:163], v[184:187], v[56:59]
	v_mfma_f32_16x16x32_bf16 v[44:47], v[152:155], v[230:233], v[44:47]
	v_mfma_f32_16x16x32_bf16 v[40:43], v[160:163], v[230:233], v[40:43]
	v_mfma_f32_16x16x32_bf16 v[28:31], v[152:155], v[238:241], v[28:31]
	v_mfma_f32_16x16x32_bf16 v[24:27], v[160:163], v[238:241], v[24:27]
	v_mfma_f32_16x16x32_bf16 v[12:15], v[152:155], v[246:249], v[12:15]
	v_mfma_f32_16x16x32_bf16 v[8:11], v[160:163], v[246:249], v[8:11]
	s_setprio 0
	s_setprio 1
	v_mfma_f32_16x16x32_bf16 v[52:55], v[164:167], v[180:183], 0
	v_mfma_f32_16x16x32_bf16 v[48:51], v[172:175], v[180:183], 0
	v_mfma_f32_16x16x32_bf16 v[36:39], v[164:167], v[208:211], 0
	v_mfma_f32_16x16x32_bf16 v[32:35], v[172:175], v[208:211], 0
	v_mfma_f32_16x16x32_bf16 v[20:23], v[164:167], v[234:237], 0
	v_mfma_f32_16x16x32_bf16 v[16:19], v[172:175], v[234:237], 0
	v_mfma_f32_16x16x32_bf16 v[4:7], v[164:167], v[242:245], 0
	v_mfma_f32_16x16x32_bf16 v[0:3], v[172:175], v[242:245], 0
	v_mfma_f32_16x16x32_bf16 v[52:55], v[168:171], v[184:187], v[52:55]
	v_mfma_f32_16x16x32_bf16 v[48:51], v[176:179], v[184:187], v[48:51]
	v_mfma_f32_16x16x32_bf16 v[36:39], v[168:171], v[230:233], v[36:39]
	v_mfma_f32_16x16x32_bf16 v[32:35], v[176:179], v[230:233], v[32:35]
	v_mfma_f32_16x16x32_bf16 v[20:23], v[168:171], v[238:241], v[20:23]
	v_mfma_f32_16x16x32_bf16 v[16:19], v[176:179], v[238:241], v[16:19]
	v_mfma_f32_16x16x32_bf16 v[4:7], v[168:171], v[246:249], v[4:7]
	v_mfma_f32_16x16x32_bf16 v[0:3], v[176:179], v[246:249], v[0:3]
	s_setprio 0
	s_barrier
	s_add_i32 s57, 0, 0x18000
	v_add_u32_e32 v146, s57, v148
	s_add_i32 s58, 0, 0x1c000
	ds_read_b128 v[142:145], v146
	ds_read_b128 v[152:155], v146 offset:1024
	ds_read_b128 v[156:159], v146 offset:2048
	ds_read_b128 v[160:163], v146 offset:3072
	v_add_u32_e32 v146, s58, v148
	ds_read_b128 v[164:167], v146
	ds_read_b128 v[168:171], v146 offset:1024
	ds_read_b128 v[172:175], v146 offset:2048
	ds_read_b128 v[176:179], v146 offset:3072
	s_add_u32 s30, s30, 0x40000
	s_addc_u32 s31, s31, 0
	s_mov_b32 m0, s41
	ds_read_b128 v[180:183], v151 offset:32768
	ds_read_b128 v[184:187], v151 offset:33792
	ds_read_b128 v[208:211], v151 offset:34816
	ds_read_b128 v[230:233], v151 offset:35840
	ds_read_b128 v[234:237], v151 offset:36864
	ds_read_b128 v[238:241], v151 offset:37888
	ds_read_b128 v[242:245], v151 offset:38912
	ds_read_b128 v[246:249], v151 offset:39936
	global_load_lds_dwordx4 v130, s[30:31]
	s_mov_b32 m0, s42
	s_nop 0
	global_load_lds_dwordx4 v132, s[30:31]
	s_waitcnt vmcnt(8)
	s_waitcnt lgkmcnt(0)
	v_mfma_f32_16x16x32_bf16 v[126:129], v[142:145], v[180:183], v[126:129]
	v_mfma_f32_16x16x32_bf16 v[122:125], v[156:159], v[180:183], v[122:125]
	v_mfma_f32_16x16x32_bf16 v[108:111], v[142:145], v[208:211], v[108:111]
	v_mfma_f32_16x16x32_bf16 v[104:107], v[156:159], v[208:211], v[104:107]
	v_mfma_f32_16x16x32_bf16 v[92:95], v[142:145], v[234:237], v[92:95]
	v_mfma_f32_16x16x32_bf16 v[88:91], v[156:159], v[234:237], v[88:91]
	v_mfma_f32_16x16x32_bf16 v[76:79], v[142:145], v[242:245], v[76:79]
	v_mfma_f32_16x16x32_bf16 v[72:75], v[156:159], v[242:245], v[72:75]
	s_barrier
	s_setprio 1
	v_mfma_f32_16x16x32_bf16 v[126:129], v[152:155], v[184:187], v[126:129]
	v_mfma_f32_16x16x32_bf16 v[122:125], v[160:163], v[184:187], v[122:125]
	v_mfma_f32_16x16x32_bf16 v[108:111], v[152:155], v[230:233], v[108:111]
	v_mfma_f32_16x16x32_bf16 v[104:107], v[160:163], v[230:233], v[104:107]
	v_mfma_f32_16x16x32_bf16 v[92:95], v[152:155], v[238:241], v[92:95]
	v_mfma_f32_16x16x32_bf16 v[88:91], v[160:163], v[238:241], v[88:91]
	v_mfma_f32_16x16x32_bf16 v[76:79], v[152:155], v[246:249], v[76:79]
	v_mfma_f32_16x16x32_bf16 v[72:75], v[160:163], v[246:249], v[72:75]
	s_setprio 0
	s_setprio 1
	v_mfma_f32_16x16x32_bf16 v[118:121], v[164:167], v[180:183], v[118:121]
	v_mfma_f32_16x16x32_bf16 v[114:117], v[172:175], v[180:183], v[114:117]
	v_mfma_f32_16x16x32_bf16 v[100:103], v[164:167], v[208:211], v[100:103]
	v_mfma_f32_16x16x32_bf16 v[96:99], v[172:175], v[208:211], v[96:99]
	v_mfma_f32_16x16x32_bf16 v[84:87], v[164:167], v[234:237], v[84:87]
	v_mfma_f32_16x16x32_bf16 v[80:83], v[172:175], v[234:237], v[80:83]
	v_mfma_f32_16x16x32_bf16 v[68:71], v[164:167], v[242:245], v[68:71]
	v_mfma_f32_16x16x32_bf16 v[64:67], v[172:175], v[242:245], v[64:67]
	v_mfma_f32_16x16x32_bf16 v[118:121], v[168:171], v[184:187], v[118:121]
	v_mfma_f32_16x16x32_bf16 v[114:117], v[176:179], v[184:187], v[114:117]
	v_mfma_f32_16x16x32_bf16 v[100:103], v[168:171], v[230:233], v[100:103]
	v_mfma_f32_16x16x32_bf16 v[96:99], v[176:179], v[230:233], v[96:99]
	v_mfma_f32_16x16x32_bf16 v[84:87], v[168:171], v[238:241], v[84:87]
	v_mfma_f32_16x16x32_bf16 v[80:83], v[176:179], v[238:241], v[80:83]
	v_mfma_f32_16x16x32_bf16 v[68:71], v[168:171], v[246:249], v[68:71]
	v_mfma_f32_16x16x32_bf16 v[64:67], v[176:179], v[246:249], v[64:67]
	s_setprio 0
	s_barrier
	s_add_i32 s30, s57, s39
	s_mov_b32 m0, s30
	ds_read_b128 v[180:183], v151 offset:49152
	ds_read_b128 v[184:187], v151 offset:50176
	ds_read_b128 v[208:211], v151 offset:51200
	ds_read_b128 v[230:233], v151 offset:52224
	ds_read_b128 v[234:237], v151 offset:53248
	ds_read_b128 v[238:241], v151 offset:54272
	ds_read_b128 v[242:245], v151 offset:55296
	ds_read_b128 v[246:249], v151 offset:56320
	s_add_u32 s98, s28, 0x80
	s_addc_u32 s99, s29, 0
	global_load_lds_dwordx4 v112, s[98:99]
	s_add_i32 m0, s30, 0x2000
	s_add_u32 s28, s28, 0x40080
	v_lshl_add_u64 v[188:189], v[212:213], 0, s[96:97]
	s_addc_u32 s29, s29, 0
	s_add_i32 s30, s58, s39
	global_load_lds_dwordx4 v[188:189], off
	s_mov_b32 m0, s30
	s_nop 0
	global_load_lds_dwordx4 v112, s[28:29]
	s_add_i32 m0, s30, 0x2000
	s_nop 0
	global_load_lds_dwordx4 v134, s[28:29]
	v_lshl_add_u64 v[188:189], v[250:251], 0, s[96:97]
	s_mov_b32 m0, s43
	s_nop 0
	global_load_lds_dwordx4 v[188:189], off
	v_lshl_add_u64 v[188:189], v[252:253], 0, s[96:97]
	s_mov_b32 m0, s44
	s_nop 0
	global_load_lds_dwordx4 v[188:189], off
	s_waitcnt vmcnt(8)
	s_waitcnt lgkmcnt(0)
	v_mfma_f32_16x16x32_bf16 v[60:63], v[142:145], v[180:183], v[60:63]
	v_mfma_f32_16x16x32_bf16 v[56:59], v[156:159], v[180:183], v[56:59]
	v_mfma_f32_16x16x32_bf16 v[44:47], v[142:145], v[208:211], v[44:47]
	v_mfma_f32_16x16x32_bf16 v[40:43], v[156:159], v[208:211], v[40:43]
	v_mfma_f32_16x16x32_bf16 v[28:31], v[142:145], v[234:237], v[28:31]
	v_mfma_f32_16x16x32_bf16 v[24:27], v[156:159], v[234:237], v[24:27]
	v_mfma_f32_16x16x32_bf16 v[12:15], v[142:145], v[242:245], v[12:15]
	v_mfma_f32_16x16x32_bf16 v[8:11], v[156:159], v[242:245], v[8:11]
	s_barrier
	s_setprio 1
	v_mfma_f32_16x16x32_bf16 v[60:63], v[152:155], v[184:187], v[60:63]
	v_mfma_f32_16x16x32_bf16 v[56:59], v[160:163], v[184:187], v[56:59]
	v_mfma_f32_16x16x32_bf16 v[44:47], v[152:155], v[230:233], v[44:47]
	v_mfma_f32_16x16x32_bf16 v[40:43], v[160:163], v[230:233], v[40:43]
	v_mfma_f32_16x16x32_bf16 v[28:31], v[152:155], v[238:241], v[28:31]
	v_mfma_f32_16x16x32_bf16 v[24:27], v[160:163], v[238:241], v[24:27]
	v_mfma_f32_16x16x32_bf16 v[12:15], v[152:155], v[246:249], v[12:15]
	v_mfma_f32_16x16x32_bf16 v[8:11], v[160:163], v[246:249], v[8:11]
	s_setprio 0
	s_setprio 1
	v_mfma_f32_16x16x32_bf16 v[52:55], v[164:167], v[180:183], v[52:55]
	v_mfma_f32_16x16x32_bf16 v[48:51], v[172:175], v[180:183], v[48:51]
	v_mfma_f32_16x16x32_bf16 v[36:39], v[164:167], v[208:211], v[36:39]
	v_mfma_f32_16x16x32_bf16 v[32:35], v[172:175], v[208:211], v[32:35]
	v_mfma_f32_16x16x32_bf16 v[20:23], v[164:167], v[234:237], v[20:23]
	v_mfma_f32_16x16x32_bf16 v[16:19], v[172:175], v[234:237], v[16:19]
	v_mfma_f32_16x16x32_bf16 v[4:7], v[164:167], v[242:245], v[4:7]
	v_mfma_f32_16x16x32_bf16 v[0:3], v[172:175], v[242:245], v[0:3]
	v_mfma_f32_16x16x32_bf16 v[52:55], v[168:171], v[184:187], v[52:55]
	v_mfma_f32_16x16x32_bf16 v[48:51], v[176:179], v[184:187], v[48:51]
	v_mfma_f32_16x16x32_bf16 v[36:39], v[168:171], v[230:233], v[36:39]
	v_mfma_f32_16x16x32_bf16 v[32:35], v[176:179], v[230:233], v[32:35]
	v_mfma_f32_16x16x32_bf16 v[20:23], v[168:171], v[238:241], v[20:23]
	v_mfma_f32_16x16x32_bf16 v[16:19], v[176:179], v[238:241], v[16:19]
	v_mfma_f32_16x16x32_bf16 v[4:7], v[168:171], v[246:249], v[4:7]
	v_mfma_f32_16x16x32_bf16 v[0:3], v[176:179], v[246:249], v[0:3]
	s_setprio 0
	s_barrier
	s_add_i32 s56, s56, 2
	s_add_u32 s54, s54, 0x100
	s_addc_u32 s55, s55, 0
	s_add_u32 s6, s6, 0x100
	s_addc_u32 s7, s7, 0
	s_cmp_gt_u32 s56, 13
	s_cbranch_scc0 .LBB0_2369
	s_branch .Lpeel_exit_2369
.LBB0_2369:
	s_add_u32 s28, s6, 0xfffc0080
	s_addc_u32 s29, s7, -1
	s_add_i32 s57, 0, 0x10000
	s_cmp_eq_u32 s56, 12
	s_cselect_b32 s31, s5, s29
	s_cselect_b32 s30, s23, s28
	v_add_u32_e32 v146, s57, v148
	s_cselect_b32 s29, s15, s55
	s_cselect_b32 s28, s47, s54
	s_add_i32 s60, 0, 0x14000
	ds_read_b128 v[142:145], v146
	ds_read_b128 v[152:155], v146 offset:1024
	ds_read_b128 v[156:159], v146 offset:2048
	ds_read_b128 v[160:163], v146 offset:3072
	v_add_u32_e32 v146, s60, v148
	ds_read_b128 v[164:167], v146
	ds_read_b128 v[168:171], v146 offset:1024
	ds_read_b128 v[172:175], v146 offset:2048
	ds_read_b128 v[176:179], v146 offset:3072
	s_add_i32 m0, s21, 0xc000
	ds_read_b128 v[180:183], v151
	ds_read_b128 v[184:187], v151 offset:1024
	ds_read_b128 v[208:211], v151 offset:2048
	ds_read_b128 v[230:233], v151 offset:3072
	ds_read_b128 v[234:237], v151 offset:4096
	ds_read_b128 v[238:241], v151 offset:5120
	ds_read_b128 v[242:245], v151 offset:6144
	ds_read_b128 v[246:249], v151 offset:7168
	global_load_lds_dwordx4 v140, s[6:7]
	s_add_i32 m0, s21, 0xe000
	s_nop 0
	global_load_lds_dwordx4 v138, s[6:7]
	s_waitcnt vmcnt(8)
	s_waitcnt lgkmcnt(0)
	v_mfma_f32_16x16x32_bf16 v[126:129], v[142:145], v[180:183], v[126:129]
	v_mfma_f32_16x16x32_bf16 v[122:125], v[156:159], v[180:183], v[122:125]
	v_mfma_f32_16x16x32_bf16 v[108:111], v[142:145], v[208:211], v[108:111]
	v_mfma_f32_16x16x32_bf16 v[104:107], v[156:159], v[208:211], v[104:107]
	v_mfma_f32_16x16x32_bf16 v[92:95], v[142:145], v[234:237], v[92:95]
	v_mfma_f32_16x16x32_bf16 v[88:91], v[156:159], v[234:237], v[88:91]
	v_mfma_f32_16x16x32_bf16 v[76:79], v[142:145], v[242:245], v[76:79]
	v_mfma_f32_16x16x32_bf16 v[72:75], v[156:159], v[242:245], v[72:75]
	s_barrier
	s_setprio 1
	v_mfma_f32_16x16x32_bf16 v[126:129], v[152:155], v[184:187], v[126:129]
	v_mfma_f32_16x16x32_bf16 v[122:125], v[160:163], v[184:187], v[122:125]
	v_mfma_f32_16x16x32_bf16 v[108:111], v[152:155], v[230:233], v[108:111]
	v_mfma_f32_16x16x32_bf16 v[104:107], v[160:163], v[230:233], v[104:107]
	v_mfma_f32_16x16x32_bf16 v[92:95], v[152:155], v[238:241], v[92:95]
	v_mfma_f32_16x16x32_bf16 v[88:91], v[160:163], v[238:241], v[88:91]
	v_mfma_f32_16x16x32_bf16 v[76:79], v[152:155], v[246:249], v[76:79]
	v_mfma_f32_16x16x32_bf16 v[72:75], v[160:163], v[246:249], v[72:75]
	s_setprio 0
	s_setprio 1
	v_mfma_f32_16x16x32_bf16 v[118:121], v[164:167], v[180:183], v[118:121]
	v_mfma_f32_16x16x32_bf16 v[114:117], v[172:175], v[180:183], v[114:117]
	v_mfma_f32_16x16x32_bf16 v[100:103], v[164:167], v[208:211], v[100:103]
	v_mfma_f32_16x16x32_bf16 v[96:99], v[172:175], v[208:211], v[96:99]
	v_mfma_f32_16x16x32_bf16 v[84:87], v[164:167], v[234:237], v[84:87]
	v_mfma_f32_16x16x32_bf16 v[80:83], v[172:175], v[234:237], v[80:83]
	v_mfma_f32_16x16x32_bf16 v[68:71], v[164:167], v[242:245], v[68:71]
	v_mfma_f32_16x16x32_bf16 v[64:67], v[172:175], v[242:245], v[64:67]
	v_mfma_f32_16x16x32_bf16 v[118:121], v[168:171], v[184:187], v[118:121]
	v_mfma_f32_16x16x32_bf16 v[114:117], v[176:179], v[184:187], v[114:117]
	v_mfma_f32_16x16x32_bf16 v[100:103], v[168:171], v[230:233], v[100:103]
	v_mfma_f32_16x16x32_bf16 v[96:99], v[176:179], v[230:233], v[96:99]
	v_mfma_f32_16x16x32_bf16 v[84:87], v[168:171], v[238:241], v[84:87]
	v_mfma_f32_16x16x32_bf16 v[80:83], v[176:179], v[238:241], v[80:83]
	v_mfma_f32_16x16x32_bf16 v[68:71], v[168:171], v[246:249], v[68:71]
	v_mfma_f32_16x16x32_bf16 v[64:67], v[176:179], v[246:249], v[64:67]
	s_setprio 0
	s_barrier
	s_add_i32 s57, s57, s39
	s_mov_b32 m0, s57
	ds_read_b128 v[180:183], v151 offset:16384
	ds_read_b128 v[184:187], v151 offset:17408
	ds_read_b128 v[208:211], v151 offset:18432
	ds_read_b128 v[230:233], v151 offset:19456
	ds_read_b128 v[234:237], v151 offset:20480
	ds_read_b128 v[238:241], v151 offset:21504
	ds_read_b128 v[242:245], v151 offset:22528
	ds_read_b128 v[246:249], v151 offset:23552
	global_load_lds_dwordx4 v112, s[28:29]
	s_add_i32 m0, s57, 0x2000
	s_add_u32 s58, s28, 0x40000
	v_lshl_add_u64 v[212:213], s[28:29], 0, v[134:135]
	s_addc_u32 s59, s29, 0
	s_add_i32 s57, s60, s39
	global_load_lds_dwordx4 v134, s[28:29]
	s_mov_b32 m0, s57
	v_lshl_add_u64 v[252:253], s[30:31], 0, v[132:133]
	global_load_lds_dwordx4 v112, s[58:59]
	s_add_i32 m0, s57, 0x2000
	s_nop 0
	global_load_lds_dwordx4 v134, s[58:59]
	v_lshl_add_u64 v[250:251], s[30:31], 0, v[130:131]
	s_mov_b32 m0, s21
	s_nop 0
	global_load_lds_dwordx4 v130, s[30:31]
	s_mov_b32 m0, s40
	s_nop 0
	global_load_lds_dwordx4 v132, s[30:31]
	s_waitcnt vmcnt(8)
	s_waitcnt lgkmcnt(0)
	v_mfma_f32_16x16x32_bf16 v[60:63], v[142:145], v[180:183], v[60:63]
	v_mfma_f32_16x16x32_bf16 v[56:59], v[156:159], v[180:183], v[56:59]
	v_mfma_f32_16x16x32_bf16 v[44:47], v[142:145], v[208:211], v[44:47]
	v_mfma_f32_16x16x32_bf16 v[40:43], v[156:159], v[208:211], v[40:43]
	v_mfma_f32_16x16x32_bf16 v[28:31], v[142:145], v[234:237], v[28:31]
	v_mfma_f32_16x16x32_bf16 v[24:27], v[156:159], v[234:237], v[24:27]
	v_mfma_f32_16x16x32_bf16 v[12:15], v[142:145], v[242:245], v[12:15]
	v_mfma_f32_16x16x32_bf16 v[8:11], v[156:159], v[242:245], v[8:11]
	s_barrier
	s_setprio 1
	v_mfma_f32_16x16x32_bf16 v[60:63], v[152:155], v[184:187], v[60:63]
	v_mfma_f32_16x16x32_bf16 v[56:59], v[160:163], v[184:187], v[56:59]
	v_mfma_f32_16x16x32_bf16 v[44:47], v[152:155], v[230:233], v[44:47]
	v_mfma_f32_16x16x32_bf16 v[40:43], v[160:163], v[230:233], v[40:43]
	v_mfma_f32_16x16x32_bf16 v[28:31], v[152:155], v[238:241], v[28:31]
	v_mfma_f32_16x16x32_bf16 v[24:27], v[160:163], v[238:241], v[24:27]
	v_mfma_f32_16x16x32_bf16 v[12:15], v[152:155], v[246:249], v[12:15]
	v_mfma_f32_16x16x32_bf16 v[8:11], v[160:163], v[246:249], v[8:11]
	s_setprio 0
	s_setprio 1
	v_mfma_f32_16x16x32_bf16 v[52:55], v[164:167], v[180:183], v[52:55]
	v_mfma_f32_16x16x32_bf16 v[48:51], v[172:175], v[180:183], v[48:51]
	v_mfma_f32_16x16x32_bf16 v[36:39], v[164:167], v[208:211], v[36:39]
	v_mfma_f32_16x16x32_bf16 v[32:35], v[172:175], v[208:211], v[32:35]
	v_mfma_f32_16x16x32_bf16 v[20:23], v[164:167], v[234:237], v[20:23]
	v_mfma_f32_16x16x32_bf16 v[16:19], v[172:175], v[234:237], v[16:19]
	v_mfma_f32_16x16x32_bf16 v[4:7], v[164:167], v[242:245], v[4:7]
	v_mfma_f32_16x16x32_bf16 v[0:3], v[172:175], v[242:245], v[0:3]
	v_mfma_f32_16x16x32_bf16 v[52:55], v[168:171], v[184:187], v[52:55]
	v_mfma_f32_16x16x32_bf16 v[48:51], v[176:179], v[184:187], v[48:51]
	v_mfma_f32_16x16x32_bf16 v[36:39], v[168:171], v[230:233], v[36:39]
	v_mfma_f32_16x16x32_bf16 v[32:35], v[176:179], v[230:233], v[32:35]
	v_mfma_f32_16x16x32_bf16 v[20:23], v[168:171], v[238:241], v[20:23]
	v_mfma_f32_16x16x32_bf16 v[16:19], v[176:179], v[238:241], v[16:19]
	v_mfma_f32_16x16x32_bf16 v[4:7], v[168:171], v[246:249], v[4:7]
	v_mfma_f32_16x16x32_bf16 v[0:3], v[176:179], v[246:249], v[0:3]
	s_setprio 0
	s_barrier
	s_add_i32 s57, 0, 0x18000
	v_add_u32_e32 v146, s57, v148
	s_add_i32 s58, 0, 0x1c000
	ds_read_b128 v[142:145], v146
	ds_read_b128 v[152:155], v146 offset:1024
	ds_read_b128 v[156:159], v146 offset:2048
	ds_read_b128 v[160:163], v146 offset:3072
	v_add_u32_e32 v146, s58, v148
	ds_read_b128 v[164:167], v146
	ds_read_b128 v[168:171], v146 offset:1024
	ds_read_b128 v[172:175], v146 offset:2048
	ds_read_b128 v[176:179], v146 offset:3072
	s_add_u32 s30, s30, 0x40000
	s_addc_u32 s31, s31, 0
	s_mov_b32 m0, s41
	ds_read_b128 v[180:183], v151 offset:32768
	ds_read_b128 v[184:187], v151 offset:33792
	ds_read_b128 v[208:211], v151 offset:34816
	ds_read_b128 v[230:233], v151 offset:35840
	ds_read_b128 v[234:237], v151 offset:36864
	ds_read_b128 v[238:241], v151 offset:37888
	ds_read_b128 v[242:245], v151 offset:38912
	ds_read_b128 v[246:249], v151 offset:39936
	global_load_lds_dwordx4 v130, s[30:31]
	s_mov_b32 m0, s42
	s_nop 0
	global_load_lds_dwordx4 v132, s[30:31]
	s_waitcnt vmcnt(8)
	s_waitcnt lgkmcnt(0)
	v_mfma_f32_16x16x32_bf16 v[126:129], v[142:145], v[180:183], v[126:129]
	v_mfma_f32_16x16x32_bf16 v[122:125], v[156:159], v[180:183], v[122:125]
	v_mfma_f32_16x16x32_bf16 v[108:111], v[142:145], v[208:211], v[108:111]
	v_mfma_f32_16x16x32_bf16 v[104:107], v[156:159], v[208:211], v[104:107]
	v_mfma_f32_16x16x32_bf16 v[92:95], v[142:145], v[234:237], v[92:95]
	v_mfma_f32_16x16x32_bf16 v[88:91], v[156:159], v[234:237], v[88:91]
	v_mfma_f32_16x16x32_bf16 v[76:79], v[142:145], v[242:245], v[76:79]
	v_mfma_f32_16x16x32_bf16 v[72:75], v[156:159], v[242:245], v[72:75]
	s_barrier
	s_setprio 1
	v_mfma_f32_16x16x32_bf16 v[126:129], v[152:155], v[184:187], v[126:129]
	v_mfma_f32_16x16x32_bf16 v[122:125], v[160:163], v[184:187], v[122:125]
	v_mfma_f32_16x16x32_bf16 v[108:111], v[152:155], v[230:233], v[108:111]
	v_mfma_f32_16x16x32_bf16 v[104:107], v[160:163], v[230:233], v[104:107]
	v_mfma_f32_16x16x32_bf16 v[92:95], v[152:155], v[238:241], v[92:95]
	v_mfma_f32_16x16x32_bf16 v[88:91], v[160:163], v[238:241], v[88:91]
	v_mfma_f32_16x16x32_bf16 v[76:79], v[152:155], v[246:249], v[76:79]
	v_mfma_f32_16x16x32_bf16 v[72:75], v[160:163], v[246:249], v[72:75]
	s_setprio 0
	s_setprio 1
	v_mfma_f32_16x16x32_bf16 v[118:121], v[164:167], v[180:183], v[118:121]
	v_mfma_f32_16x16x32_bf16 v[114:117], v[172:175], v[180:183], v[114:117]
	v_mfma_f32_16x16x32_bf16 v[100:103], v[164:167], v[208:211], v[100:103]
	v_mfma_f32_16x16x32_bf16 v[96:99], v[172:175], v[208:211], v[96:99]
	v_mfma_f32_16x16x32_bf16 v[84:87], v[164:167], v[234:237], v[84:87]
	v_mfma_f32_16x16x32_bf16 v[80:83], v[172:175], v[234:237], v[80:83]
	v_mfma_f32_16x16x32_bf16 v[68:71], v[164:167], v[242:245], v[68:71]
	v_mfma_f32_16x16x32_bf16 v[64:67], v[172:175], v[242:245], v[64:67]
	v_mfma_f32_16x16x32_bf16 v[118:121], v[168:171], v[184:187], v[118:121]
	v_mfma_f32_16x16x32_bf16 v[114:117], v[176:179], v[184:187], v[114:117]
	v_mfma_f32_16x16x32_bf16 v[100:103], v[168:171], v[230:233], v[100:103]
	v_mfma_f32_16x16x32_bf16 v[96:99], v[176:179], v[230:233], v[96:99]
	v_mfma_f32_16x16x32_bf16 v[84:87], v[168:171], v[238:241], v[84:87]
	v_mfma_f32_16x16x32_bf16 v[80:83], v[176:179], v[238:241], v[80:83]
	v_mfma_f32_16x16x32_bf16 v[68:71], v[168:171], v[246:249], v[68:71]
	v_mfma_f32_16x16x32_bf16 v[64:67], v[176:179], v[246:249], v[64:67]
	s_setprio 0
	s_barrier
	s_add_i32 s30, s57, s39
	s_mov_b32 m0, s30
	ds_read_b128 v[180:183], v151 offset:49152
	ds_read_b128 v[184:187], v151 offset:50176
	ds_read_b128 v[208:211], v151 offset:51200
	ds_read_b128 v[230:233], v151 offset:52224
	ds_read_b128 v[234:237], v151 offset:53248
	ds_read_b128 v[238:241], v151 offset:54272
	ds_read_b128 v[242:245], v151 offset:55296
	ds_read_b128 v[246:249], v151 offset:56320
	s_add_u32 s98, s28, 0x80
	s_addc_u32 s99, s29, 0
	global_load_lds_dwordx4 v112, s[98:99]
	s_add_i32 m0, s30, 0x2000
	s_add_u32 s28, s28, 0x40080
	v_lshl_add_u64 v[188:189], v[212:213], 0, s[96:97]
	s_addc_u32 s29, s29, 0
	s_add_i32 s30, s58, s39
	global_load_lds_dwordx4 v[188:189], off
	s_mov_b32 m0, s30
	s_nop 0
	global_load_lds_dwordx4 v112, s[28:29]
	s_add_i32 m0, s30, 0x2000
	s_nop 0
	global_load_lds_dwordx4 v134, s[28:29]
	v_lshl_add_u64 v[188:189], v[250:251], 0, s[96:97]
	s_mov_b32 m0, s43
	s_nop 0
	global_load_lds_dwordx4 v[188:189], off
	v_lshl_add_u64 v[188:189], v[252:253], 0, s[96:97]
	s_mov_b32 m0, s44
	s_nop 0
	global_load_lds_dwordx4 v[188:189], off
	s_waitcnt vmcnt(8)
	s_waitcnt lgkmcnt(0)
	v_mfma_f32_16x16x32_bf16 v[60:63], v[142:145], v[180:183], v[60:63]
	v_mfma_f32_16x16x32_bf16 v[56:59], v[156:159], v[180:183], v[56:59]
	v_mfma_f32_16x16x32_bf16 v[44:47], v[142:145], v[208:211], v[44:47]
	v_mfma_f32_16x16x32_bf16 v[40:43], v[156:159], v[208:211], v[40:43]
	v_mfma_f32_16x16x32_bf16 v[28:31], v[142:145], v[234:237], v[28:31]
	v_mfma_f32_16x16x32_bf16 v[24:27], v[156:159], v[234:237], v[24:27]
	v_mfma_f32_16x16x32_bf16 v[12:15], v[142:145], v[242:245], v[12:15]
	v_mfma_f32_16x16x32_bf16 v[8:11], v[156:159], v[242:245], v[8:11]
	s_barrier
	s_setprio 1
	v_mfma_f32_16x16x32_bf16 v[60:63], v[152:155], v[184:187], v[60:63]
	v_mfma_f32_16x16x32_bf16 v[56:59], v[160:163], v[184:187], v[56:59]
	v_mfma_f32_16x16x32_bf16 v[44:47], v[152:155], v[230:233], v[44:47]
	v_mfma_f32_16x16x32_bf16 v[40:43], v[160:163], v[230:233], v[40:43]
	v_mfma_f32_16x16x32_bf16 v[28:31], v[152:155], v[238:241], v[28:31]
	v_mfma_f32_16x16x32_bf16 v[24:27], v[160:163], v[238:241], v[24:27]
	v_mfma_f32_16x16x32_bf16 v[12:15], v[152:155], v[246:249], v[12:15]
	v_mfma_f32_16x16x32_bf16 v[8:11], v[160:163], v[246:249], v[8:11]
	s_setprio 0
	s_setprio 1
	v_mfma_f32_16x16x32_bf16 v[52:55], v[164:167], v[180:183], v[52:55]
	v_mfma_f32_16x16x32_bf16 v[48:51], v[172:175], v[180:183], v[48:51]
	v_mfma_f32_16x16x32_bf16 v[36:39], v[164:167], v[208:211], v[36:39]
	v_mfma_f32_16x16x32_bf16 v[32:35], v[172:175], v[208:211], v[32:35]
	v_mfma_f32_16x16x32_bf16 v[20:23], v[164:167], v[234:237], v[20:23]
	v_mfma_f32_16x16x32_bf16 v[16:19], v[172:175], v[234:237], v[16:19]
	v_mfma_f32_16x16x32_bf16 v[4:7], v[164:167], v[242:245], v[4:7]
	v_mfma_f32_16x16x32_bf16 v[0:3], v[172:175], v[242:245], v[0:3]
	v_mfma_f32_16x16x32_bf16 v[52:55], v[168:171], v[184:187], v[52:55]
	v_mfma_f32_16x16x32_bf16 v[48:51], v[176:179], v[184:187], v[48:51]
	v_mfma_f32_16x16x32_bf16 v[36:39], v[168:171], v[230:233], v[36:39]
	v_mfma_f32_16x16x32_bf16 v[32:35], v[176:179], v[230:233], v[32:35]
	v_mfma_f32_16x16x32_bf16 v[20:23], v[168:171], v[238:241], v[20:23]
	v_mfma_f32_16x16x32_bf16 v[16:19], v[176:179], v[238:241], v[16:19]
	v_mfma_f32_16x16x32_bf16 v[4:7], v[168:171], v[246:249], v[4:7]
	v_mfma_f32_16x16x32_bf16 v[0:3], v[176:179], v[246:249], v[0:3]
	s_setprio 0
	s_barrier
	s_add_i32 s56, s56, 2
	s_add_u32 s54, s54, 0x100
	s_addc_u32 s55, s55, 0
	s_add_u32 s6, s6, 0x100
	s_addc_u32 s7, s7, 0
	s_cmp_gt_u32 s56, 13
	s_cbranch_scc0 .LBB0_2369
